# v11 plus GEMM K-loop barrier handoff: s_setprio 1 hoisted above pre-MMA barrier, redundant post-barrier lgkmcnt(0) dropped, s_setprio 0 sunk below post-MMA barrier
# baseline (speedup 1.0000x reference)
; #define PG8_STAGE(bufoff, gbase, voff) do { _Pragma("unroll") for (int _i = 0; _i < 2; ++_i) \
;         __builtin_amdgcn_global_load_lds((const unsigned*)((const char*)(gbase) + (voff)[_i]), (PG8_LAS unsigned*)(lds + (bufoff) + ldsw + _i * 8192), 16, 0, 0); } while (0)
; #define PG8_LDA(dst, b, h) do { _Pragma("unroll") for (int m = 0; m < 4; ++m) _Pragma("unroll") for (int k = 0; k < 2; ++k) dst[m][k] = *(const PG8_LAS bf16x8*)(lds + PG8_SA(b, h) + aoff + m * 2048 + k * 1024); } while (0)
; #define PG8_LDB(dst, b, h) do { _Pragma("unroll") for (int n = 0; n < 2; ++n) _Pragma("unroll") for (int k = 0; k < 2; ++k) dst[n][k] = *(const PG8_LAS bf16x8*)(lds + PG8_SB(b, h) + boff + n * 2048 + k * 1024); } while (0)
; #define PG8_MMA(ai, bj, At, Bt) do { __builtin_amdgcn_s_setprio(1); _Pragma("unroll") for (int m = 0; m < 4; ++m) _Pragma("unroll") for (int n = 0; n < 2; ++n) _Pragma("unroll") for (int k = 0; k < 2; ++k) \
;         acc[ai][bj][m][n] = __builtin_amdgcn_mfma_f32_16x16x32_bf16(Bt[n][k], At[m][k], acc[ai][bj][m][n], 0, 0, 0); __builtin_amdgcn_s_setprio(0); } while (0)
; #define PG8_WAIT_V(n) asm volatile("s_waitcnt vmcnt(" #n ")" ::: "memory")
; #define PG8_WAIT_L(n) asm volatile("s_waitcnt lgkmcnt(" #n ")" ::: "memory")
; #define PG8_BAR __builtin_amdgcn_s_barrier()
; #define PG8_SCHED __builtin_amdgcn_sched_barrier(0)
; template <class Epi, class Sched, bool ALIGN_EPI = false, bool SP2 = false>
; __device__ __forceinline__ void gemm_phase(PG8_LAS unsigned char* lds, const Gemm g, const Sched& S, const Epi& E) {
;     ...
;             PG8_LDB(B0, 0, 0); PG8_LDB(B1, 0, 1); PG8_SCHED; PG8_LDA(At, 0, 0); PG8_STAGE(PG8_SA(1, 1), a1 + hstep, voffA);
;             PG8_WAIT_V(8); PG8_WAIT_L(0); PG8_BAR; PG8_MMA(0, 0, At, B0); PG8_MMA(0, 1, At, B1); PG8_BAR; PG8_SCHED;
;             PG8_LDA(At, 0, 1); PG8_STAGE(PG8_SB(0, 0), b2, voffB); PG8_STAGE(PG8_SB(0, 1), b2 + hstep, voffB); PG8_STAGE(PG8_SA(0, 0), a2, voffA);
;             PG8_WAIT_V(8); PG8_WAIT_L(0); PG8_BAR; PG8_MMA(1, 0, At, B0); PG8_MMA(1, 1, At, B1); PG8_BAR; PG8_SCHED;
.LBB0_139:
	ds_read_b128 v[2:5], v187
	ds_read_b128 v[6:9], v187 offset:1024
	ds_read_b128 v[138:141], v187 offset:2048
	ds_read_b128 v[142:145], v187 offset:3072
	ds_read_b128 v[146:149], v197
	ds_read_b128 v[150:153], v197 offset:1024
	ds_read_b128 v[154:157], v197 offset:2048
	ds_read_b128 v[158:161], v197 offset:3072
	s_add_u32 s14, s12, 0xfff00080
	s_addc_u32 s15, s13, -1
	s_cmp_eq_u32 s33, 60
	s_cselect_b32 s17, s2, s15
	s_cselect_b32 s16, s11, s14
	s_cselect_b32 s15, s26, s30
	s_cselect_b32 s14, s28, s29
	v_lshl_add_u64 v[162:163], s[12:13], 0, v[188:189]
	s_add_i32 m0, s27, 0xc000
	ds_read_b128 v[202:205], v199
	ds_read_b128 v[206:209], v199 offset:1024
	ds_read_b128 v[214:217], v199 offset:2048
	ds_read_b128 v[218:221], v199 offset:3072
	ds_read_b128 v[222:225], v199 offset:4096
	ds_read_b128 v[226:229], v199 offset:5120
	ds_read_b128 v[230:233], v199 offset:6144
	ds_read_b128 v[234:237], v199 offset:7168
	global_load_lds_dwordx4 v[162:163], off
	v_lshl_add_u64 v[162:163], s[12:13], 0, v[190:191]
	s_add_i32 m0, s27, 0xe000
	s_nop 0
	global_load_lds_dwordx4 v[162:163], off
	s_waitcnt vmcnt(8)
	s_waitcnt lgkmcnt(0)
	s_setprio 1
	s_barrier
	v_mfma_f32_16x16x32_bf16 v[134:137], v[2:5], v[202:205], v[134:137]
	v_mfma_f32_16x16x32_bf16 v[130:133], v[138:141], v[202:205], v[130:133]
	v_mfma_f32_16x16x32_bf16 v[118:121], v[2:5], v[214:217], v[118:121]
	v_mfma_f32_16x16x32_bf16 v[114:117], v[138:141], v[214:217], v[114:117]
	v_mfma_f32_16x16x32_bf16 v[102:105], v[2:5], v[222:225], v[102:105]
	v_mfma_f32_16x16x32_bf16 v[98:101], v[138:141], v[222:225], v[98:101]
	v_mfma_f32_16x16x32_bf16 v[86:89], v[2:5], v[230:233], v[86:89]
	v_mfma_f32_16x16x32_bf16 v[82:85], v[138:141], v[230:233], v[82:85]
	v_mfma_f32_16x16x32_bf16 v[134:137], v[6:9], v[206:209], v[134:137]
	v_mfma_f32_16x16x32_bf16 v[130:133], v[142:145], v[206:209], v[130:133]
	v_mfma_f32_16x16x32_bf16 v[118:121], v[6:9], v[218:221], v[118:121]
	v_mfma_f32_16x16x32_bf16 v[114:117], v[142:145], v[218:221], v[114:117]
	v_mfma_f32_16x16x32_bf16 v[102:105], v[6:9], v[226:229], v[102:105]
	v_mfma_f32_16x16x32_bf16 v[98:101], v[142:145], v[226:229], v[98:101]
	v_mfma_f32_16x16x32_bf16 v[86:89], v[6:9], v[234:237], v[86:89]
	v_mfma_f32_16x16x32_bf16 v[82:85], v[142:145], v[234:237], v[82:85]
	s_setprio 0
	s_setprio 1
	v_mfma_f32_16x16x32_bf16 v[126:129], v[146:149], v[202:205], v[126:129]
	v_mfma_f32_16x16x32_bf16 v[122:125], v[154:157], v[202:205], v[122:125]
	v_mfma_f32_16x16x32_bf16 v[110:113], v[146:149], v[214:217], v[110:113]
	v_mfma_f32_16x16x32_bf16 v[106:109], v[154:157], v[214:217], v[106:109]
	v_mfma_f32_16x16x32_bf16 v[94:97], v[146:149], v[222:225], v[94:97]
	v_mfma_f32_16x16x32_bf16 v[90:93], v[154:157], v[222:225], v[90:93]
	v_mfma_f32_16x16x32_bf16 v[78:81], v[146:149], v[230:233], v[78:81]
	v_mfma_f32_16x16x32_bf16 v[74:77], v[154:157], v[230:233], v[74:77]
	v_mfma_f32_16x16x32_bf16 v[126:129], v[150:153], v[206:209], v[126:129]
	v_mfma_f32_16x16x32_bf16 v[122:125], v[158:161], v[206:209], v[122:125]
	v_mfma_f32_16x16x32_bf16 v[110:113], v[150:153], v[218:221], v[110:113]
	v_mfma_f32_16x16x32_bf16 v[106:109], v[158:161], v[218:221], v[106:109]
	v_mfma_f32_16x16x32_bf16 v[94:97], v[150:153], v[226:229], v[94:97]
	v_mfma_f32_16x16x32_bf16 v[90:93], v[158:161], v[226:229], v[90:93]
	v_mfma_f32_16x16x32_bf16 v[78:81], v[150:153], v[234:237], v[78:81]
	v_mfma_f32_16x16x32_bf16 v[74:77], v[158:161], v[234:237], v[74:77]
	s_barrier
	s_setprio 0
	s_add_i32 s34, s41, s25
	v_lshl_add_u64 v[162:163], s[14:15], 0, v[168:169]
	s_mov_b32 m0, s34
	ds_read_b128 v[202:205], v199 offset:16384
	ds_read_b128 v[206:209], v199 offset:17408
	ds_read_b128 v[214:217], v199 offset:18432
	ds_read_b128 v[218:221], v199 offset:19456
	ds_read_b128 v[222:225], v199 offset:20480
	ds_read_b128 v[226:229], v199 offset:21504
	ds_read_b128 v[230:233], v199 offset:22528
	ds_read_b128 v[234:237], v199 offset:23552
	global_load_lds_dwordx4 v[162:163], off
	s_add_i32 m0, s34, 0x2000
	s_add_u32 s34, s14, 0x100000
	v_lshl_add_u64 v[210:211], s[14:15], 0, v[172:173]
	s_addc_u32 s35, s15, 0
	s_add_i32 s79, s92, s25
	global_load_lds_dwordx4 v[210:211], off
	v_lshl_add_u64 v[238:239], s[34:35], 0, v[168:169]
	s_mov_b32 m0, s79
	v_lshl_add_u64 v[240:241], s[16:17], 0, v[170:171]
	global_load_lds_dwordx4 v[238:239], off
	v_lshl_add_u64 v[238:239], s[34:35], 0, v[172:173]
	s_add_i32 m0, s79, 0x2000
	s_nop 0
	global_load_lds_dwordx4 v[238:239], off
	v_lshl_add_u64 v[238:239], s[16:17], 0, v[164:165]
	s_mov_b32 m0, s27
	s_nop 0
	global_load_lds_dwordx4 v[238:239], off
	s_mov_b32 m0, s39
	s_nop 0
	global_load_lds_dwordx4 v[240:241], off
	s_waitcnt vmcnt(8)
	s_waitcnt lgkmcnt(0)
	s_setprio 1
	s_barrier
; #define PG8_STAGE(bufoff, gbase, voff) do { _Pragma("unroll") for (int _i = 0; _i < 2; ++_i) \
;         __builtin_amdgcn_global_load_lds((const unsigned*)((const char*)(gbase) + (voff)[_i]), (PG8_LAS unsigned*)(lds + (bufoff) + ldsw + _i * 8192), 16, 0, 0); } while (0)
; #define PG8_LDA(dst, b, h) do { _Pragma("unroll") for (int m = 0; m < 4; ++m) _Pragma("unroll") for (int k = 0; k < 2; ++k) dst[m][k] = *(const PG8_LAS bf16x8*)(lds + PG8_SA(b, h) + aoff + m * 2048 + k * 1024); } while (0)
; #define PG8_LDB(dst, b, h) do { _Pragma("unroll") for (int n = 0; n < 2; ++n) _Pragma("unroll") for (int k = 0; k < 2; ++k) dst[n][k] = *(const PG8_LAS bf16x8*)(lds + PG8_SB(b, h) + boff + n * 2048 + k * 1024); } while (0)
; #define PG8_MMA(ai, bj, At, Bt) do { __builtin_amdgcn_s_setprio(1); _Pragma("unroll") for (int m = 0; m < 4; ++m) _Pragma("unroll") for (int n = 0; n < 2; ++n) _Pragma("unroll") for (int k = 0; k < 2; ++k) \
;         acc[ai][bj][m][n] = __builtin_amdgcn_mfma_f32_16x16x32_bf16(Bt[n][k], At[m][k], acc[ai][bj][m][n], 0, 0, 0); __builtin_amdgcn_s_setprio(0); } while (0)
; #define PG8_WAIT_V(n) asm volatile("s_waitcnt vmcnt(" #n ")" ::: "memory")
; #define PG8_WAIT_L(n) asm volatile("s_waitcnt lgkmcnt(" #n ")" ::: "memory")
; #define PG8_BAR __builtin_amdgcn_s_barrier()
; #define PG8_SCHED __builtin_amdgcn_sched_barrier(0)
; template <class Epi, class Sched, bool ALIGN_EPI = false, bool SP2 = false>
; __device__ __forceinline__ void gemm_phase(PG8_LAS unsigned char* lds, const Gemm g, const Sched& S, const Epi& E) {
;     ...
;             PG8_WAIT_V(8); PG8_WAIT_L(0); PG8_BAR; PG8_MMA(1, 0, At, B0); PG8_MMA(1, 1, At, B1); PG8_BAR; PG8_SCHED;
;             PG8_LDB(B0, 1, 0); PG8_LDB(B1, 1, 1); PG8_SCHED; PG8_LDA(At, 1, 0); PG8_STAGE(PG8_SA(0, 1), a2 + hstep, voffA);
;             PG8_WAIT_V(8); PG8_WAIT_L(0); PG8_BAR; PG8_MMA(0, 0, At, B0); PG8_MMA(0, 1, At, B1); PG8_BAR; PG8_SCHED;
	v_mfma_f32_16x16x32_bf16 v[70:73], v[2:5], v[202:205], v[70:73]
	v_mfma_f32_16x16x32_bf16 v[66:69], v[138:141], v[202:205], v[66:69]
	v_mfma_f32_16x16x32_bf16 v[54:57], v[2:5], v[214:217], v[54:57]
	v_mfma_f32_16x16x32_bf16 v[50:53], v[138:141], v[214:217], v[50:53]
	v_mfma_f32_16x16x32_bf16 v[38:41], v[2:5], v[222:225], v[38:41]
	v_mfma_f32_16x16x32_bf16 v[34:37], v[138:141], v[222:225], v[34:37]
	v_mfma_f32_16x16x32_bf16 v[2:5], v[2:5], v[230:233], v[22:25]
	v_mfma_f32_16x16x32_bf16 v[70:73], v[6:9], v[206:209], v[70:73]
	v_mfma_f32_16x16x32_bf16 v[66:69], v[142:145], v[206:209], v[66:69]
	v_mfma_f32_16x16x32_bf16 v[54:57], v[6:9], v[218:221], v[54:57]
	v_mfma_f32_16x16x32_bf16 v[50:53], v[142:145], v[218:221], v[50:53]
	v_mfma_f32_16x16x32_bf16 v[38:41], v[6:9], v[226:229], v[38:41]
	v_mfma_f32_16x16x32_bf16 v[34:37], v[142:145], v[226:229], v[34:37]
	v_mfma_f32_16x16x32_bf16 v[2:5], v[6:9], v[234:237], v[2:5]
	v_mfma_f32_16x16x32_bf16 v[6:9], v[138:141], v[230:233], v[18:21]
	v_mfma_f32_16x16x32_bf16 v[6:9], v[142:145], v[234:237], v[6:9]
	s_setprio 0
	s_setprio 1
	v_mfma_f32_16x16x32_bf16 v[18:21], v[146:149], v[202:205], v[62:65]
	v_mfma_f32_16x16x32_bf16 v[62:65], v[150:153], v[206:209], v[18:21]
	v_mfma_f32_16x16x32_bf16 v[18:21], v[154:157], v[202:205], v[58:61]
	v_mfma_f32_16x16x32_bf16 v[58:61], v[158:161], v[206:209], v[18:21]
	v_mfma_f32_16x16x32_bf16 v[18:21], v[146:149], v[214:217], v[46:49]
	v_mfma_f32_16x16x32_bf16 v[46:49], v[150:153], v[218:221], v[18:21]
	v_mfma_f32_16x16x32_bf16 v[18:21], v[154:157], v[214:217], v[42:45]
	v_mfma_f32_16x16x32_bf16 v[42:45], v[158:161], v[218:221], v[18:21]
	v_mfma_f32_16x16x32_bf16 v[18:21], v[146:149], v[222:225], v[30:33]
	v_mfma_f32_16x16x32_bf16 v[30:33], v[150:153], v[226:229], v[18:21]
	v_mfma_f32_16x16x32_bf16 v[18:21], v[154:157], v[222:225], v[26:29]
	v_mfma_f32_16x16x32_bf16 v[14:17], v[146:149], v[230:233], v[14:17]
	v_mfma_f32_16x16x32_bf16 v[10:13], v[154:157], v[230:233], v[10:13]
	v_mfma_f32_16x16x32_bf16 v[26:29], v[158:161], v[226:229], v[18:21]
	v_mfma_f32_16x16x32_bf16 v[14:17], v[150:153], v[234:237], v[14:17]
	v_mfma_f32_16x16x32_bf16 v[10:13], v[158:161], v[234:237], v[10:13]
	s_barrier
	s_setprio 0
	s_add_i32 s34, 0, 0x18000
	s_add_i32 s35, 0, 0x1c000
	v_add_u32_e32 v142, s34, v179
	v_add_u32_e32 v158, s35, v179
	ds_read_b128 v[18:21], v142
	ds_read_b128 v[22:25], v142 offset:1024
	ds_read_b128 v[138:141], v142 offset:2048
	ds_read_b128 v[142:145], v142 offset:3072
	ds_read_b128 v[146:149], v158
	ds_read_b128 v[150:153], v158 offset:1024
	ds_read_b128 v[154:157], v158 offset:2048
	ds_read_b128 v[158:161], v158 offset:3072
	s_add_u32 s16, s16, 0x100000
	s_addc_u32 s17, s17, 0
	s_mov_b32 m0, s71
	v_lshl_add_u64 v[242:243], s[16:17], 0, v[164:165]
	ds_read_b128 v[202:205], v199 offset:32768
	ds_read_b128 v[206:209], v199 offset:33792
	ds_read_b128 v[214:217], v199 offset:34816
	ds_read_b128 v[218:221], v199 offset:35840
	ds_read_b128 v[222:225], v199 offset:36864
	ds_read_b128 v[226:229], v199 offset:37888
	ds_read_b128 v[230:233], v199 offset:38912
	ds_read_b128 v[234:237], v199 offset:39936
	global_load_lds_dwordx4 v[242:243], off
	v_lshl_add_u64 v[242:243], s[16:17], 0, v[170:171]
	s_mov_b32 m0, s87
	s_nop 0
	global_load_lds_dwordx4 v[242:243], off
	s_waitcnt vmcnt(8)
	s_waitcnt lgkmcnt(0)
	s_setprio 1
	s_barrier
	v_mfma_f32_16x16x32_bf16 v[134:137], v[18:21], v[202:205], v[134:137]
	v_mfma_f32_16x16x32_bf16 v[130:133], v[138:141], v[202:205], v[130:133]
	v_mfma_f32_16x16x32_bf16 v[118:121], v[18:21], v[214:217], v[118:121]
	v_mfma_f32_16x16x32_bf16 v[114:117], v[138:141], v[214:217], v[114:117]
	v_mfma_f32_16x16x32_bf16 v[102:105], v[18:21], v[222:225], v[102:105]
	v_mfma_f32_16x16x32_bf16 v[98:101], v[138:141], v[222:225], v[98:101]
	v_mfma_f32_16x16x32_bf16 v[86:89], v[18:21], v[230:233], v[86:89]
	v_mfma_f32_16x16x32_bf16 v[82:85], v[138:141], v[230:233], v[82:85]
	v_mfma_f32_16x16x32_bf16 v[134:137], v[22:25], v[206:209], v[134:137]
	v_mfma_f32_16x16x32_bf16 v[130:133], v[142:145], v[206:209], v[130:133]
	v_mfma_f32_16x16x32_bf16 v[118:121], v[22:25], v[218:221], v[118:121]
	v_mfma_f32_16x16x32_bf16 v[114:117], v[142:145], v[218:221], v[114:117]
	v_mfma_f32_16x16x32_bf16 v[102:105], v[22:25], v[226:229], v[102:105]
	v_mfma_f32_16x16x32_bf16 v[98:101], v[142:145], v[226:229], v[98:101]
	v_mfma_f32_16x16x32_bf16 v[86:89], v[22:25], v[234:237], v[86:89]
	v_mfma_f32_16x16x32_bf16 v[82:85], v[142:145], v[234:237], v[82:85]
	s_setprio 0
	s_setprio 1
	v_mfma_f32_16x16x32_bf16 v[126:129], v[146:149], v[202:205], v[126:129]
	v_mfma_f32_16x16x32_bf16 v[122:125], v[154:157], v[202:205], v[122:125]
	v_mfma_f32_16x16x32_bf16 v[110:113], v[146:149], v[214:217], v[110:113]
	v_mfma_f32_16x16x32_bf16 v[106:109], v[154:157], v[214:217], v[106:109]
	v_mfma_f32_16x16x32_bf16 v[94:97], v[146:149], v[222:225], v[94:97]
	v_mfma_f32_16x16x32_bf16 v[90:93], v[154:157], v[222:225], v[90:93]
	v_mfma_f32_16x16x32_bf16 v[78:81], v[146:149], v[230:233], v[78:81]
	v_mfma_f32_16x16x32_bf16 v[74:77], v[154:157], v[230:233], v[74:77]
	v_mfma_f32_16x16x32_bf16 v[126:129], v[150:153], v[206:209], v[126:129]
	v_mfma_f32_16x16x32_bf16 v[122:125], v[158:161], v[206:209], v[122:125]
	v_mfma_f32_16x16x32_bf16 v[110:113], v[150:153], v[218:221], v[110:113]
	v_mfma_f32_16x16x32_bf16 v[106:109], v[158:161], v[218:221], v[106:109]
	v_mfma_f32_16x16x32_bf16 v[94:97], v[150:153], v[226:229], v[94:97]
	v_mfma_f32_16x16x32_bf16 v[90:93], v[158:161], v[226:229], v[90:93]
	v_mfma_f32_16x16x32_bf16 v[78:81], v[150:153], v[234:237], v[78:81]
	v_mfma_f32_16x16x32_bf16 v[74:77], v[158:161], v[234:237], v[74:77]
	s_barrier
; #define PG8_STAGE(bufoff, gbase, voff) do { _Pragma("unroll") for (int _i = 0; _i < 2; ++_i) \
;         __builtin_amdgcn_global_load_lds((const unsigned*)((const char*)(gbase) + (voff)[_i]), (PG8_LAS unsigned*)(lds + (bufoff) + ldsw + _i * 8192), 16, 0, 0); } while (0)
; #define PG8_LDA(dst, b, h) do { _Pragma("unroll") for (int m = 0; m < 4; ++m) _Pragma("unroll") for (int k = 0; k < 2; ++k) dst[m][k] = *(const PG8_LAS bf16x8*)(lds + PG8_SA(b, h) + aoff + m * 2048 + k * 1024); } while (0)
; #define PG8_LDB(dst, b, h) do { _Pragma("unroll") for (int n = 0; n < 2; ++n) _Pragma("unroll") for (int k = 0; k < 2; ++k) dst[n][k] = *(const PG8_LAS bf16x8*)(lds + PG8_SB(b, h) + boff + n * 2048 + k * 1024); } while (0)
; #define PG8_MMA(ai, bj, At, Bt) do { __builtin_amdgcn_s_setprio(1); _Pragma("unroll") for (int m = 0; m < 4; ++m) _Pragma("unroll") for (int n = 0; n < 2; ++n) _Pragma("unroll") for (int k = 0; k < 2; ++k) \
;         acc[ai][bj][m][n] = __builtin_amdgcn_mfma_f32_16x16x32_bf16(Bt[n][k], At[m][k], acc[ai][bj][m][n], 0, 0, 0); __builtin_amdgcn_s_setprio(0); } while (0)
; #define PG8_WAIT_V(n) asm volatile("s_waitcnt vmcnt(" #n ")" ::: "memory")
; #define PG8_WAIT_L(n) asm volatile("s_waitcnt lgkmcnt(" #n ")" ::: "memory")
; #define PG8_BAR __builtin_amdgcn_s_barrier()
; #define PG8_SCHED __builtin_amdgcn_sched_barrier(0)
; template <class Epi, class Sched, bool ALIGN_EPI = false, bool SP2 = false>
; __device__ __forceinline__ void gemm_phase(PG8_LAS unsigned char* lds, const Gemm g, const Sched& S, const Epi& E) {
;     ...
;         for (int t = 0; t < nt; t += 2) {
;     ...
;             PG8_LDB(B0, 1, 0); PG8_LDB(B1, 1, 1); PG8_SCHED; PG8_LDA(At, 1, 0); PG8_STAGE(PG8_SA(0, 1), a2 + hstep, voffA);
;             PG8_WAIT_V(8); PG8_WAIT_L(0); PG8_BAR; PG8_MMA(0, 0, At, B0); PG8_MMA(0, 1, At, B1); PG8_BAR; PG8_SCHED;
;             PG8_LDA(At, 1, 1); PG8_STAGE(PG8_SB(1, 0), b3, voffB); PG8_STAGE(PG8_SB(1, 1), b3 + hstep, voffB); PG8_STAGE(PG8_SA(1, 0), a3, voffA);
;             PG8_WAIT_V(8); PG8_WAIT_L(0); PG8_BAR; PG8_MMA(1, 0, At, B0); PG8_MMA(1, 1, At, B1); PG8_BAR; PG8_SCHED;
	s_setprio 0
	s_add_i32 s16, s34, s25
	v_lshl_add_u64 v[162:163], v[162:163], 0, s[46:47]
	s_mov_b32 m0, s16
	ds_read_b128 v[202:205], v199 offset:49152
	ds_read_b128 v[206:209], v199 offset:50176
	ds_read_b128 v[214:217], v199 offset:51200
	ds_read_b128 v[218:221], v199 offset:52224
	ds_read_b128 v[222:225], v199 offset:53248
	ds_read_b128 v[226:229], v199 offset:54272
	ds_read_b128 v[230:233], v199 offset:55296
	ds_read_b128 v[234:237], v199 offset:56320
	global_load_lds_dwordx4 v[162:163], off
	s_add_i32 m0, s16, 0x2000
	s_add_u32 s14, s14, 0x100080
	v_lshl_add_u64 v[162:163], v[210:211], 0, s[46:47]
	s_addc_u32 s15, s15, 0
	s_add_i32 s16, s35, s25
	global_load_lds_dwordx4 v[162:163], off
	v_lshl_add_u64 v[162:163], s[14:15], 0, v[168:169]
	s_mov_b32 m0, s16
	s_nop 0
	global_load_lds_dwordx4 v[162:163], off
	v_lshl_add_u64 v[162:163], s[14:15], 0, v[172:173]
	s_add_i32 m0, s16, 0x2000
	s_nop 0
	global_load_lds_dwordx4 v[162:163], off
	v_lshl_add_u64 v[162:163], v[238:239], 0, s[46:47]
	s_mov_b32 m0, s95
	s_nop 0
	global_load_lds_dwordx4 v[162:163], off
	v_lshl_add_u64 v[162:163], v[240:241], 0, s[46:47]
	s_mov_b32 m0, s96
	s_nop 0
	global_load_lds_dwordx4 v[162:163], off
	s_waitcnt vmcnt(8)
	s_waitcnt lgkmcnt(0)
	s_setprio 1
	s_barrier
	v_mfma_f32_16x16x32_bf16 v[70:73], v[18:21], v[202:205], v[70:73]
	v_mfma_f32_16x16x32_bf16 v[54:57], v[18:21], v[214:217], v[54:57]
	v_mfma_f32_16x16x32_bf16 v[38:41], v[18:21], v[222:225], v[38:41]
	v_mfma_f32_16x16x32_bf16 v[2:5], v[18:21], v[230:233], v[2:5]
	v_mfma_f32_16x16x32_bf16 v[70:73], v[22:25], v[206:209], v[70:73]
	v_mfma_f32_16x16x32_bf16 v[66:69], v[138:141], v[202:205], v[66:69]
	v_mfma_f32_16x16x32_bf16 v[54:57], v[22:25], v[218:221], v[54:57]
	v_mfma_f32_16x16x32_bf16 v[50:53], v[138:141], v[214:217], v[50:53]
	v_mfma_f32_16x16x32_bf16 v[38:41], v[22:25], v[226:229], v[38:41]
	v_mfma_f32_16x16x32_bf16 v[34:37], v[138:141], v[222:225], v[34:37]
	v_mfma_f32_16x16x32_bf16 v[22:25], v[22:25], v[234:237], v[2:5]
	v_mfma_f32_16x16x32_bf16 v[2:5], v[138:141], v[230:233], v[6:9]
	v_mfma_f32_16x16x32_bf16 v[66:69], v[142:145], v[206:209], v[66:69]
	v_mfma_f32_16x16x32_bf16 v[50:53], v[142:145], v[218:221], v[50:53]
	v_mfma_f32_16x16x32_bf16 v[34:37], v[142:145], v[226:229], v[34:37]
	v_mfma_f32_16x16x32_bf16 v[18:21], v[142:145], v[234:237], v[2:5]
	s_setprio 0
	s_setprio 1
	v_mfma_f32_16x16x32_bf16 v[2:5], v[146:149], v[202:205], v[62:65]
	v_mfma_f32_16x16x32_bf16 v[62:65], v[150:153], v[206:209], v[2:5]
	v_mfma_f32_16x16x32_bf16 v[2:5], v[154:157], v[202:205], v[58:61]
	v_mfma_f32_16x16x32_bf16 v[58:61], v[158:161], v[206:209], v[2:5]
	v_mfma_f32_16x16x32_bf16 v[2:5], v[146:149], v[214:217], v[46:49]
	v_mfma_f32_16x16x32_bf16 v[46:49], v[150:153], v[218:221], v[2:5]
	v_mfma_f32_16x16x32_bf16 v[2:5], v[154:157], v[214:217], v[42:45]
	v_mfma_f32_16x16x32_bf16 v[42:45], v[158:161], v[218:221], v[2:5]
	v_mfma_f32_16x16x32_bf16 v[2:5], v[146:149], v[222:225], v[30:33]
	v_mfma_f32_16x16x32_bf16 v[30:33], v[150:153], v[226:229], v[2:5]
	v_mfma_f32_16x16x32_bf16 v[2:5], v[154:157], v[222:225], v[26:29]
	v_mfma_f32_16x16x32_bf16 v[26:29], v[158:161], v[226:229], v[2:5]
	v_mfma_f32_16x16x32_bf16 v[2:5], v[146:149], v[230:233], v[14:17]
	v_mfma_f32_16x16x32_bf16 v[14:17], v[150:153], v[234:237], v[2:5]
	v_mfma_f32_16x16x32_bf16 v[2:5], v[154:157], v[230:233], v[10:13]
	v_mfma_f32_16x16x32_bf16 v[10:13], v[158:161], v[234:237], v[2:5]
	s_barrier
	s_setprio 0
	s_add_i32 s33, s33, 2
	s_add_u32 s12, s12, 0x100
	s_addc_u32 s13, s13, 0
	s_add_u32 s29, s29, 0x100
	s_addc_u32 s30, s30, 0
	s_cmp_gt_u32 s33, 61
	s_cbranch_scc0 .LBB0_139
	s_and_b64 vcc, exec, s[48:49]
	s_cbranch_vccz .LBB0_142
	s_barrier

; #define PG8_STAGE(bufoff, gbase, voff) do { _Pragma("unroll") for (int _i = 0; _i < 2; ++_i) \
;         __builtin_amdgcn_global_load_lds((const unsigned*)((const char*)(gbase) + (voff)[_i]), (PG8_LAS unsigned*)(lds + (bufoff) + ldsw + _i * 8192), 16, 0, 0); } while (0)
; #define PG8_LDA(dst, b, h) do { _Pragma("unroll") for (int m = 0; m < 4; ++m) _Pragma("unroll") for (int k = 0; k < 2; ++k) dst[m][k] = *(const PG8_LAS bf16x8*)(lds + PG8_SA(b, h) + aoff + m * 2048 + k * 1024); } while (0)
; #define PG8_LDB(dst, b, h) do { _Pragma("unroll") for (int n = 0; n < 2; ++n) _Pragma("unroll") for (int k = 0; k < 2; ++k) dst[n][k] = *(const PG8_LAS bf16x8*)(lds + PG8_SB(b, h) + boff + n * 2048 + k * 1024); } while (0)
; #define PG8_MMA(ai, bj, At, Bt) do { __builtin_amdgcn_s_setprio(1); _Pragma("unroll") for (int m = 0; m < 4; ++m) _Pragma("unroll") for (int n = 0; n < 2; ++n) _Pragma("unroll") for (int k = 0; k < 2; ++k) \
;         acc[ai][bj][m][n] = __builtin_amdgcn_mfma_f32_16x16x32_bf16(Bt[n][k], At[m][k], acc[ai][bj][m][n], 0, 0, 0); __builtin_amdgcn_s_setprio(0); } while (0)
; #define PG8_WAIT_V(n) asm volatile("s_waitcnt vmcnt(" #n ")" ::: "memory")
; #define PG8_WAIT_L(n) asm volatile("s_waitcnt lgkmcnt(" #n ")" ::: "memory")
; #define PG8_BAR __builtin_amdgcn_s_barrier()
; #define PG8_SCHED __builtin_amdgcn_sched_barrier(0)
; template <class Epi, class Sched, bool ALIGN_EPI = false, bool SP2 = false>
; __device__ __forceinline__ void gemm_phase(PG8_LAS unsigned char* lds, const Gemm g, const Sched& S, const Epi& E) {
;     ...
;             PG8_LDB(B0, 0, 0); PG8_LDB(B1, 0, 1); PG8_SCHED; PG8_LDA(At, 0, 0); PG8_STAGE(PG8_SA(1, 1), a1 + hstep, voffA);
;             PG8_WAIT_V(8); PG8_WAIT_L(0); PG8_BAR; PG8_MMA(0, 0, At, B0); PG8_MMA(0, 1, At, B1); PG8_BAR; PG8_SCHED;
;             PG8_LDA(At, 0, 1); PG8_STAGE(PG8_SB(0, 0), b2, voffB); PG8_STAGE(PG8_SB(0, 1), b2 + hstep, voffB); PG8_STAGE(PG8_SA(0, 0), a2, voffA);
;             PG8_WAIT_V(8); PG8_WAIT_L(0); PG8_BAR; PG8_MMA(1, 0, At, B0); PG8_MMA(1, 1, At, B1); PG8_BAR; PG8_SCHED;
.LBB0_592:
	s_or_b32 s10, s52, 1
	s_lshl_b64 s[96:97], s[10:11], 7
	s_add_i32 s10, s52, 2
	s_lshl_b64 s[54:55], s[10:11], 7
	s_cmp_lg_u32 s52, s94
	s_cselect_b32 s52, s54, 0
	s_cselect_b32 s53, s55, 0
	s_add_u32 s54, s50, s52
	s_addc_u32 s55, s51, s53
	s_add_i32 s95, 0, 0x10000
	v_add_u32_e32 v87, s95, v85
	ds_read_b128 v[88:91], v87
	ds_read_b128 v[92:95], v87 offset:1024
	ds_read_b128 v[100:103], v87 offset:2048
	ds_read_b128 v[104:107], v87 offset:3072
	s_add_u32 s52, s48, s52
	s_addc_u32 s53, s49, s53
	s_add_u32 s96, s50, s96
	s_addc_u32 s97, s51, s97
	s_add_u32 s96, s96, 0x100000
	s_addc_u32 s97, s97, 0
	v_lshl_add_u64 v[96:97], s[96:97], 0, v[66:67]
	s_add_i32 m0, s17, 0xc000
	ds_read_b128 v[108:111], v86
	ds_read_b128 v[112:115], v86 offset:1024
	ds_read_b128 v[116:119], v86 offset:2048
	ds_read_b128 v[120:123], v86 offset:3072
	ds_read_b128 v[124:127], v86 offset:4096
	ds_read_b128 v[128:131], v86 offset:5120
	ds_read_b128 v[132:135], v86 offset:6144
	ds_read_b128 v[136:139], v86 offset:7168
	global_load_lds_dwordx4 v[96:97], off
	v_lshl_add_u64 v[96:97], s[96:97], 0, v[76:77]
	s_add_i32 m0, s17, 0xe000
	s_nop 0
	global_load_lds_dwordx4 v[96:97], off
	s_waitcnt vmcnt(8)
	s_waitcnt lgkmcnt(0)
	s_setprio 1
	s_barrier
	v_mfma_f32_16x16x32_bf16 v[62:65], v[88:91], v[108:111], v[62:65]
	v_mfma_f32_16x16x32_bf16 v[58:61], v[100:103], v[108:111], v[58:61]
	v_mfma_f32_16x16x32_bf16 v[54:57], v[88:91], v[116:119], v[54:57]
	v_mfma_f32_16x16x32_bf16 v[50:53], v[100:103], v[116:119], v[50:53]
	v_mfma_f32_16x16x32_bf16 v[46:49], v[88:91], v[124:127], v[46:49]
	v_mfma_f32_16x16x32_bf16 v[42:45], v[100:103], v[124:127], v[42:45]
	v_mfma_f32_16x16x32_bf16 v[38:41], v[88:91], v[132:135], v[38:41]
	v_mfma_f32_16x16x32_bf16 v[34:37], v[100:103], v[132:135], v[34:37]
	v_mfma_f32_16x16x32_bf16 v[62:65], v[92:95], v[112:115], v[62:65]
	v_mfma_f32_16x16x32_bf16 v[58:61], v[104:107], v[112:115], v[58:61]
	v_mfma_f32_16x16x32_bf16 v[54:57], v[92:95], v[120:123], v[54:57]
	v_mfma_f32_16x16x32_bf16 v[50:53], v[104:107], v[120:123], v[50:53]
	v_mfma_f32_16x16x32_bf16 v[46:49], v[92:95], v[128:131], v[46:49]
	v_mfma_f32_16x16x32_bf16 v[42:45], v[104:107], v[128:131], v[42:45]
	v_mfma_f32_16x16x32_bf16 v[38:41], v[92:95], v[136:139], v[38:41]
	v_mfma_f32_16x16x32_bf16 v[34:37], v[104:107], v[136:139], v[34:37]
	s_setprio 0
	s_setprio 1
	s_setprio 0
	s_barrier
	s_add_i32 s95, s95, s29
	v_lshl_add_u64 v[96:97], s[52:53], 0, v[78:79]
	s_mov_b32 m0, s95
	ds_read_b128 v[108:111], v86 offset:16384
	ds_read_b128 v[112:115], v86 offset:17408
	ds_read_b128 v[116:119], v86 offset:18432
	ds_read_b128 v[120:123], v86 offset:19456
	ds_read_b128 v[124:127], v86 offset:20480
	ds_read_b128 v[128:131], v86 offset:21504
	ds_read_b128 v[132:135], v86 offset:22528
	ds_read_b128 v[136:139], v86 offset:23552
	global_load_lds_dwordx4 v[96:97], off
	s_add_i32 m0, s95, 0x2000
	s_add_u32 s96, s52, 0x100000
	v_lshl_add_u64 v[140:141], s[52:53], 0, v[74:75]
	s_addc_u32 s97, s53, 0
	global_load_lds_dwordx4 v[140:141], off
	v_lshl_add_u64 v[142:143], s[96:97], 0, v[78:79]
	s_mov_b32 m0, s30
	v_lshl_add_u64 v[144:145], s[54:55], 0, v[76:77]
	global_load_lds_dwordx4 v[142:143], off
	v_lshl_add_u64 v[142:143], s[96:97], 0, v[74:75]
	s_mov_b32 m0, s33
	s_nop 0
	global_load_lds_dwordx4 v[142:143], off
	v_lshl_add_u64 v[142:143], s[54:55], 0, v[66:67]
	s_mov_b32 m0, s17
	s_nop 0
	global_load_lds_dwordx4 v[142:143], off
	s_mov_b32 m0, s34
	s_nop 0
	global_load_lds_dwordx4 v[144:145], off
	s_waitcnt vmcnt(8)
	s_waitcnt lgkmcnt(0)
	s_setprio 1
	s_barrier
	v_mfma_f32_16x16x32_bf16 v[30:33], v[88:91], v[108:111], v[30:33]
	v_mfma_f32_16x16x32_bf16 v[26:29], v[100:103], v[108:111], v[26:29]
	v_mfma_f32_16x16x32_bf16 v[22:25], v[88:91], v[116:119], v[22:25]
	v_mfma_f32_16x16x32_bf16 v[18:21], v[100:103], v[116:119], v[18:21]
	v_mfma_f32_16x16x32_bf16 v[14:17], v[88:91], v[124:127], v[14:17]
	v_mfma_f32_16x16x32_bf16 v[10:13], v[100:103], v[124:127], v[10:13]
	v_mfma_f32_16x16x32_bf16 v[6:9], v[88:91], v[132:135], v[6:9]
	v_mfma_f32_16x16x32_bf16 v[2:5], v[100:103], v[132:135], v[2:5]
	v_mfma_f32_16x16x32_bf16 v[30:33], v[92:95], v[112:115], v[30:33]
	v_mfma_f32_16x16x32_bf16 v[26:29], v[104:107], v[112:115], v[26:29]
	v_mfma_f32_16x16x32_bf16 v[22:25], v[92:95], v[120:123], v[22:25]
	v_mfma_f32_16x16x32_bf16 v[18:21], v[104:107], v[120:123], v[18:21]
	v_mfma_f32_16x16x32_bf16 v[14:17], v[92:95], v[128:131], v[14:17]
	v_mfma_f32_16x16x32_bf16 v[10:13], v[104:107], v[128:131], v[10:13]
	v_mfma_f32_16x16x32_bf16 v[6:9], v[92:95], v[136:139], v[6:9]
	v_mfma_f32_16x16x32_bf16 v[2:5], v[104:107], v[136:139], v[2:5]
	s_setprio 0
	s_setprio 1
	s_setprio 0
	s_barrier
; #define PG8_STAGE(bufoff, gbase, voff) do { _Pragma("unroll") for (int _i = 0; _i < 2; ++_i) \
;         __builtin_amdgcn_global_load_lds((const unsigned*)((const char*)(gbase) + (voff)[_i]), (PG8_LAS unsigned*)(lds + (bufoff) + ldsw + _i * 8192), 16, 0, 0); } while (0)
; #define PG8_LDA(dst, b, h) do { _Pragma("unroll") for (int m = 0; m < 4; ++m) _Pragma("unroll") for (int k = 0; k < 2; ++k) dst[m][k] = *(const PG8_LAS bf16x8*)(lds + PG8_SA(b, h) + aoff + m * 2048 + k * 1024); } while (0)
; #define PG8_LDB(dst, b, h) do { _Pragma("unroll") for (int n = 0; n < 2; ++n) _Pragma("unroll") for (int k = 0; k < 2; ++k) dst[n][k] = *(const PG8_LAS bf16x8*)(lds + PG8_SB(b, h) + boff + n * 2048 + k * 1024); } while (0)
; #define PG8_MMA(ai, bj, At, Bt) do { __builtin_amdgcn_s_setprio(1); _Pragma("unroll") for (int m = 0; m < 4; ++m) _Pragma("unroll") for (int n = 0; n < 2; ++n) _Pragma("unroll") for (int k = 0; k < 2; ++k) \
;         acc[ai][bj][m][n] = __builtin_amdgcn_mfma_f32_16x16x32_bf16(Bt[n][k], At[m][k], acc[ai][bj][m][n], 0, 0, 0); __builtin_amdgcn_s_setprio(0); } while (0)
; #define PG8_WAIT_V(n) asm volatile("s_waitcnt vmcnt(" #n ")" ::: "memory")
; #define PG8_WAIT_L(n) asm volatile("s_waitcnt lgkmcnt(" #n ")" ::: "memory")
; #define PG8_BAR __builtin_amdgcn_s_barrier()
; #define PG8_SCHED __builtin_amdgcn_sched_barrier(0)
; template <class Epi, class Sched, bool ALIGN_EPI = false, bool SP2 = false>
; __device__ __forceinline__ void gemm_phase(PG8_LAS unsigned char* lds, const Gemm g, const Sched& S, const Epi& E) {
;     ...
;             PG8_LDB(B0, 1, 0); PG8_LDB(B1, 1, 1); PG8_SCHED; PG8_LDA(At, 1, 0); PG8_STAGE(PG8_SA(0, 1), a2 + hstep, voffA);
;             PG8_WAIT_V(8); PG8_WAIT_L(0); PG8_BAR; PG8_MMA(0, 0, At, B0); PG8_MMA(0, 1, At, B1); PG8_BAR; PG8_SCHED;
;             PG8_LDA(At, 1, 1); PG8_STAGE(PG8_SB(1, 0), b3, voffB); PG8_STAGE(PG8_SB(1, 1), b3 + hstep, voffB); PG8_STAGE(PG8_SA(1, 0), a3, voffA);
;             PG8_WAIT_V(8); PG8_WAIT_L(0); PG8_BAR; PG8_MMA(1, 0, At, B0); PG8_MMA(1, 1, At, B1); PG8_BAR; PG8_SCHED;
	s_add_i32 s95, 0, 0x18000
	v_add_u32_e32 v87, s95, v85
	ds_read_b128 v[88:91], v87
	ds_read_b128 v[92:95], v87 offset:1024
	ds_read_b128 v[100:103], v87 offset:2048
	ds_read_b128 v[104:107], v87 offset:3072
	s_add_u32 s54, s54, 0x100000
	s_addc_u32 s55, s55, 0
	s_mov_b32 m0, s35
	v_lshl_add_u64 v[146:147], s[54:55], 0, v[66:67]
	ds_read_b128 v[108:111], v86 offset:32768
	ds_read_b128 v[112:115], v86 offset:33792
	ds_read_b128 v[116:119], v86 offset:34816
	ds_read_b128 v[120:123], v86 offset:35840
	ds_read_b128 v[124:127], v86 offset:36864
	ds_read_b128 v[128:131], v86 offset:37888
	ds_read_b128 v[132:135], v86 offset:38912
	ds_read_b128 v[136:139], v86 offset:39936
	global_load_lds_dwordx4 v[146:147], off
	v_lshl_add_u64 v[146:147], s[54:55], 0, v[76:77]
	s_mov_b32 m0, s88
	s_nop 0
	global_load_lds_dwordx4 v[146:147], off
	s_waitcnt vmcnt(8)
	s_waitcnt lgkmcnt(0)
	s_setprio 1
	s_barrier
	v_mfma_f32_16x16x32_bf16 v[62:65], v[88:91], v[108:111], v[62:65]
	v_mfma_f32_16x16x32_bf16 v[58:61], v[100:103], v[108:111], v[58:61]
	v_mfma_f32_16x16x32_bf16 v[54:57], v[88:91], v[116:119], v[54:57]
	v_mfma_f32_16x16x32_bf16 v[50:53], v[100:103], v[116:119], v[50:53]
	v_mfma_f32_16x16x32_bf16 v[46:49], v[88:91], v[124:127], v[46:49]
	v_mfma_f32_16x16x32_bf16 v[42:45], v[100:103], v[124:127], v[42:45]
	v_mfma_f32_16x16x32_bf16 v[38:41], v[88:91], v[132:135], v[38:41]
	v_mfma_f32_16x16x32_bf16 v[34:37], v[100:103], v[132:135], v[34:37]
	v_mfma_f32_16x16x32_bf16 v[62:65], v[92:95], v[112:115], v[62:65]
	v_mfma_f32_16x16x32_bf16 v[58:61], v[104:107], v[112:115], v[58:61]
	v_mfma_f32_16x16x32_bf16 v[54:57], v[92:95], v[120:123], v[54:57]
	v_mfma_f32_16x16x32_bf16 v[50:53], v[104:107], v[120:123], v[50:53]
	v_mfma_f32_16x16x32_bf16 v[46:49], v[92:95], v[128:131], v[46:49]
	v_mfma_f32_16x16x32_bf16 v[42:45], v[104:107], v[128:131], v[42:45]
	v_mfma_f32_16x16x32_bf16 v[38:41], v[92:95], v[136:139], v[38:41]
	v_mfma_f32_16x16x32_bf16 v[34:37], v[104:107], v[136:139], v[34:37]
	s_setprio 0
	s_setprio 1
	s_setprio 0
	s_barrier
	s_add_i32 s54, s95, s29
	v_lshl_add_u64 v[96:97], v[96:97], 0, s[14:15]
	s_mov_b32 m0, s54
	ds_read_b128 v[108:111], v86 offset:49152
	ds_read_b128 v[112:115], v86 offset:50176
	ds_read_b128 v[116:119], v86 offset:51200
	ds_read_b128 v[120:123], v86 offset:52224
	ds_read_b128 v[124:127], v86 offset:53248
	ds_read_b128 v[128:131], v86 offset:54272
	ds_read_b128 v[132:135], v86 offset:55296
	ds_read_b128 v[136:139], v86 offset:56320
	global_load_lds_dwordx4 v[96:97], off
	s_add_i32 m0, s54, 0x2000
	s_add_u32 s52, s52, 0x100080
	v_lshl_add_u64 v[96:97], v[140:141], 0, s[14:15]
	s_addc_u32 s53, s53, 0
	global_load_lds_dwordx4 v[96:97], off
	v_lshl_add_u64 v[96:97], s[52:53], 0, v[78:79]
	s_mov_b32 m0, s92
	s_nop 0
	global_load_lds_dwordx4 v[96:97], off
	v_lshl_add_u64 v[96:97], s[52:53], 0, v[74:75]
	s_mov_b32 m0, s93
	s_nop 0
	global_load_lds_dwordx4 v[96:97], off
	v_lshl_add_u64 v[96:97], v[142:143], 0, s[14:15]
	s_mov_b32 m0, s90
	s_nop 0
	global_load_lds_dwordx4 v[96:97], off
	v_lshl_add_u64 v[96:97], v[144:145], 0, s[14:15]
	s_mov_b32 m0, s91
	s_nop 0
	global_load_lds_dwordx4 v[96:97], off
	s_waitcnt vmcnt(8)
	s_waitcnt lgkmcnt(0)
	s_setprio 1
	s_barrier
	v_mfma_f32_16x16x32_bf16 v[30:33], v[88:91], v[108:111], v[30:33]
	v_mfma_f32_16x16x32_bf16 v[26:29], v[100:103], v[108:111], v[26:29]
	v_mfma_f32_16x16x32_bf16 v[22:25], v[88:91], v[116:119], v[22:25]
	v_mfma_f32_16x16x32_bf16 v[18:21], v[100:103], v[116:119], v[18:21]
	v_mfma_f32_16x16x32_bf16 v[14:17], v[88:91], v[124:127], v[14:17]
	v_mfma_f32_16x16x32_bf16 v[10:13], v[100:103], v[124:127], v[10:13]
	v_mfma_f32_16x16x32_bf16 v[6:9], v[88:91], v[132:135], v[6:9]
	v_mfma_f32_16x16x32_bf16 v[2:5], v[100:103], v[132:135], v[2:5]
	v_mfma_f32_16x16x32_bf16 v[30:33], v[92:95], v[112:115], v[30:33]
	v_mfma_f32_16x16x32_bf16 v[26:29], v[104:107], v[112:115], v[26:29]
	v_mfma_f32_16x16x32_bf16 v[22:25], v[92:95], v[120:123], v[22:25]
	v_mfma_f32_16x16x32_bf16 v[18:21], v[104:107], v[120:123], v[18:21]
	v_mfma_f32_16x16x32_bf16 v[14:17], v[92:95], v[128:131], v[14:17]
	v_mfma_f32_16x16x32_bf16 v[10:13], v[104:107], v[128:131], v[10:13]
	v_mfma_f32_16x16x32_bf16 v[6:9], v[92:95], v[136:139], v[6:9]
	v_mfma_f32_16x16x32_bf16 v[2:5], v[104:107], v[136:139], v[2:5]
	s_setprio 0
	s_setprio 1
	s_setprio 0
	s_barrier
	s_cmp_ge_u32 s10, s28
	s_mov_b32 s52, s10
	s_cbranch_scc0 .LBB0_592
	s_cmpk_lt_u32 s26, 0x100
	s_cbranch_scc0 .LBB0_482
	s_barrier
	s_branch .LBB0_482

; #define PG8_STAGE(bufoff, gbase, voff) do { _Pragma("unroll") for (int _i = 0; _i < 2; ++_i) \
;         __builtin_amdgcn_global_load_lds((const unsigned*)((const char*)(gbase) + (voff)[_i]), (PG8_LAS unsigned*)(lds + (bufoff) + ldsw + _i * 8192), 16, 0, 0); } while (0)
; #define PG8_LDA(dst, b, h) do { _Pragma("unroll") for (int m = 0; m < 4; ++m) _Pragma("unroll") for (int k = 0; k < 2; ++k) dst[m][k] = *(const PG8_LAS bf16x8*)(lds + PG8_SA(b, h) + aoff + m * 2048 + k * 1024); } while (0)
; #define PG8_LDB(dst, b, h) do { _Pragma("unroll") for (int n = 0; n < 2; ++n) _Pragma("unroll") for (int k = 0; k < 2; ++k) dst[n][k] = *(const PG8_LAS bf16x8*)(lds + PG8_SB(b, h) + boff + n * 2048 + k * 1024); } while (0)
; #define PG8_MMA(ai, bj, At, Bt) do { __builtin_amdgcn_s_setprio(1); _Pragma("unroll") for (int m = 0; m < 4; ++m) _Pragma("unroll") for (int n = 0; n < 2; ++n) _Pragma("unroll") for (int k = 0; k < 2; ++k) \
;         acc[ai][bj][m][n] = __builtin_amdgcn_mfma_f32_16x16x32_bf16(Bt[n][k], At[m][k], acc[ai][bj][m][n], 0, 0, 0); __builtin_amdgcn_s_setprio(0); } while (0)
; #define PG8_WAIT_V(n) asm volatile("s_waitcnt vmcnt(" #n ")" ::: "memory")
; #define PG8_WAIT_L(n) asm volatile("s_waitcnt lgkmcnt(" #n ")" ::: "memory")
; #define PG8_BAR __builtin_amdgcn_s_barrier()
; #define PG8_SCHED __builtin_amdgcn_sched_barrier(0)
; template <class Epi, class Sched, bool ALIGN_EPI = false, bool SP2 = false>
; __device__ __forceinline__ void gemm_phase(PG8_LAS unsigned char* lds, const Gemm g, const Sched& S, const Epi& E) {
;     ...
;             PG8_LDB(B0, 0, 0); PG8_LDB(B1, 0, 1); PG8_SCHED; PG8_LDA(At, 0, 0); PG8_STAGE(PG8_SA(1, 1), a1 + hstep, voffA);
;             PG8_WAIT_V(8); PG8_WAIT_L(0); PG8_BAR; PG8_MMA(0, 0, At, B0); PG8_MMA(0, 1, At, B1); PG8_BAR; PG8_SCHED;
;             PG8_LDA(At, 0, 1); PG8_STAGE(PG8_SB(0, 0), b2, voffB); PG8_STAGE(PG8_SB(0, 1), b2 + hstep, voffB); PG8_STAGE(PG8_SA(0, 0), a2, voffA);
;             PG8_WAIT_V(8); PG8_WAIT_L(0); PG8_BAR; PG8_MMA(1, 0, At, B0); PG8_MMA(1, 1, At, B1); PG8_BAR; PG8_SCHED;
.LBB0_1062:
	ds_read_b128 v[146:149], v155
	ds_read_b128 v[158:161], v155 offset:1024
	ds_read_b128 v[168:171], v155 offset:2048
	ds_read_b128 v[172:175], v155 offset:3072
	ds_read_b128 v[176:179], v156
	ds_read_b128 v[180:183], v156 offset:1024
	ds_read_b128 v[184:187], v156 offset:2048
	ds_read_b128 v[188:191], v156 offset:3072
	s_add_u32 s72, s70, 0xfff80080
	s_addc_u32 s73, s71, -1
	s_cmp_eq_u32 s77, 28
	s_cselect_b32 s75, s34, s73
	s_cselect_b32 s74, s35, s72
	s_cselect_b32 s73, s61, s76
	s_cselect_b32 s72, s63, s69
	v_lshl_add_u64 v[150:151], s[70:71], 0, v[138:139]
	s_add_i32 m0, s25, 0xc000
	ds_read_b128 v[200:203], v157
	ds_read_b128 v[204:207], v157 offset:1024
	ds_read_b128 v[208:211], v157 offset:2048
	ds_read_b128 v[212:215], v157 offset:3072
	ds_read_b128 v[216:219], v157 offset:4096
	ds_read_b128 v[220:223], v157 offset:5120
	ds_read_b128 v[224:227], v157 offset:6144
	ds_read_b128 v[228:231], v157 offset:7168
	global_load_lds_dwordx4 v[150:151], off
	v_lshl_add_u64 v[150:151], s[70:71], 0, v[140:141]
	s_add_i32 m0, s25, 0xe000
	s_nop 0
	global_load_lds_dwordx4 v[150:151], off
	s_waitcnt vmcnt(8)
	s_waitcnt lgkmcnt(0)
	s_setprio 1
	s_barrier
	v_mfma_f32_16x16x32_bf16 v[126:129], v[146:149], v[200:203], v[126:129]
	v_mfma_f32_16x16x32_bf16 v[122:125], v[168:171], v[200:203], v[122:125]
	v_mfma_f32_16x16x32_bf16 v[110:113], v[146:149], v[208:211], v[110:113]
	v_mfma_f32_16x16x32_bf16 v[106:109], v[168:171], v[208:211], v[106:109]
	v_mfma_f32_16x16x32_bf16 v[94:97], v[146:149], v[216:219], v[94:97]
	v_mfma_f32_16x16x32_bf16 v[90:93], v[168:171], v[216:219], v[90:93]
	v_mfma_f32_16x16x32_bf16 v[78:81], v[146:149], v[224:227], v[78:81]
	v_mfma_f32_16x16x32_bf16 v[74:77], v[168:171], v[224:227], v[74:77]
	v_mfma_f32_16x16x32_bf16 v[126:129], v[158:161], v[204:207], v[126:129]
	v_mfma_f32_16x16x32_bf16 v[122:125], v[172:175], v[204:207], v[122:125]
	v_mfma_f32_16x16x32_bf16 v[110:113], v[158:161], v[212:215], v[110:113]
	v_mfma_f32_16x16x32_bf16 v[106:109], v[172:175], v[212:215], v[106:109]
	v_mfma_f32_16x16x32_bf16 v[94:97], v[158:161], v[220:223], v[94:97]
	v_mfma_f32_16x16x32_bf16 v[90:93], v[172:175], v[220:223], v[90:93]
	v_mfma_f32_16x16x32_bf16 v[78:81], v[158:161], v[228:231], v[78:81]
	v_mfma_f32_16x16x32_bf16 v[74:77], v[172:175], v[228:231], v[74:77]
	s_setprio 0
	s_setprio 1
	v_mfma_f32_16x16x32_bf16 v[118:121], v[176:179], v[200:203], v[118:121]
	v_mfma_f32_16x16x32_bf16 v[114:117], v[184:187], v[200:203], v[114:117]
	v_mfma_f32_16x16x32_bf16 v[102:105], v[176:179], v[208:211], v[102:105]
	v_mfma_f32_16x16x32_bf16 v[98:101], v[184:187], v[208:211], v[98:101]
	v_mfma_f32_16x16x32_bf16 v[86:89], v[176:179], v[216:219], v[86:89]
	v_mfma_f32_16x16x32_bf16 v[82:85], v[184:187], v[216:219], v[82:85]
	v_mfma_f32_16x16x32_bf16 v[70:73], v[176:179], v[224:227], v[70:73]
	v_mfma_f32_16x16x32_bf16 v[66:69], v[184:187], v[224:227], v[66:69]
	v_mfma_f32_16x16x32_bf16 v[118:121], v[180:183], v[204:207], v[118:121]
	v_mfma_f32_16x16x32_bf16 v[114:117], v[188:191], v[204:207], v[114:117]
	v_mfma_f32_16x16x32_bf16 v[102:105], v[180:183], v[212:215], v[102:105]
	v_mfma_f32_16x16x32_bf16 v[98:101], v[188:191], v[212:215], v[98:101]
	v_mfma_f32_16x16x32_bf16 v[86:89], v[180:183], v[220:223], v[86:89]
	v_mfma_f32_16x16x32_bf16 v[82:85], v[188:191], v[220:223], v[82:85]
	v_mfma_f32_16x16x32_bf16 v[70:73], v[180:183], v[228:231], v[70:73]
	v_mfma_f32_16x16x32_bf16 v[66:69], v[188:191], v[228:231], v[66:69]
	s_barrier
	s_setprio 0
	s_add_i32 s78, s31, s2
	v_lshl_add_u64 v[150:151], s[72:73], 0, v[134:135]
	s_mov_b32 m0, s78
	ds_read_b128 v[200:203], v157 offset:16384
	ds_read_b128 v[204:207], v157 offset:17408
	ds_read_b128 v[208:211], v157 offset:18432
	ds_read_b128 v[212:215], v157 offset:19456
	ds_read_b128 v[216:219], v157 offset:20480
	ds_read_b128 v[220:223], v157 offset:21504
	ds_read_b128 v[224:227], v157 offset:22528
	ds_read_b128 v[228:231], v157 offset:23552
	global_load_lds_dwordx4 v[150:151], off
	s_add_i32 m0, s78, 0x2000
	s_add_u32 s78, s72, 0x80000
	v_lshl_add_u64 v[162:163], s[72:73], 0, v[130:131]
	s_addc_u32 s79, s73, 0
	s_add_i32 s80, s40, s2
	global_load_lds_dwordx4 v[162:163], off
	v_lshl_add_u64 v[192:193], s[78:79], 0, v[134:135]
	s_mov_b32 m0, s80
	v_lshl_add_u64 v[232:233], s[74:75], 0, v[132:133]
	global_load_lds_dwordx4 v[192:193], off
	v_lshl_add_u64 v[192:193], s[78:79], 0, v[130:131]
	s_add_i32 m0, s80, 0x2000
	s_nop 0
	global_load_lds_dwordx4 v[192:193], off
	v_lshl_add_u64 v[192:193], s[74:75], 0, v[136:137]
	s_mov_b32 m0, s25
	s_nop 0
	global_load_lds_dwordx4 v[192:193], off
	s_mov_b32 m0, s26
	s_nop 0
	global_load_lds_dwordx4 v[232:233], off
	s_waitcnt vmcnt(8)
	s_waitcnt lgkmcnt(0)
	s_setprio 1
	s_barrier
; #define PG8_STAGE(bufoff, gbase, voff) do { _Pragma("unroll") for (int _i = 0; _i < 2; ++_i) \
;         __builtin_amdgcn_global_load_lds((const unsigned*)((const char*)(gbase) + (voff)[_i]), (PG8_LAS unsigned*)(lds + (bufoff) + ldsw + _i * 8192), 16, 0, 0); } while (0)
; #define PG8_LDA(dst, b, h) do { _Pragma("unroll") for (int m = 0; m < 4; ++m) _Pragma("unroll") for (int k = 0; k < 2; ++k) dst[m][k] = *(const PG8_LAS bf16x8*)(lds + PG8_SA(b, h) + aoff + m * 2048 + k * 1024); } while (0)
; #define PG8_LDB(dst, b, h) do { _Pragma("unroll") for (int n = 0; n < 2; ++n) _Pragma("unroll") for (int k = 0; k < 2; ++k) dst[n][k] = *(const PG8_LAS bf16x8*)(lds + PG8_SB(b, h) + boff + n * 2048 + k * 1024); } while (0)
; #define PG8_MMA(ai, bj, At, Bt) do { __builtin_amdgcn_s_setprio(1); _Pragma("unroll") for (int m = 0; m < 4; ++m) _Pragma("unroll") for (int n = 0; n < 2; ++n) _Pragma("unroll") for (int k = 0; k < 2; ++k) \
;         acc[ai][bj][m][n] = __builtin_amdgcn_mfma_f32_16x16x32_bf16(Bt[n][k], At[m][k], acc[ai][bj][m][n], 0, 0, 0); __builtin_amdgcn_s_setprio(0); } while (0)
; #define PG8_WAIT_V(n) asm volatile("s_waitcnt vmcnt(" #n ")" ::: "memory")
; #define PG8_WAIT_L(n) asm volatile("s_waitcnt lgkmcnt(" #n ")" ::: "memory")
; #define PG8_BAR __builtin_amdgcn_s_barrier()
; #define PG8_SCHED __builtin_amdgcn_sched_barrier(0)
; template <class Epi, class Sched, bool ALIGN_EPI = false, bool SP2 = false>
; __device__ __forceinline__ void gemm_phase(PG8_LAS unsigned char* lds, const Gemm g, const Sched& S, const Epi& E) {
;     ...
;             PG8_WAIT_V(8); PG8_WAIT_L(0); PG8_BAR; PG8_MMA(1, 0, At, B0); PG8_MMA(1, 1, At, B1); PG8_BAR; PG8_SCHED;
;             PG8_LDB(B0, 1, 0); PG8_LDB(B1, 1, 1); PG8_SCHED; PG8_LDA(At, 1, 0); PG8_STAGE(PG8_SA(0, 1), a2 + hstep, voffA);
;             PG8_WAIT_V(8); PG8_WAIT_L(0); PG8_BAR; PG8_MMA(0, 0, At, B0); PG8_MMA(0, 1, At, B1); PG8_BAR; PG8_SCHED;
	v_mfma_f32_16x16x32_bf16 v[62:65], v[146:149], v[200:203], v[62:65]
	v_mfma_f32_16x16x32_bf16 v[58:61], v[168:171], v[200:203], v[58:61]
	v_mfma_f32_16x16x32_bf16 v[46:49], v[146:149], v[208:211], v[46:49]
	v_mfma_f32_16x16x32_bf16 v[42:45], v[168:171], v[208:211], v[42:45]
	v_mfma_f32_16x16x32_bf16 v[30:33], v[146:149], v[216:219], v[30:33]
	v_mfma_f32_16x16x32_bf16 v[26:29], v[168:171], v[216:219], v[26:29]
	v_mfma_f32_16x16x32_bf16 v[14:17], v[146:149], v[224:227], v[14:17]
	v_mfma_f32_16x16x32_bf16 v[10:13], v[168:171], v[224:227], v[10:13]
	v_mfma_f32_16x16x32_bf16 v[62:65], v[158:161], v[204:207], v[62:65]
	v_mfma_f32_16x16x32_bf16 v[58:61], v[172:175], v[204:207], v[58:61]
	v_mfma_f32_16x16x32_bf16 v[46:49], v[158:161], v[212:215], v[46:49]
	v_mfma_f32_16x16x32_bf16 v[42:45], v[172:175], v[212:215], v[42:45]
	v_mfma_f32_16x16x32_bf16 v[30:33], v[158:161], v[220:223], v[30:33]
	v_mfma_f32_16x16x32_bf16 v[26:29], v[172:175], v[220:223], v[26:29]
	v_mfma_f32_16x16x32_bf16 v[14:17], v[158:161], v[228:231], v[14:17]
	v_mfma_f32_16x16x32_bf16 v[10:13], v[172:175], v[228:231], v[10:13]
	s_setprio 0
	s_setprio 1
	v_mfma_f32_16x16x32_bf16 v[54:57], v[176:179], v[200:203], v[54:57]
	v_mfma_f32_16x16x32_bf16 v[50:53], v[184:187], v[200:203], v[50:53]
	v_mfma_f32_16x16x32_bf16 v[38:41], v[176:179], v[208:211], v[38:41]
	v_mfma_f32_16x16x32_bf16 v[34:37], v[184:187], v[208:211], v[34:37]
	v_mfma_f32_16x16x32_bf16 v[22:25], v[176:179], v[216:219], v[22:25]
	v_mfma_f32_16x16x32_bf16 v[18:21], v[184:187], v[216:219], v[18:21]
	v_mfma_f32_16x16x32_bf16 v[6:9], v[176:179], v[224:227], v[6:9]
	v_mfma_f32_16x16x32_bf16 v[2:5], v[184:187], v[224:227], v[2:5]
	v_mfma_f32_16x16x32_bf16 v[54:57], v[180:183], v[204:207], v[54:57]
	v_mfma_f32_16x16x32_bf16 v[50:53], v[188:191], v[204:207], v[50:53]
	v_mfma_f32_16x16x32_bf16 v[38:41], v[180:183], v[212:215], v[38:41]
	v_mfma_f32_16x16x32_bf16 v[34:37], v[188:191], v[212:215], v[34:37]
	v_mfma_f32_16x16x32_bf16 v[22:25], v[180:183], v[220:223], v[22:25]
	v_mfma_f32_16x16x32_bf16 v[18:21], v[188:191], v[220:223], v[18:21]
	v_mfma_f32_16x16x32_bf16 v[6:9], v[180:183], v[228:231], v[6:9]
	v_mfma_f32_16x16x32_bf16 v[2:5], v[188:191], v[228:231], v[2:5]
	s_barrier
	s_setprio 0
	s_add_i32 s78, 0, 0x18000
	v_add_u32_e32 v166, s78, v153
	s_add_i32 s79, 0, 0x1c000
	ds_read_b128 v[146:149], v166
	ds_read_b128 v[158:161], v166 offset:1024
	ds_read_b128 v[168:171], v166 offset:2048
	ds_read_b128 v[172:175], v166 offset:3072
	v_add_u32_e32 v166, s79, v153
	ds_read_b128 v[176:179], v166
	ds_read_b128 v[180:183], v166 offset:1024
	ds_read_b128 v[184:187], v166 offset:2048
	ds_read_b128 v[188:191], v166 offset:3072
	s_add_u32 s74, s74, 0x80000
	s_addc_u32 s75, s75, 0
	s_mov_b32 m0, s27
	v_lshl_add_u64 v[240:241], s[74:75], 0, v[136:137]
	ds_read_b128 v[200:203], v157 offset:32768
	ds_read_b128 v[204:207], v157 offset:33792
	ds_read_b128 v[208:211], v157 offset:34816
	ds_read_b128 v[212:215], v157 offset:35840
	ds_read_b128 v[216:219], v157 offset:36864
	ds_read_b128 v[220:223], v157 offset:37888
	ds_read_b128 v[224:227], v157 offset:38912
	ds_read_b128 v[228:231], v157 offset:39936
	global_load_lds_dwordx4 v[240:241], off
	v_lshl_add_u64 v[240:241], s[74:75], 0, v[132:133]
	s_mov_b32 m0, s28
	s_nop 0
	global_load_lds_dwordx4 v[240:241], off
	s_waitcnt vmcnt(8)
	s_waitcnt lgkmcnt(0)
	s_setprio 1
	s_barrier
	v_mfma_f32_16x16x32_bf16 v[126:129], v[146:149], v[200:203], v[126:129]
	v_mfma_f32_16x16x32_bf16 v[122:125], v[168:171], v[200:203], v[122:125]
	v_mfma_f32_16x16x32_bf16 v[110:113], v[146:149], v[208:211], v[110:113]
	v_mfma_f32_16x16x32_bf16 v[106:109], v[168:171], v[208:211], v[106:109]
	v_mfma_f32_16x16x32_bf16 v[94:97], v[146:149], v[216:219], v[94:97]
	v_mfma_f32_16x16x32_bf16 v[90:93], v[168:171], v[216:219], v[90:93]
	v_mfma_f32_16x16x32_bf16 v[78:81], v[146:149], v[224:227], v[78:81]
	v_mfma_f32_16x16x32_bf16 v[74:77], v[168:171], v[224:227], v[74:77]
	v_mfma_f32_16x16x32_bf16 v[126:129], v[158:161], v[204:207], v[126:129]
	v_mfma_f32_16x16x32_bf16 v[122:125], v[172:175], v[204:207], v[122:125]
	v_mfma_f32_16x16x32_bf16 v[110:113], v[158:161], v[212:215], v[110:113]
	v_mfma_f32_16x16x32_bf16 v[106:109], v[172:175], v[212:215], v[106:109]
	v_mfma_f32_16x16x32_bf16 v[94:97], v[158:161], v[220:223], v[94:97]
	v_mfma_f32_16x16x32_bf16 v[90:93], v[172:175], v[220:223], v[90:93]
	v_mfma_f32_16x16x32_bf16 v[78:81], v[158:161], v[228:231], v[78:81]
	v_mfma_f32_16x16x32_bf16 v[74:77], v[172:175], v[228:231], v[74:77]
	s_setprio 0
	s_setprio 1
	v_mfma_f32_16x16x32_bf16 v[118:121], v[176:179], v[200:203], v[118:121]
	v_mfma_f32_16x16x32_bf16 v[114:117], v[184:187], v[200:203], v[114:117]
	v_mfma_f32_16x16x32_bf16 v[102:105], v[176:179], v[208:211], v[102:105]
	v_mfma_f32_16x16x32_bf16 v[98:101], v[184:187], v[208:211], v[98:101]
	v_mfma_f32_16x16x32_bf16 v[86:89], v[176:179], v[216:219], v[86:89]
	v_mfma_f32_16x16x32_bf16 v[82:85], v[184:187], v[216:219], v[82:85]
	v_mfma_f32_16x16x32_bf16 v[70:73], v[176:179], v[224:227], v[70:73]
	v_mfma_f32_16x16x32_bf16 v[66:69], v[184:187], v[224:227], v[66:69]
	v_mfma_f32_16x16x32_bf16 v[118:121], v[180:183], v[204:207], v[118:121]
	v_mfma_f32_16x16x32_bf16 v[114:117], v[188:191], v[204:207], v[114:117]
	v_mfma_f32_16x16x32_bf16 v[102:105], v[180:183], v[212:215], v[102:105]
	v_mfma_f32_16x16x32_bf16 v[98:101], v[188:191], v[212:215], v[98:101]
	v_mfma_f32_16x16x32_bf16 v[86:89], v[180:183], v[220:223], v[86:89]
	v_mfma_f32_16x16x32_bf16 v[82:85], v[188:191], v[220:223], v[82:85]
	v_mfma_f32_16x16x32_bf16 v[70:73], v[180:183], v[228:231], v[70:73]
	v_mfma_f32_16x16x32_bf16 v[66:69], v[188:191], v[228:231], v[66:69]
	s_barrier
; #define PG8_STAGE(bufoff, gbase, voff) do { _Pragma("unroll") for (int _i = 0; _i < 2; ++_i) \
;         __builtin_amdgcn_global_load_lds((const unsigned*)((const char*)(gbase) + (voff)[_i]), (PG8_LAS unsigned*)(lds + (bufoff) + ldsw + _i * 8192), 16, 0, 0); } while (0)
; #define PG8_LDA(dst, b, h) do { _Pragma("unroll") for (int m = 0; m < 4; ++m) _Pragma("unroll") for (int k = 0; k < 2; ++k) dst[m][k] = *(const PG8_LAS bf16x8*)(lds + PG8_SA(b, h) + aoff + m * 2048 + k * 1024); } while (0)
; #define PG8_MMA(ai, bj, At, Bt) do { __builtin_amdgcn_s_setprio(1); _Pragma("unroll") for (int m = 0; m < 4; ++m) _Pragma("unroll") for (int n = 0; n < 2; ++n) _Pragma("unroll") for (int k = 0; k < 2; ++k) \
;         acc[ai][bj][m][n] = __builtin_amdgcn_mfma_f32_16x16x32_bf16(Bt[n][k], At[m][k], acc[ai][bj][m][n], 0, 0, 0); __builtin_amdgcn_s_setprio(0); } while (0)
; #define PG8_WAIT_V(n) asm volatile("s_waitcnt vmcnt(" #n ")" ::: "memory")
; #define PG8_WAIT_L(n) asm volatile("s_waitcnt lgkmcnt(" #n ")" ::: "memory")
; #define PG8_BAR __builtin_amdgcn_s_barrier()
; #define PG8_SCHED __builtin_amdgcn_sched_barrier(0)
; template <class Epi, class Sched, bool ALIGN_EPI = false, bool SP2 = false>
; __device__ __forceinline__ void gemm_phase(PG8_LAS unsigned char* lds, const Gemm g, const Sched& S, const Epi& E) {
;     ...
;         for (int t = 0; t < nt; t += 2) {
;     ...
;             PG8_WAIT_V(8); PG8_WAIT_L(0); PG8_BAR; PG8_MMA(0, 0, At, B0); PG8_MMA(0, 1, At, B1); PG8_BAR; PG8_SCHED;
;             PG8_LDA(At, 1, 1); PG8_STAGE(PG8_SB(1, 0), b3, voffB); PG8_STAGE(PG8_SB(1, 1), b3 + hstep, voffB); PG8_STAGE(PG8_SA(1, 0), a3, voffA);
;             PG8_WAIT_V(8); PG8_WAIT_L(0); PG8_BAR; PG8_MMA(1, 0, At, B0); PG8_MMA(1, 1, At, B1); PG8_BAR; PG8_SCHED;
	s_setprio 0
	s_add_i32 s74, s78, s2
	v_lshl_add_u64 v[150:151], v[150:151], 0, s[10:11]
	s_mov_b32 m0, s74
	ds_read_b128 v[200:203], v157 offset:49152
	ds_read_b128 v[204:207], v157 offset:50176
	ds_read_b128 v[208:211], v157 offset:51200
	ds_read_b128 v[212:215], v157 offset:52224
	ds_read_b128 v[216:219], v157 offset:53248
	ds_read_b128 v[220:223], v157 offset:54272
	ds_read_b128 v[224:227], v157 offset:55296
	ds_read_b128 v[228:231], v157 offset:56320
	global_load_lds_dwordx4 v[150:151], off
	s_add_i32 m0, s74, 0x2000
	s_add_u32 s72, s72, 0x80080
	v_lshl_add_u64 v[150:151], v[162:163], 0, s[10:11]
	s_addc_u32 s73, s73, 0
	s_add_i32 s74, s79, s2
	global_load_lds_dwordx4 v[150:151], off
	v_lshl_add_u64 v[150:151], s[72:73], 0, v[134:135]
	s_mov_b32 m0, s74
	s_nop 0
	global_load_lds_dwordx4 v[150:151], off
	v_lshl_add_u64 v[150:151], s[72:73], 0, v[130:131]
	s_add_i32 m0, s74, 0x2000
	s_nop 0
	global_load_lds_dwordx4 v[150:151], off
	v_lshl_add_u64 v[150:151], v[192:193], 0, s[10:11]
	s_mov_b32 m0, s30
	s_nop 0
	global_load_lds_dwordx4 v[150:151], off
	v_lshl_add_u64 v[150:151], v[232:233], 0, s[10:11]
	s_mov_b32 m0, s33
	s_nop 0
	global_load_lds_dwordx4 v[150:151], off
	s_waitcnt vmcnt(8)
	s_waitcnt lgkmcnt(0)
	s_setprio 1
	s_barrier
	v_mfma_f32_16x16x32_bf16 v[62:65], v[146:149], v[200:203], v[62:65]
	v_mfma_f32_16x16x32_bf16 v[58:61], v[168:171], v[200:203], v[58:61]
	v_mfma_f32_16x16x32_bf16 v[46:49], v[146:149], v[208:211], v[46:49]
	v_mfma_f32_16x16x32_bf16 v[42:45], v[168:171], v[208:211], v[42:45]
	v_mfma_f32_16x16x32_bf16 v[30:33], v[146:149], v[216:219], v[30:33]
	v_mfma_f32_16x16x32_bf16 v[26:29], v[168:171], v[216:219], v[26:29]
	v_mfma_f32_16x16x32_bf16 v[14:17], v[146:149], v[224:227], v[14:17]
	v_mfma_f32_16x16x32_bf16 v[10:13], v[168:171], v[224:227], v[10:13]
	v_mfma_f32_16x16x32_bf16 v[62:65], v[158:161], v[204:207], v[62:65]
	v_mfma_f32_16x16x32_bf16 v[58:61], v[172:175], v[204:207], v[58:61]
	v_mfma_f32_16x16x32_bf16 v[46:49], v[158:161], v[212:215], v[46:49]
	v_mfma_f32_16x16x32_bf16 v[42:45], v[172:175], v[212:215], v[42:45]
	v_mfma_f32_16x16x32_bf16 v[30:33], v[158:161], v[220:223], v[30:33]
	v_mfma_f32_16x16x32_bf16 v[26:29], v[172:175], v[220:223], v[26:29]
	v_mfma_f32_16x16x32_bf16 v[14:17], v[158:161], v[228:231], v[14:17]
	v_mfma_f32_16x16x32_bf16 v[10:13], v[172:175], v[228:231], v[10:13]
	s_setprio 0
	s_setprio 1
	v_mfma_f32_16x16x32_bf16 v[54:57], v[176:179], v[200:203], v[54:57]
	v_mfma_f32_16x16x32_bf16 v[50:53], v[184:187], v[200:203], v[50:53]
	v_mfma_f32_16x16x32_bf16 v[38:41], v[176:179], v[208:211], v[38:41]
	v_mfma_f32_16x16x32_bf16 v[34:37], v[184:187], v[208:211], v[34:37]
	v_mfma_f32_16x16x32_bf16 v[22:25], v[176:179], v[216:219], v[22:25]
	v_mfma_f32_16x16x32_bf16 v[18:21], v[184:187], v[216:219], v[18:21]
	v_mfma_f32_16x16x32_bf16 v[6:9], v[176:179], v[224:227], v[6:9]
	v_mfma_f32_16x16x32_bf16 v[2:5], v[184:187], v[224:227], v[2:5]
	v_mfma_f32_16x16x32_bf16 v[54:57], v[180:183], v[204:207], v[54:57]
	v_mfma_f32_16x16x32_bf16 v[50:53], v[188:191], v[204:207], v[50:53]
	v_mfma_f32_16x16x32_bf16 v[38:41], v[180:183], v[212:215], v[38:41]
	v_mfma_f32_16x16x32_bf16 v[34:37], v[188:191], v[212:215], v[34:37]
	v_mfma_f32_16x16x32_bf16 v[22:25], v[180:183], v[220:223], v[22:25]
	v_mfma_f32_16x16x32_bf16 v[18:21], v[188:191], v[220:223], v[18:21]
	v_mfma_f32_16x16x32_bf16 v[6:9], v[180:183], v[228:231], v[6:9]
	v_mfma_f32_16x16x32_bf16 v[2:5], v[188:191], v[228:231], v[2:5]
	s_barrier
	s_setprio 0
	s_add_i32 s77, s77, 2
	s_add_u32 s70, s70, 0x100
	s_addc_u32 s71, s71, 0
	s_add_u32 s69, s69, 0x100
	s_addc_u32 s76, s76, 0
	s_cmp_gt_u32 s77, 29
	s_cbranch_scc0 .LBB0_1062
	s_and_b64 vcc, exec, s[48:49]
	s_cbranch_vccz .LBB0_1065
	s_barrier

; #define PG8_STAGE(bufoff, gbase, voff) do { _Pragma("unroll") for (int _i = 0; _i < 2; ++_i) \
;         __builtin_amdgcn_global_load_lds((const unsigned*)((const char*)(gbase) + (voff)[_i]), (PG8_LAS unsigned*)(lds + (bufoff) + ldsw + _i * 8192), 16, 0, 0); } while (0)
; #define PG8_LDA(dst, b, h) do { _Pragma("unroll") for (int m = 0; m < 4; ++m) _Pragma("unroll") for (int k = 0; k < 2; ++k) dst[m][k] = *(const PG8_LAS bf16x8*)(lds + PG8_SA(b, h) + aoff + m * 2048 + k * 1024); } while (0)
; #define PG8_LDB(dst, b, h) do { _Pragma("unroll") for (int n = 0; n < 2; ++n) _Pragma("unroll") for (int k = 0; k < 2; ++k) dst[n][k] = *(const PG8_LAS bf16x8*)(lds + PG8_SB(b, h) + boff + n * 2048 + k * 1024); } while (0)
; #define PG8_MMA(ai, bj, At, Bt) do { __builtin_amdgcn_s_setprio(1); _Pragma("unroll") for (int m = 0; m < 4; ++m) _Pragma("unroll") for (int n = 0; n < 2; ++n) _Pragma("unroll") for (int k = 0; k < 2; ++k) \
;         acc[ai][bj][m][n] = __builtin_amdgcn_mfma_f32_16x16x32_bf16(Bt[n][k], At[m][k], acc[ai][bj][m][n], 0, 0, 0); __builtin_amdgcn_s_setprio(0); } while (0)
; #define PG8_WAIT_V(n) asm volatile("s_waitcnt vmcnt(" #n ")" ::: "memory")
; #define PG8_WAIT_L(n) asm volatile("s_waitcnt lgkmcnt(" #n ")" ::: "memory")
; #define PG8_BAR __builtin_amdgcn_s_barrier()
; #define PG8_SCHED __builtin_amdgcn_sched_barrier(0)
; template <class Epi, class Sched, bool ALIGN_EPI = false, bool SP2 = false>
; __device__ __forceinline__ void gemm_phase(PG8_LAS unsigned char* lds, const Gemm g, const Sched& S, const Epi& E) {
;     ...
;             PG8_LDB(B0, 0, 0); PG8_LDB(B1, 0, 1); PG8_SCHED; PG8_LDA(At, 0, 0); PG8_STAGE(PG8_SA(1, 1), a1 + hstep, voffA);
;             PG8_WAIT_V(8); PG8_WAIT_L(0); PG8_BAR; PG8_MMA(0, 0, At, B0); PG8_MMA(0, 1, At, B1); PG8_BAR; PG8_SCHED;
;             PG8_LDA(At, 0, 1); PG8_STAGE(PG8_SB(0, 0), b2, voffB); PG8_STAGE(PG8_SB(0, 1), b2 + hstep, voffB); PG8_STAGE(PG8_SA(0, 0), a2, voffA);
;             PG8_WAIT_V(8); PG8_WAIT_L(0); PG8_BAR; PG8_MMA(1, 0, At, B0); PG8_MMA(1, 1, At, B1); PG8_BAR; PG8_SCHED;
.LBB0_1078:
	ds_read_b128 v[146:149], v155
	ds_read_b128 v[158:161], v155 offset:1024
	ds_read_b128 v[168:171], v155 offset:2048
	ds_read_b128 v[172:175], v155 offset:3072
	ds_read_b128 v[176:179], v156
	ds_read_b128 v[180:183], v156 offset:1024
	ds_read_b128 v[184:187], v156 offset:2048
	ds_read_b128 v[188:191], v156 offset:3072
	s_add_u32 s68, s66, 0xfff80080
	s_addc_u32 s69, s67, -1
	s_cmp_eq_u32 s73, 28
	s_cselect_b32 s71, s34, s69
	s_cselect_b32 s70, s35, s68
	s_cselect_b32 s69, s57, s72
	s_cselect_b32 s68, s59, s65
	v_lshl_add_u64 v[150:151], s[66:67], 0, v[138:139]
	s_add_i32 m0, s25, 0xc000
	ds_read_b128 v[200:203], v157
	ds_read_b128 v[204:207], v157 offset:1024
	ds_read_b128 v[208:211], v157 offset:2048
	ds_read_b128 v[212:215], v157 offset:3072
	ds_read_b128 v[216:219], v157 offset:4096
	ds_read_b128 v[220:223], v157 offset:5120
	ds_read_b128 v[224:227], v157 offset:6144
	ds_read_b128 v[228:231], v157 offset:7168
	global_load_lds_dwordx4 v[150:151], off
	v_lshl_add_u64 v[150:151], s[66:67], 0, v[140:141]
	s_add_i32 m0, s25, 0xe000
	s_nop 0
	global_load_lds_dwordx4 v[150:151], off
	s_waitcnt vmcnt(8)
	s_waitcnt lgkmcnt(0)
	s_setprio 1
	s_barrier
	v_mfma_f32_16x16x32_bf16 v[126:129], v[146:149], v[200:203], v[126:129]
	v_mfma_f32_16x16x32_bf16 v[122:125], v[168:171], v[200:203], v[122:125]
	v_mfma_f32_16x16x32_bf16 v[110:113], v[146:149], v[208:211], v[110:113]
	v_mfma_f32_16x16x32_bf16 v[106:109], v[168:171], v[208:211], v[106:109]
	v_mfma_f32_16x16x32_bf16 v[94:97], v[146:149], v[216:219], v[94:97]
	v_mfma_f32_16x16x32_bf16 v[90:93], v[168:171], v[216:219], v[90:93]
	v_mfma_f32_16x16x32_bf16 v[78:81], v[146:149], v[224:227], v[78:81]
	v_mfma_f32_16x16x32_bf16 v[74:77], v[168:171], v[224:227], v[74:77]
	v_mfma_f32_16x16x32_bf16 v[126:129], v[158:161], v[204:207], v[126:129]
	v_mfma_f32_16x16x32_bf16 v[122:125], v[172:175], v[204:207], v[122:125]
	v_mfma_f32_16x16x32_bf16 v[110:113], v[158:161], v[212:215], v[110:113]
	v_mfma_f32_16x16x32_bf16 v[106:109], v[172:175], v[212:215], v[106:109]
	v_mfma_f32_16x16x32_bf16 v[94:97], v[158:161], v[220:223], v[94:97]
	v_mfma_f32_16x16x32_bf16 v[90:93], v[172:175], v[220:223], v[90:93]
	v_mfma_f32_16x16x32_bf16 v[78:81], v[158:161], v[228:231], v[78:81]
	v_mfma_f32_16x16x32_bf16 v[74:77], v[172:175], v[228:231], v[74:77]
	s_setprio 0
	s_setprio 1
	v_mfma_f32_16x16x32_bf16 v[118:121], v[176:179], v[200:203], v[118:121]
	v_mfma_f32_16x16x32_bf16 v[114:117], v[184:187], v[200:203], v[114:117]
	v_mfma_f32_16x16x32_bf16 v[102:105], v[176:179], v[208:211], v[102:105]
	v_mfma_f32_16x16x32_bf16 v[98:101], v[184:187], v[208:211], v[98:101]
	v_mfma_f32_16x16x32_bf16 v[86:89], v[176:179], v[216:219], v[86:89]
	v_mfma_f32_16x16x32_bf16 v[82:85], v[184:187], v[216:219], v[82:85]
	v_mfma_f32_16x16x32_bf16 v[70:73], v[176:179], v[224:227], v[70:73]
	v_mfma_f32_16x16x32_bf16 v[66:69], v[184:187], v[224:227], v[66:69]
	v_mfma_f32_16x16x32_bf16 v[118:121], v[180:183], v[204:207], v[118:121]
	v_mfma_f32_16x16x32_bf16 v[114:117], v[188:191], v[204:207], v[114:117]
	v_mfma_f32_16x16x32_bf16 v[102:105], v[180:183], v[212:215], v[102:105]
	v_mfma_f32_16x16x32_bf16 v[98:101], v[188:191], v[212:215], v[98:101]
	v_mfma_f32_16x16x32_bf16 v[86:89], v[180:183], v[220:223], v[86:89]
	v_mfma_f32_16x16x32_bf16 v[82:85], v[188:191], v[220:223], v[82:85]
	v_mfma_f32_16x16x32_bf16 v[70:73], v[180:183], v[228:231], v[70:73]
	v_mfma_f32_16x16x32_bf16 v[66:69], v[188:191], v[228:231], v[66:69]
	s_barrier
	s_setprio 0
	s_add_i32 s74, s31, s2
	v_lshl_add_u64 v[150:151], s[68:69], 0, v[134:135]
	s_mov_b32 m0, s74
	ds_read_b128 v[200:203], v157 offset:16384
	ds_read_b128 v[204:207], v157 offset:17408
	ds_read_b128 v[208:211], v157 offset:18432
	ds_read_b128 v[212:215], v157 offset:19456
	ds_read_b128 v[216:219], v157 offset:20480
	ds_read_b128 v[220:223], v157 offset:21504
	ds_read_b128 v[224:227], v157 offset:22528
	ds_read_b128 v[228:231], v157 offset:23552
	global_load_lds_dwordx4 v[150:151], off
	s_add_i32 m0, s74, 0x2000
	s_add_u32 s74, s68, 0x80000
	v_lshl_add_u64 v[162:163], s[68:69], 0, v[130:131]
	s_addc_u32 s75, s69, 0
	s_add_i32 s76, s40, s2
	global_load_lds_dwordx4 v[162:163], off
	v_lshl_add_u64 v[192:193], s[74:75], 0, v[134:135]
	s_mov_b32 m0, s76
	v_lshl_add_u64 v[232:233], s[70:71], 0, v[132:133]
	global_load_lds_dwordx4 v[192:193], off
	v_lshl_add_u64 v[192:193], s[74:75], 0, v[130:131]
	s_add_i32 m0, s76, 0x2000
	s_nop 0
	global_load_lds_dwordx4 v[192:193], off
	v_lshl_add_u64 v[192:193], s[70:71], 0, v[136:137]
	s_mov_b32 m0, s25
	s_nop 0
	global_load_lds_dwordx4 v[192:193], off
	s_mov_b32 m0, s26
	s_nop 0
	global_load_lds_dwordx4 v[232:233], off
	s_waitcnt vmcnt(8)
	s_waitcnt lgkmcnt(0)
	s_setprio 1
	s_barrier
; #define PG8_STAGE(bufoff, gbase, voff) do { _Pragma("unroll") for (int _i = 0; _i < 2; ++_i) \
;         __builtin_amdgcn_global_load_lds((const unsigned*)((const char*)(gbase) + (voff)[_i]), (PG8_LAS unsigned*)(lds + (bufoff) + ldsw + _i * 8192), 16, 0, 0); } while (0)
; #define PG8_LDA(dst, b, h) do { _Pragma("unroll") for (int m = 0; m < 4; ++m) _Pragma("unroll") for (int k = 0; k < 2; ++k) dst[m][k] = *(const PG8_LAS bf16x8*)(lds + PG8_SA(b, h) + aoff + m * 2048 + k * 1024); } while (0)
; #define PG8_LDB(dst, b, h) do { _Pragma("unroll") for (int n = 0; n < 2; ++n) _Pragma("unroll") for (int k = 0; k < 2; ++k) dst[n][k] = *(const PG8_LAS bf16x8*)(lds + PG8_SB(b, h) + boff + n * 2048 + k * 1024); } while (0)
; #define PG8_MMA(ai, bj, At, Bt) do { __builtin_amdgcn_s_setprio(1); _Pragma("unroll") for (int m = 0; m < 4; ++m) _Pragma("unroll") for (int n = 0; n < 2; ++n) _Pragma("unroll") for (int k = 0; k < 2; ++k) \
;         acc[ai][bj][m][n] = __builtin_amdgcn_mfma_f32_16x16x32_bf16(Bt[n][k], At[m][k], acc[ai][bj][m][n], 0, 0, 0); __builtin_amdgcn_s_setprio(0); } while (0)
; #define PG8_WAIT_V(n) asm volatile("s_waitcnt vmcnt(" #n ")" ::: "memory")
; #define PG8_WAIT_L(n) asm volatile("s_waitcnt lgkmcnt(" #n ")" ::: "memory")
; #define PG8_BAR __builtin_amdgcn_s_barrier()
; #define PG8_SCHED __builtin_amdgcn_sched_barrier(0)
; template <class Epi, class Sched, bool ALIGN_EPI = false, bool SP2 = false>
; __device__ __forceinline__ void gemm_phase(PG8_LAS unsigned char* lds, const Gemm g, const Sched& S, const Epi& E) {
;     ...
;             PG8_WAIT_V(8); PG8_WAIT_L(0); PG8_BAR; PG8_MMA(1, 0, At, B0); PG8_MMA(1, 1, At, B1); PG8_BAR; PG8_SCHED;
;             PG8_LDB(B0, 1, 0); PG8_LDB(B1, 1, 1); PG8_SCHED; PG8_LDA(At, 1, 0); PG8_STAGE(PG8_SA(0, 1), a2 + hstep, voffA);
;             PG8_WAIT_V(8); PG8_WAIT_L(0); PG8_BAR; PG8_MMA(0, 0, At, B0); PG8_MMA(0, 1, At, B1); PG8_BAR; PG8_SCHED;
	v_mfma_f32_16x16x32_bf16 v[62:65], v[146:149], v[200:203], v[62:65]
	v_mfma_f32_16x16x32_bf16 v[58:61], v[168:171], v[200:203], v[58:61]
	v_mfma_f32_16x16x32_bf16 v[46:49], v[146:149], v[208:211], v[46:49]
	v_mfma_f32_16x16x32_bf16 v[42:45], v[168:171], v[208:211], v[42:45]
	v_mfma_f32_16x16x32_bf16 v[30:33], v[146:149], v[216:219], v[30:33]
	v_mfma_f32_16x16x32_bf16 v[26:29], v[168:171], v[216:219], v[26:29]
	v_mfma_f32_16x16x32_bf16 v[14:17], v[146:149], v[224:227], v[14:17]
	v_mfma_f32_16x16x32_bf16 v[10:13], v[168:171], v[224:227], v[10:13]
	v_mfma_f32_16x16x32_bf16 v[62:65], v[158:161], v[204:207], v[62:65]
	v_mfma_f32_16x16x32_bf16 v[58:61], v[172:175], v[204:207], v[58:61]
	v_mfma_f32_16x16x32_bf16 v[46:49], v[158:161], v[212:215], v[46:49]
	v_mfma_f32_16x16x32_bf16 v[42:45], v[172:175], v[212:215], v[42:45]
	v_mfma_f32_16x16x32_bf16 v[30:33], v[158:161], v[220:223], v[30:33]
	v_mfma_f32_16x16x32_bf16 v[26:29], v[172:175], v[220:223], v[26:29]
	v_mfma_f32_16x16x32_bf16 v[14:17], v[158:161], v[228:231], v[14:17]
	v_mfma_f32_16x16x32_bf16 v[10:13], v[172:175], v[228:231], v[10:13]
	s_setprio 0
	s_setprio 1
	v_mfma_f32_16x16x32_bf16 v[54:57], v[176:179], v[200:203], v[54:57]
	v_mfma_f32_16x16x32_bf16 v[50:53], v[184:187], v[200:203], v[50:53]
	v_mfma_f32_16x16x32_bf16 v[38:41], v[176:179], v[208:211], v[38:41]
	v_mfma_f32_16x16x32_bf16 v[34:37], v[184:187], v[208:211], v[34:37]
	v_mfma_f32_16x16x32_bf16 v[22:25], v[176:179], v[216:219], v[22:25]
	v_mfma_f32_16x16x32_bf16 v[18:21], v[184:187], v[216:219], v[18:21]
	v_mfma_f32_16x16x32_bf16 v[6:9], v[176:179], v[224:227], v[6:9]
	v_mfma_f32_16x16x32_bf16 v[2:5], v[184:187], v[224:227], v[2:5]
	v_mfma_f32_16x16x32_bf16 v[54:57], v[180:183], v[204:207], v[54:57]
	v_mfma_f32_16x16x32_bf16 v[50:53], v[188:191], v[204:207], v[50:53]
	v_mfma_f32_16x16x32_bf16 v[38:41], v[180:183], v[212:215], v[38:41]
	v_mfma_f32_16x16x32_bf16 v[34:37], v[188:191], v[212:215], v[34:37]
	v_mfma_f32_16x16x32_bf16 v[22:25], v[180:183], v[220:223], v[22:25]
	v_mfma_f32_16x16x32_bf16 v[18:21], v[188:191], v[220:223], v[18:21]
	v_mfma_f32_16x16x32_bf16 v[6:9], v[180:183], v[228:231], v[6:9]
	v_mfma_f32_16x16x32_bf16 v[2:5], v[188:191], v[228:231], v[2:5]
	s_barrier
	s_setprio 0
	s_add_i32 s74, 0, 0x18000
	v_add_u32_e32 v166, s74, v153
	s_add_i32 s75, 0, 0x1c000
	ds_read_b128 v[146:149], v166
	ds_read_b128 v[158:161], v166 offset:1024
	ds_read_b128 v[168:171], v166 offset:2048
	ds_read_b128 v[172:175], v166 offset:3072
	v_add_u32_e32 v166, s75, v153
	ds_read_b128 v[176:179], v166
	ds_read_b128 v[180:183], v166 offset:1024
	ds_read_b128 v[184:187], v166 offset:2048
	ds_read_b128 v[188:191], v166 offset:3072
	s_add_u32 s70, s70, 0x80000
	s_addc_u32 s71, s71, 0
	s_mov_b32 m0, s27
	v_lshl_add_u64 v[240:241], s[70:71], 0, v[136:137]
	ds_read_b128 v[200:203], v157 offset:32768
	ds_read_b128 v[204:207], v157 offset:33792
	ds_read_b128 v[208:211], v157 offset:34816
	ds_read_b128 v[212:215], v157 offset:35840
	ds_read_b128 v[216:219], v157 offset:36864
	ds_read_b128 v[220:223], v157 offset:37888
	ds_read_b128 v[224:227], v157 offset:38912
	ds_read_b128 v[228:231], v157 offset:39936
	global_load_lds_dwordx4 v[240:241], off
	v_lshl_add_u64 v[240:241], s[70:71], 0, v[132:133]
	s_mov_b32 m0, s28
	s_nop 0
	global_load_lds_dwordx4 v[240:241], off
	s_waitcnt vmcnt(8)
	s_waitcnt lgkmcnt(0)
	s_setprio 1
	s_barrier
	v_mfma_f32_16x16x32_bf16 v[126:129], v[146:149], v[200:203], v[126:129]
	v_mfma_f32_16x16x32_bf16 v[122:125], v[168:171], v[200:203], v[122:125]
	v_mfma_f32_16x16x32_bf16 v[110:113], v[146:149], v[208:211], v[110:113]
	v_mfma_f32_16x16x32_bf16 v[106:109], v[168:171], v[208:211], v[106:109]
	v_mfma_f32_16x16x32_bf16 v[94:97], v[146:149], v[216:219], v[94:97]
	v_mfma_f32_16x16x32_bf16 v[90:93], v[168:171], v[216:219], v[90:93]
	v_mfma_f32_16x16x32_bf16 v[78:81], v[146:149], v[224:227], v[78:81]
	v_mfma_f32_16x16x32_bf16 v[74:77], v[168:171], v[224:227], v[74:77]
	v_mfma_f32_16x16x32_bf16 v[126:129], v[158:161], v[204:207], v[126:129]
	v_mfma_f32_16x16x32_bf16 v[122:125], v[172:175], v[204:207], v[122:125]
	v_mfma_f32_16x16x32_bf16 v[110:113], v[158:161], v[212:215], v[110:113]
	v_mfma_f32_16x16x32_bf16 v[106:109], v[172:175], v[212:215], v[106:109]
	v_mfma_f32_16x16x32_bf16 v[94:97], v[158:161], v[220:223], v[94:97]
	v_mfma_f32_16x16x32_bf16 v[90:93], v[172:175], v[220:223], v[90:93]
	v_mfma_f32_16x16x32_bf16 v[78:81], v[158:161], v[228:231], v[78:81]
	v_mfma_f32_16x16x32_bf16 v[74:77], v[172:175], v[228:231], v[74:77]
	s_setprio 0
	s_setprio 1
	v_mfma_f32_16x16x32_bf16 v[118:121], v[176:179], v[200:203], v[118:121]
	v_mfma_f32_16x16x32_bf16 v[114:117], v[184:187], v[200:203], v[114:117]
	v_mfma_f32_16x16x32_bf16 v[102:105], v[176:179], v[208:211], v[102:105]
	v_mfma_f32_16x16x32_bf16 v[98:101], v[184:187], v[208:211], v[98:101]
	v_mfma_f32_16x16x32_bf16 v[86:89], v[176:179], v[216:219], v[86:89]
	v_mfma_f32_16x16x32_bf16 v[82:85], v[184:187], v[216:219], v[82:85]
	v_mfma_f32_16x16x32_bf16 v[70:73], v[176:179], v[224:227], v[70:73]
	v_mfma_f32_16x16x32_bf16 v[66:69], v[184:187], v[224:227], v[66:69]
	v_mfma_f32_16x16x32_bf16 v[118:121], v[180:183], v[204:207], v[118:121]
	v_mfma_f32_16x16x32_bf16 v[114:117], v[188:191], v[204:207], v[114:117]
	v_mfma_f32_16x16x32_bf16 v[102:105], v[180:183], v[212:215], v[102:105]
	v_mfma_f32_16x16x32_bf16 v[98:101], v[188:191], v[212:215], v[98:101]
	v_mfma_f32_16x16x32_bf16 v[86:89], v[180:183], v[220:223], v[86:89]
	v_mfma_f32_16x16x32_bf16 v[82:85], v[188:191], v[220:223], v[82:85]
	v_mfma_f32_16x16x32_bf16 v[70:73], v[180:183], v[228:231], v[70:73]
	v_mfma_f32_16x16x32_bf16 v[66:69], v[188:191], v[228:231], v[66:69]
	s_barrier
; #define PG8_STAGE(bufoff, gbase, voff) do { _Pragma("unroll") for (int _i = 0; _i < 2; ++_i) \
;         __builtin_amdgcn_global_load_lds((const unsigned*)((const char*)(gbase) + (voff)[_i]), (PG8_LAS unsigned*)(lds + (bufoff) + ldsw + _i * 8192), 16, 0, 0); } while (0)
; #define PG8_LDA(dst, b, h) do { _Pragma("unroll") for (int m = 0; m < 4; ++m) _Pragma("unroll") for (int k = 0; k < 2; ++k) dst[m][k] = *(const PG8_LAS bf16x8*)(lds + PG8_SA(b, h) + aoff + m * 2048 + k * 1024); } while (0)
; #define PG8_MMA(ai, bj, At, Bt) do { __builtin_amdgcn_s_setprio(1); _Pragma("unroll") for (int m = 0; m < 4; ++m) _Pragma("unroll") for (int n = 0; n < 2; ++n) _Pragma("unroll") for (int k = 0; k < 2; ++k) \
;         acc[ai][bj][m][n] = __builtin_amdgcn_mfma_f32_16x16x32_bf16(Bt[n][k], At[m][k], acc[ai][bj][m][n], 0, 0, 0); __builtin_amdgcn_s_setprio(0); } while (0)
; #define PG8_WAIT_V(n) asm volatile("s_waitcnt vmcnt(" #n ")" ::: "memory")
; #define PG8_WAIT_L(n) asm volatile("s_waitcnt lgkmcnt(" #n ")" ::: "memory")
; #define PG8_BAR __builtin_amdgcn_s_barrier()
; #define PG8_SCHED __builtin_amdgcn_sched_barrier(0)
; template <class Epi, class Sched, bool ALIGN_EPI = false, bool SP2 = false>
; __device__ __forceinline__ void gemm_phase(PG8_LAS unsigned char* lds, const Gemm g, const Sched& S, const Epi& E) {
;     ...
;         for (int t = 0; t < nt; t += 2) {
;     ...
;             PG8_WAIT_V(8); PG8_WAIT_L(0); PG8_BAR; PG8_MMA(0, 0, At, B0); PG8_MMA(0, 1, At, B1); PG8_BAR; PG8_SCHED;
;             PG8_LDA(At, 1, 1); PG8_STAGE(PG8_SB(1, 0), b3, voffB); PG8_STAGE(PG8_SB(1, 1), b3 + hstep, voffB); PG8_STAGE(PG8_SA(1, 0), a3, voffA);
;             PG8_WAIT_V(8); PG8_WAIT_L(0); PG8_BAR; PG8_MMA(1, 0, At, B0); PG8_MMA(1, 1, At, B1); PG8_BAR; PG8_SCHED;
	s_setprio 0
	s_add_i32 s70, s74, s2
	v_lshl_add_u64 v[150:151], v[150:151], 0, s[8:9]
	s_mov_b32 m0, s70
	ds_read_b128 v[200:203], v157 offset:49152
	ds_read_b128 v[204:207], v157 offset:50176
	ds_read_b128 v[208:211], v157 offset:51200
	ds_read_b128 v[212:215], v157 offset:52224
	ds_read_b128 v[216:219], v157 offset:53248
	ds_read_b128 v[220:223], v157 offset:54272
	ds_read_b128 v[224:227], v157 offset:55296
	ds_read_b128 v[228:231], v157 offset:56320
	global_load_lds_dwordx4 v[150:151], off
	s_add_i32 m0, s70, 0x2000
	s_add_u32 s68, s68, 0x80080
	v_lshl_add_u64 v[150:151], v[162:163], 0, s[8:9]
	s_addc_u32 s69, s69, 0
	s_add_i32 s70, s75, s2
	global_load_lds_dwordx4 v[150:151], off
	v_lshl_add_u64 v[150:151], s[68:69], 0, v[134:135]
	s_mov_b32 m0, s70
	s_nop 0
	global_load_lds_dwordx4 v[150:151], off
	v_lshl_add_u64 v[150:151], s[68:69], 0, v[130:131]
	s_add_i32 m0, s70, 0x2000
	s_nop 0
	global_load_lds_dwordx4 v[150:151], off
	v_lshl_add_u64 v[150:151], v[192:193], 0, s[8:9]
	s_mov_b32 m0, s30
	s_nop 0
	global_load_lds_dwordx4 v[150:151], off
	v_lshl_add_u64 v[150:151], v[232:233], 0, s[8:9]
	s_mov_b32 m0, s33
	s_nop 0
	global_load_lds_dwordx4 v[150:151], off
	s_waitcnt vmcnt(8)
	s_waitcnt lgkmcnt(0)
	s_setprio 1
	s_barrier
	v_mfma_f32_16x16x32_bf16 v[62:65], v[146:149], v[200:203], v[62:65]
	v_mfma_f32_16x16x32_bf16 v[58:61], v[168:171], v[200:203], v[58:61]
	v_mfma_f32_16x16x32_bf16 v[46:49], v[146:149], v[208:211], v[46:49]
	v_mfma_f32_16x16x32_bf16 v[42:45], v[168:171], v[208:211], v[42:45]
	v_mfma_f32_16x16x32_bf16 v[30:33], v[146:149], v[216:219], v[30:33]
	v_mfma_f32_16x16x32_bf16 v[26:29], v[168:171], v[216:219], v[26:29]
	v_mfma_f32_16x16x32_bf16 v[14:17], v[146:149], v[224:227], v[14:17]
	v_mfma_f32_16x16x32_bf16 v[10:13], v[168:171], v[224:227], v[10:13]
	v_mfma_f32_16x16x32_bf16 v[62:65], v[158:161], v[204:207], v[62:65]
	v_mfma_f32_16x16x32_bf16 v[58:61], v[172:175], v[204:207], v[58:61]
	v_mfma_f32_16x16x32_bf16 v[46:49], v[158:161], v[212:215], v[46:49]
	v_mfma_f32_16x16x32_bf16 v[42:45], v[172:175], v[212:215], v[42:45]
	v_mfma_f32_16x16x32_bf16 v[30:33], v[158:161], v[220:223], v[30:33]
	v_mfma_f32_16x16x32_bf16 v[26:29], v[172:175], v[220:223], v[26:29]
	v_mfma_f32_16x16x32_bf16 v[14:17], v[158:161], v[228:231], v[14:17]
	v_mfma_f32_16x16x32_bf16 v[10:13], v[172:175], v[228:231], v[10:13]
	s_setprio 0
	s_setprio 1
	v_mfma_f32_16x16x32_bf16 v[54:57], v[176:179], v[200:203], v[54:57]
	v_mfma_f32_16x16x32_bf16 v[50:53], v[184:187], v[200:203], v[50:53]
	v_mfma_f32_16x16x32_bf16 v[38:41], v[176:179], v[208:211], v[38:41]
	v_mfma_f32_16x16x32_bf16 v[34:37], v[184:187], v[208:211], v[34:37]
	v_mfma_f32_16x16x32_bf16 v[22:25], v[176:179], v[216:219], v[22:25]
	v_mfma_f32_16x16x32_bf16 v[18:21], v[184:187], v[216:219], v[18:21]
	v_mfma_f32_16x16x32_bf16 v[6:9], v[176:179], v[224:227], v[6:9]
	v_mfma_f32_16x16x32_bf16 v[2:5], v[184:187], v[224:227], v[2:5]
	v_mfma_f32_16x16x32_bf16 v[54:57], v[180:183], v[204:207], v[54:57]
	v_mfma_f32_16x16x32_bf16 v[50:53], v[188:191], v[204:207], v[50:53]
	v_mfma_f32_16x16x32_bf16 v[38:41], v[180:183], v[212:215], v[38:41]
	v_mfma_f32_16x16x32_bf16 v[34:37], v[188:191], v[212:215], v[34:37]
	v_mfma_f32_16x16x32_bf16 v[22:25], v[180:183], v[220:223], v[22:25]
	v_mfma_f32_16x16x32_bf16 v[18:21], v[188:191], v[220:223], v[18:21]
	v_mfma_f32_16x16x32_bf16 v[6:9], v[180:183], v[228:231], v[6:9]
	v_mfma_f32_16x16x32_bf16 v[2:5], v[188:191], v[228:231], v[2:5]
	s_barrier
	s_setprio 0
	s_add_i32 s73, s73, 2
	s_add_u32 s66, s66, 0x100
	s_addc_u32 s67, s67, 0
	s_add_u32 s65, s65, 0x100
	s_addc_u32 s72, s72, 0
	s_cmp_gt_u32 s73, 29
	s_cbranch_scc0 .LBB0_1078
	s_and_b64 vcc, exec, s[10:11]
	s_cbranch_vccz .LBB0_1081
	s_barrier

; #define PG8_STAGE(bufoff, gbase, voff) do { _Pragma("unroll") for (int _i = 0; _i < 2; ++_i) \
;         __builtin_amdgcn_global_load_lds((const unsigned*)((const char*)(gbase) + (voff)[_i]), (PG8_LAS unsigned*)(lds + (bufoff) + ldsw + _i * 8192), 16, 0, 0); } while (0)
; #define PG8_LDA(dst, b, h) do { _Pragma("unroll") for (int m = 0; m < 4; ++m) _Pragma("unroll") for (int k = 0; k < 2; ++k) dst[m][k] = *(const PG8_LAS bf16x8*)(lds + PG8_SA(b, h) + aoff + m * 2048 + k * 1024); } while (0)
; #define PG8_LDB(dst, b, h) do { _Pragma("unroll") for (int n = 0; n < 2; ++n) _Pragma("unroll") for (int k = 0; k < 2; ++k) dst[n][k] = *(const PG8_LAS bf16x8*)(lds + PG8_SB(b, h) + boff + n * 2048 + k * 1024); } while (0)
; #define PG8_MMA(ai, bj, At, Bt) do { __builtin_amdgcn_s_setprio(1); _Pragma("unroll") for (int m = 0; m < 4; ++m) _Pragma("unroll") for (int n = 0; n < 2; ++n) _Pragma("unroll") for (int k = 0; k < 2; ++k) \
;         acc[ai][bj][m][n] = __builtin_amdgcn_mfma_f32_16x16x32_bf16(Bt[n][k], At[m][k], acc[ai][bj][m][n], 0, 0, 0); __builtin_amdgcn_s_setprio(0); } while (0)
; #define PG8_WAIT_V(n) asm volatile("s_waitcnt vmcnt(" #n ")" ::: "memory")
; #define PG8_WAIT_L(n) asm volatile("s_waitcnt lgkmcnt(" #n ")" ::: "memory")
; #define PG8_BAR __builtin_amdgcn_s_barrier()
; #define PG8_SCHED __builtin_amdgcn_sched_barrier(0)
; template <class Epi, class Sched, bool ALIGN_EPI = false, bool SP2 = false>
; __device__ __forceinline__ void gemm_phase(PG8_LAS unsigned char* lds, const Gemm g, const Sched& S, const Epi& E) {
;     ...
;             PG8_LDB(B0, 0, 0); PG8_LDB(B1, 0, 1); PG8_SCHED; PG8_LDA(At, 0, 0); PG8_STAGE(PG8_SA(1, 1), a1 + hstep, voffA);
;             PG8_WAIT_V(8); PG8_WAIT_L(0); PG8_BAR; PG8_MMA(0, 0, At, B0); PG8_MMA(0, 1, At, B1); PG8_BAR; PG8_SCHED;
;             PG8_LDA(At, 0, 1); PG8_STAGE(PG8_SB(0, 0), b2, voffB); PG8_STAGE(PG8_SB(0, 1), b2 + hstep, voffB); PG8_STAGE(PG8_SA(0, 0), a2, voffA);
;             PG8_WAIT_V(8); PG8_WAIT_L(0); PG8_BAR; PG8_MMA(1, 0, At, B0); PG8_MMA(1, 1, At, B1); PG8_BAR; PG8_SCHED;
.LBB0_1203:
	ds_read_b128 v[146:149], v171
	ds_read_b128 v[176:179], v171 offset:1024
	ds_read_b128 v[180:183], v171 offset:2048
	ds_read_b128 v[184:187], v171 offset:3072
	ds_read_b128 v[188:191], v172
	ds_read_b128 v[200:203], v172 offset:1024
	ds_read_b128 v[204:207], v172 offset:2048
	ds_read_b128 v[208:211], v172 offset:3072
	s_add_u32 s63, s64, 0xfff00080
	s_addc_u32 s66, s65, -1
	s_cmp_eq_u32 s61, 60
	s_cselect_b32 s69, s34, s66
	s_cselect_b32 s68, s35, s63
	s_cselect_b32 s67, s40, s55
	s_cselect_b32 s66, s41, s53
	v_lshl_add_u64 v[150:151], s[64:65], 0, v[138:139]
	s_add_i32 m0, s4, 0xc000
	ds_read_b128 v[212:215], v173
	ds_read_b128 v[216:219], v173 offset:1024
	ds_read_b128 v[220:223], v173 offset:2048
	ds_read_b128 v[224:227], v173 offset:3072
	ds_read_b128 v[228:231], v173 offset:4096
	ds_read_b128 v[240:243], v173 offset:5120
	ds_read_b128 v[244:247], v173 offset:6144
	ds_read_b128 v[248:251], v173 offset:7168
	global_load_lds_dwordx4 v[150:151], off
	v_lshl_add_u64 v[150:151], s[64:65], 0, v[140:141]
	s_add_i32 m0, s4, 0xe000
	s_nop 0
	global_load_lds_dwordx4 v[150:151], off
	s_waitcnt vmcnt(8)
	s_waitcnt lgkmcnt(0)
	s_setprio 1
	s_barrier
	v_mfma_f32_16x16x32_bf16 v[126:129], v[146:149], v[212:215], v[126:129]
	v_mfma_f32_16x16x32_bf16 v[122:125], v[180:183], v[212:215], v[122:125]
	v_mfma_f32_16x16x32_bf16 v[110:113], v[146:149], v[220:223], v[110:113]
	v_mfma_f32_16x16x32_bf16 v[106:109], v[180:183], v[220:223], v[106:109]
	v_mfma_f32_16x16x32_bf16 v[94:97], v[146:149], v[228:231], v[94:97]
	v_mfma_f32_16x16x32_bf16 v[90:93], v[180:183], v[228:231], v[90:93]
	v_mfma_f32_16x16x32_bf16 v[78:81], v[146:149], v[244:247], v[78:81]
	v_mfma_f32_16x16x32_bf16 v[74:77], v[180:183], v[244:247], v[74:77]
	v_mfma_f32_16x16x32_bf16 v[126:129], v[176:179], v[216:219], v[126:129]
	v_mfma_f32_16x16x32_bf16 v[122:125], v[184:187], v[216:219], v[122:125]
	v_mfma_f32_16x16x32_bf16 v[110:113], v[176:179], v[224:227], v[110:113]
	v_mfma_f32_16x16x32_bf16 v[106:109], v[184:187], v[224:227], v[106:109]
	v_mfma_f32_16x16x32_bf16 v[94:97], v[176:179], v[240:243], v[94:97]
	v_mfma_f32_16x16x32_bf16 v[90:93], v[184:187], v[240:243], v[90:93]
	v_mfma_f32_16x16x32_bf16 v[78:81], v[176:179], v[248:251], v[78:81]
	v_mfma_f32_16x16x32_bf16 v[74:77], v[184:187], v[248:251], v[74:77]
	s_setprio 0
	s_setprio 1
	v_mfma_f32_16x16x32_bf16 v[118:121], v[188:191], v[212:215], v[118:121]
	v_mfma_f32_16x16x32_bf16 v[114:117], v[204:207], v[212:215], v[114:117]
	v_mfma_f32_16x16x32_bf16 v[102:105], v[188:191], v[220:223], v[102:105]
	v_mfma_f32_16x16x32_bf16 v[98:101], v[204:207], v[220:223], v[98:101]
	v_mfma_f32_16x16x32_bf16 v[86:89], v[188:191], v[228:231], v[86:89]
	v_mfma_f32_16x16x32_bf16 v[82:85], v[204:207], v[228:231], v[82:85]
	v_mfma_f32_16x16x32_bf16 v[70:73], v[188:191], v[244:247], v[70:73]
	v_mfma_f32_16x16x32_bf16 v[66:69], v[204:207], v[244:247], v[66:69]
	v_mfma_f32_16x16x32_bf16 v[118:121], v[200:203], v[216:219], v[118:121]
	v_mfma_f32_16x16x32_bf16 v[114:117], v[208:211], v[216:219], v[114:117]
	v_mfma_f32_16x16x32_bf16 v[102:105], v[200:203], v[224:227], v[102:105]
	v_mfma_f32_16x16x32_bf16 v[98:101], v[208:211], v[224:227], v[98:101]
	v_mfma_f32_16x16x32_bf16 v[86:89], v[200:203], v[240:243], v[86:89]
	v_mfma_f32_16x16x32_bf16 v[82:85], v[208:211], v[240:243], v[82:85]
	v_mfma_f32_16x16x32_bf16 v[70:73], v[200:203], v[248:251], v[70:73]
	v_mfma_f32_16x16x32_bf16 v[66:69], v[208:211], v[248:251], v[66:69]
	s_barrier
	s_setprio 0
	s_add_i32 s63, s31, s2
	v_lshl_add_u64 v[150:151], s[66:67], 0, v[132:133]
	s_mov_b32 m0, s63
	ds_read_b128 v[212:215], v173 offset:16384
	ds_read_b128 v[216:219], v173 offset:17408
	ds_read_b128 v[220:223], v173 offset:18432
	ds_read_b128 v[224:227], v173 offset:19456
	ds_read_b128 v[228:231], v173 offset:20480
	ds_read_b128 v[240:243], v173 offset:21504
	ds_read_b128 v[244:247], v173 offset:22528
	ds_read_b128 v[248:251], v173 offset:23552
	global_load_lds_dwordx4 v[150:151], off
	s_add_i32 m0, s63, 0x2000
	s_add_u32 s70, s66, 0x100000
	v_lshl_add_u64 v[192:193], s[66:67], 0, v[136:137]
	s_addc_u32 s71, s67, 0
	s_add_i32 s63, s39, s2
	global_load_lds_dwordx4 v[192:193], off
	v_lshl_add_u64 v[232:233], s[70:71], 0, v[132:133]
	s_mov_b32 m0, s63
	v_lshl_add_u64 v[252:253], s[68:69], 0, v[134:135]
	global_load_lds_dwordx4 v[232:233], off
	v_lshl_add_u64 v[232:233], s[70:71], 0, v[136:137]
	s_add_i32 m0, s63, 0x2000
	s_nop 0
	global_load_lds_dwordx4 v[232:233], off
	v_lshl_add_u64 v[232:233], s[68:69], 0, v[130:131]
	s_mov_b32 m0, s4
	s_nop 0
	global_load_lds_dwordx4 v[232:233], off
	s_mov_b32 m0, s5
	s_nop 0
	global_load_lds_dwordx4 v[252:253], off
	s_waitcnt vmcnt(8)
	s_waitcnt lgkmcnt(0)
	s_setprio 1
	s_barrier
; #define PG8_STAGE(bufoff, gbase, voff) do { _Pragma("unroll") for (int _i = 0; _i < 2; ++_i) \
;         __builtin_amdgcn_global_load_lds((const unsigned*)((const char*)(gbase) + (voff)[_i]), (PG8_LAS unsigned*)(lds + (bufoff) + ldsw + _i * 8192), 16, 0, 0); } while (0)
; #define PG8_LDA(dst, b, h) do { _Pragma("unroll") for (int m = 0; m < 4; ++m) _Pragma("unroll") for (int k = 0; k < 2; ++k) dst[m][k] = *(const PG8_LAS bf16x8*)(lds + PG8_SA(b, h) + aoff + m * 2048 + k * 1024); } while (0)
; #define PG8_LDB(dst, b, h) do { _Pragma("unroll") for (int n = 0; n < 2; ++n) _Pragma("unroll") for (int k = 0; k < 2; ++k) dst[n][k] = *(const PG8_LAS bf16x8*)(lds + PG8_SB(b, h) + boff + n * 2048 + k * 1024); } while (0)
; #define PG8_MMA(ai, bj, At, Bt) do { __builtin_amdgcn_s_setprio(1); _Pragma("unroll") for (int m = 0; m < 4; ++m) _Pragma("unroll") for (int n = 0; n < 2; ++n) _Pragma("unroll") for (int k = 0; k < 2; ++k) \
;         acc[ai][bj][m][n] = __builtin_amdgcn_mfma_f32_16x16x32_bf16(Bt[n][k], At[m][k], acc[ai][bj][m][n], 0, 0, 0); __builtin_amdgcn_s_setprio(0); } while (0)
; #define PG8_WAIT_V(n) asm volatile("s_waitcnt vmcnt(" #n ")" ::: "memory")
; #define PG8_WAIT_L(n) asm volatile("s_waitcnt lgkmcnt(" #n ")" ::: "memory")
; #define PG8_BAR __builtin_amdgcn_s_barrier()
; #define PG8_SCHED __builtin_amdgcn_sched_barrier(0)
; template <class Epi, class Sched, bool ALIGN_EPI = false, bool SP2 = false>
; __device__ __forceinline__ void gemm_phase(PG8_LAS unsigned char* lds, const Gemm g, const Sched& S, const Epi& E) {
;     ...
;             PG8_WAIT_V(8); PG8_WAIT_L(0); PG8_BAR; PG8_MMA(1, 0, At, B0); PG8_MMA(1, 1, At, B1); PG8_BAR; PG8_SCHED;
;             PG8_LDB(B0, 1, 0); PG8_LDB(B1, 1, 1); PG8_SCHED; PG8_LDA(At, 1, 0); PG8_STAGE(PG8_SA(0, 1), a2 + hstep, voffA);
;             PG8_WAIT_V(8); PG8_WAIT_L(0); PG8_BAR; PG8_MMA(0, 0, At, B0); PG8_MMA(0, 1, At, B1); PG8_BAR; PG8_SCHED;
	v_mfma_f32_16x16x32_bf16 v[62:65], v[146:149], v[212:215], v[62:65]
	v_mfma_f32_16x16x32_bf16 v[58:61], v[180:183], v[212:215], v[58:61]
	v_mfma_f32_16x16x32_bf16 v[46:49], v[146:149], v[220:223], v[46:49]
	v_mfma_f32_16x16x32_bf16 v[42:45], v[180:183], v[220:223], v[42:45]
	v_mfma_f32_16x16x32_bf16 v[30:33], v[146:149], v[228:231], v[30:33]
	v_mfma_f32_16x16x32_bf16 v[26:29], v[180:183], v[228:231], v[26:29]
	v_mfma_f32_16x16x32_bf16 v[14:17], v[146:149], v[244:247], v[14:17]
	v_mfma_f32_16x16x32_bf16 v[10:13], v[180:183], v[244:247], v[10:13]
	v_mfma_f32_16x16x32_bf16 v[62:65], v[176:179], v[216:219], v[62:65]
	v_mfma_f32_16x16x32_bf16 v[58:61], v[184:187], v[216:219], v[58:61]
	v_mfma_f32_16x16x32_bf16 v[46:49], v[176:179], v[224:227], v[46:49]
	v_mfma_f32_16x16x32_bf16 v[42:45], v[184:187], v[224:227], v[42:45]
	v_mfma_f32_16x16x32_bf16 v[30:33], v[176:179], v[240:243], v[30:33]
	v_mfma_f32_16x16x32_bf16 v[26:29], v[184:187], v[240:243], v[26:29]
	v_mfma_f32_16x16x32_bf16 v[14:17], v[176:179], v[248:251], v[14:17]
	v_mfma_f32_16x16x32_bf16 v[10:13], v[184:187], v[248:251], v[10:13]
	s_setprio 0
	s_setprio 1
	v_mfma_f32_16x16x32_bf16 v[54:57], v[188:191], v[212:215], v[54:57]
	v_mfma_f32_16x16x32_bf16 v[50:53], v[204:207], v[212:215], v[50:53]
	v_mfma_f32_16x16x32_bf16 v[38:41], v[188:191], v[220:223], v[38:41]
	v_mfma_f32_16x16x32_bf16 v[34:37], v[204:207], v[220:223], v[34:37]
	v_mfma_f32_16x16x32_bf16 v[22:25], v[188:191], v[228:231], v[22:25]
	v_mfma_f32_16x16x32_bf16 v[18:21], v[204:207], v[228:231], v[18:21]
	v_mfma_f32_16x16x32_bf16 v[6:9], v[188:191], v[244:247], v[6:9]
	v_mfma_f32_16x16x32_bf16 v[2:5], v[204:207], v[244:247], v[2:5]
	v_mfma_f32_16x16x32_bf16 v[54:57], v[200:203], v[216:219], v[54:57]
	v_mfma_f32_16x16x32_bf16 v[50:53], v[208:211], v[216:219], v[50:53]
	v_mfma_f32_16x16x32_bf16 v[38:41], v[200:203], v[224:227], v[38:41]
	v_mfma_f32_16x16x32_bf16 v[34:37], v[208:211], v[224:227], v[34:37]
	v_mfma_f32_16x16x32_bf16 v[22:25], v[200:203], v[240:243], v[22:25]
	v_mfma_f32_16x16x32_bf16 v[18:21], v[208:211], v[240:243], v[18:21]
	v_mfma_f32_16x16x32_bf16 v[6:9], v[200:203], v[248:251], v[6:9]
	v_mfma_f32_16x16x32_bf16 v[2:5], v[208:211], v[248:251], v[2:5]
	s_barrier
	s_setprio 0
	s_add_i32 s63, 0, 0x18000
	v_add_u32_e32 v175, s63, v153
	s_add_i32 s70, 0, 0x1c000
	ds_read_b128 v[146:149], v175
	ds_read_b128 v[176:179], v175 offset:1024
	ds_read_b128 v[180:183], v175 offset:2048
	ds_read_b128 v[184:187], v175 offset:3072
	v_add_u32_e32 v175, s70, v153
	ds_read_b128 v[188:191], v175
	ds_read_b128 v[200:203], v175 offset:1024
	ds_read_b128 v[204:207], v175 offset:2048
	ds_read_b128 v[208:211], v175 offset:3072
	s_add_u32 s68, s68, 0x100000
	s_addc_u32 s69, s69, 0
	s_mov_b32 m0, s16
	v_lshl_add_u64 v[194:195], s[68:69], 0, v[130:131]
	ds_read_b128 v[212:215], v173 offset:32768
	ds_read_b128 v[216:219], v173 offset:33792
	ds_read_b128 v[220:223], v173 offset:34816
	ds_read_b128 v[224:227], v173 offset:35840
	ds_read_b128 v[228:231], v173 offset:36864
	ds_read_b128 v[240:243], v173 offset:37888
	ds_read_b128 v[244:247], v173 offset:38912
	ds_read_b128 v[248:251], v173 offset:39936
	global_load_lds_dwordx4 v[194:195], off
	v_lshl_add_u64 v[194:195], s[68:69], 0, v[134:135]
	s_mov_b32 m0, s17
	s_nop 0
	global_load_lds_dwordx4 v[194:195], off
	s_waitcnt vmcnt(8)
	s_waitcnt lgkmcnt(0)
	s_setprio 1
	s_barrier
	v_mfma_f32_16x16x32_bf16 v[126:129], v[146:149], v[212:215], v[126:129]
	v_mfma_f32_16x16x32_bf16 v[122:125], v[180:183], v[212:215], v[122:125]
	v_mfma_f32_16x16x32_bf16 v[110:113], v[146:149], v[220:223], v[110:113]
	v_mfma_f32_16x16x32_bf16 v[106:109], v[180:183], v[220:223], v[106:109]
	v_mfma_f32_16x16x32_bf16 v[94:97], v[146:149], v[228:231], v[94:97]
	v_mfma_f32_16x16x32_bf16 v[90:93], v[180:183], v[228:231], v[90:93]
	v_mfma_f32_16x16x32_bf16 v[78:81], v[146:149], v[244:247], v[78:81]
	v_mfma_f32_16x16x32_bf16 v[74:77], v[180:183], v[244:247], v[74:77]
	v_mfma_f32_16x16x32_bf16 v[126:129], v[176:179], v[216:219], v[126:129]
	v_mfma_f32_16x16x32_bf16 v[122:125], v[184:187], v[216:219], v[122:125]
	v_mfma_f32_16x16x32_bf16 v[110:113], v[176:179], v[224:227], v[110:113]
	v_mfma_f32_16x16x32_bf16 v[106:109], v[184:187], v[224:227], v[106:109]
	v_mfma_f32_16x16x32_bf16 v[94:97], v[176:179], v[240:243], v[94:97]
	v_mfma_f32_16x16x32_bf16 v[90:93], v[184:187], v[240:243], v[90:93]
	v_mfma_f32_16x16x32_bf16 v[78:81], v[176:179], v[248:251], v[78:81]
	v_mfma_f32_16x16x32_bf16 v[74:77], v[184:187], v[248:251], v[74:77]
	s_setprio 0
	s_setprio 1
	v_mfma_f32_16x16x32_bf16 v[118:121], v[188:191], v[212:215], v[118:121]
	v_mfma_f32_16x16x32_bf16 v[114:117], v[204:207], v[212:215], v[114:117]
	v_mfma_f32_16x16x32_bf16 v[102:105], v[188:191], v[220:223], v[102:105]
	v_mfma_f32_16x16x32_bf16 v[98:101], v[204:207], v[220:223], v[98:101]
	v_mfma_f32_16x16x32_bf16 v[86:89], v[188:191], v[228:231], v[86:89]
	v_mfma_f32_16x16x32_bf16 v[82:85], v[204:207], v[228:231], v[82:85]
	v_mfma_f32_16x16x32_bf16 v[70:73], v[188:191], v[244:247], v[70:73]
	v_mfma_f32_16x16x32_bf16 v[66:69], v[204:207], v[244:247], v[66:69]
	v_mfma_f32_16x16x32_bf16 v[118:121], v[200:203], v[216:219], v[118:121]
	v_mfma_f32_16x16x32_bf16 v[114:117], v[208:211], v[216:219], v[114:117]
	v_mfma_f32_16x16x32_bf16 v[102:105], v[200:203], v[224:227], v[102:105]
	v_mfma_f32_16x16x32_bf16 v[98:101], v[208:211], v[224:227], v[98:101]
	v_mfma_f32_16x16x32_bf16 v[86:89], v[200:203], v[240:243], v[86:89]
	v_mfma_f32_16x16x32_bf16 v[82:85], v[208:211], v[240:243], v[82:85]
	v_mfma_f32_16x16x32_bf16 v[70:73], v[200:203], v[248:251], v[70:73]
	v_mfma_f32_16x16x32_bf16 v[66:69], v[208:211], v[248:251], v[66:69]
	s_barrier
; #define PG8_STAGE(bufoff, gbase, voff) do { _Pragma("unroll") for (int _i = 0; _i < 2; ++_i) \
;         __builtin_amdgcn_global_load_lds((const unsigned*)((const char*)(gbase) + (voff)[_i]), (PG8_LAS unsigned*)(lds + (bufoff) + ldsw + _i * 8192), 16, 0, 0); } while (0)
; #define PG8_LDA(dst, b, h) do { _Pragma("unroll") for (int m = 0; m < 4; ++m) _Pragma("unroll") for (int k = 0; k < 2; ++k) dst[m][k] = *(const PG8_LAS bf16x8*)(lds + PG8_SA(b, h) + aoff + m * 2048 + k * 1024); } while (0)
; #define PG8_MMA(ai, bj, At, Bt) do { __builtin_amdgcn_s_setprio(1); _Pragma("unroll") for (int m = 0; m < 4; ++m) _Pragma("unroll") for (int n = 0; n < 2; ++n) _Pragma("unroll") for (int k = 0; k < 2; ++k) \
;         acc[ai][bj][m][n] = __builtin_amdgcn_mfma_f32_16x16x32_bf16(Bt[n][k], At[m][k], acc[ai][bj][m][n], 0, 0, 0); __builtin_amdgcn_s_setprio(0); } while (0)
; #define PG8_WAIT_V(n) asm volatile("s_waitcnt vmcnt(" #n ")" ::: "memory")
; #define PG8_WAIT_L(n) asm volatile("s_waitcnt lgkmcnt(" #n ")" ::: "memory")
; #define PG8_BAR __builtin_amdgcn_s_barrier()
; #define PG8_SCHED __builtin_amdgcn_sched_barrier(0)
; template <class Epi, class Sched, bool ALIGN_EPI = false, bool SP2 = false>
; __device__ __forceinline__ void gemm_phase(PG8_LAS unsigned char* lds, const Gemm g, const Sched& S, const Epi& E) {
;     ...
;             PG8_LDA(At, 1, 1); PG8_STAGE(PG8_SB(1, 0), b3, voffB); PG8_STAGE(PG8_SB(1, 1), b3 + hstep, voffB); PG8_STAGE(PG8_SA(1, 0), a3, voffA);
;             PG8_WAIT_V(8); PG8_WAIT_L(0); PG8_BAR; PG8_MMA(1, 0, At, B0); PG8_MMA(1, 1, At, B1); PG8_BAR; PG8_SCHED;
;     ...
;         if constexpr (ALIGN_EPI) { if (wr == 0) PG8_BAR; }
	s_setprio 0
	s_add_i32 s63, s63, s2
	v_lshl_add_u64 v[150:151], v[150:151], 0, s[44:45]
	s_mov_b32 m0, s63
	ds_read_b128 v[212:215], v173 offset:49152
	ds_read_b128 v[216:219], v173 offset:50176
	ds_read_b128 v[220:223], v173 offset:51200
	ds_read_b128 v[224:227], v173 offset:52224
	ds_read_b128 v[228:231], v173 offset:53248
	ds_read_b128 v[240:243], v173 offset:54272
	ds_read_b128 v[244:247], v173 offset:55296
	ds_read_b128 v[248:251], v173 offset:56320
	global_load_lds_dwordx4 v[150:151], off
	s_add_i32 m0, s63, 0x2000
	s_add_u32 s66, s66, 0x100080
	v_lshl_add_u64 v[150:151], v[192:193], 0, s[44:45]
	s_addc_u32 s67, s67, 0
	s_add_i32 s63, s70, s2
	global_load_lds_dwordx4 v[150:151], off
	v_lshl_add_u64 v[150:151], s[66:67], 0, v[132:133]
	s_mov_b32 m0, s63
	s_nop 0
	global_load_lds_dwordx4 v[150:151], off
	v_lshl_add_u64 v[150:151], s[66:67], 0, v[136:137]
	s_add_i32 m0, s63, 0x2000
	s_nop 0
	global_load_lds_dwordx4 v[150:151], off
	v_lshl_add_u64 v[150:151], v[232:233], 0, s[44:45]
	s_mov_b32 m0, s26
	s_nop 0
	global_load_lds_dwordx4 v[150:151], off
	v_lshl_add_u64 v[150:151], v[252:253], 0, s[44:45]
	s_mov_b32 m0, s27
	s_nop 0
	global_load_lds_dwordx4 v[150:151], off
	s_waitcnt vmcnt(8)
	s_waitcnt lgkmcnt(0)
	s_setprio 1
	s_barrier
	v_mfma_f32_16x16x32_bf16 v[62:65], v[146:149], v[212:215], v[62:65]
	v_mfma_f32_16x16x32_bf16 v[58:61], v[180:183], v[212:215], v[58:61]
	v_mfma_f32_16x16x32_bf16 v[46:49], v[146:149], v[220:223], v[46:49]
	v_mfma_f32_16x16x32_bf16 v[42:45], v[180:183], v[220:223], v[42:45]
	v_mfma_f32_16x16x32_bf16 v[30:33], v[146:149], v[228:231], v[30:33]
	v_mfma_f32_16x16x32_bf16 v[26:29], v[180:183], v[228:231], v[26:29]
	v_mfma_f32_16x16x32_bf16 v[14:17], v[146:149], v[244:247], v[14:17]
	v_mfma_f32_16x16x32_bf16 v[10:13], v[180:183], v[244:247], v[10:13]
	v_mfma_f32_16x16x32_bf16 v[62:65], v[176:179], v[216:219], v[62:65]
	v_mfma_f32_16x16x32_bf16 v[58:61], v[184:187], v[216:219], v[58:61]
	v_mfma_f32_16x16x32_bf16 v[46:49], v[176:179], v[224:227], v[46:49]
	v_mfma_f32_16x16x32_bf16 v[42:45], v[184:187], v[224:227], v[42:45]
	v_mfma_f32_16x16x32_bf16 v[30:33], v[176:179], v[240:243], v[30:33]
	v_mfma_f32_16x16x32_bf16 v[26:29], v[184:187], v[240:243], v[26:29]
	v_mfma_f32_16x16x32_bf16 v[14:17], v[176:179], v[248:251], v[14:17]
	v_mfma_f32_16x16x32_bf16 v[10:13], v[184:187], v[248:251], v[10:13]
	s_setprio 0
	s_setprio 1
	v_mfma_f32_16x16x32_bf16 v[54:57], v[188:191], v[212:215], v[54:57]
	v_mfma_f32_16x16x32_bf16 v[50:53], v[204:207], v[212:215], v[50:53]
	v_mfma_f32_16x16x32_bf16 v[38:41], v[188:191], v[220:223], v[38:41]
	v_mfma_f32_16x16x32_bf16 v[34:37], v[204:207], v[220:223], v[34:37]
	v_mfma_f32_16x16x32_bf16 v[22:25], v[188:191], v[228:231], v[22:25]
	v_mfma_f32_16x16x32_bf16 v[18:21], v[204:207], v[228:231], v[18:21]
	v_mfma_f32_16x16x32_bf16 v[6:9], v[188:191], v[244:247], v[6:9]
	v_mfma_f32_16x16x32_bf16 v[2:5], v[204:207], v[244:247], v[2:5]
	v_mfma_f32_16x16x32_bf16 v[54:57], v[200:203], v[216:219], v[54:57]
	v_mfma_f32_16x16x32_bf16 v[50:53], v[208:211], v[216:219], v[50:53]
	v_mfma_f32_16x16x32_bf16 v[38:41], v[200:203], v[224:227], v[38:41]
	v_mfma_f32_16x16x32_bf16 v[34:37], v[208:211], v[224:227], v[34:37]
	v_mfma_f32_16x16x32_bf16 v[22:25], v[200:203], v[240:243], v[22:25]
	v_mfma_f32_16x16x32_bf16 v[18:21], v[208:211], v[240:243], v[18:21]
	v_mfma_f32_16x16x32_bf16 v[6:9], v[200:203], v[248:251], v[6:9]
	v_mfma_f32_16x16x32_bf16 v[2:5], v[208:211], v[248:251], v[2:5]
	s_barrier
	s_setprio 0
	s_add_i32 s61, s61, 2
	s_add_u32 s64, s64, 0x100
	s_addc_u32 s65, s65, 0
	s_add_u32 s53, s53, 0x100
	s_addc_u32 s55, s55, 0
	s_cmp_gt_u32 s61, 61
	s_cbranch_scc0 .LBB0_1203
	s_and_b64 vcc, exec, s[46:47]
	s_cbranch_vccz .LBB0_1206
	s_barrier

; #define PG8_STAGE(bufoff, gbase, voff) do { _Pragma("unroll") for (int _i = 0; _i < 2; ++_i) \
;         __builtin_amdgcn_global_load_lds((const unsigned*)((const char*)(gbase) + (voff)[_i]), (PG8_LAS unsigned*)(lds + (bufoff) + ldsw + _i * 8192), 16, 0, 0); } while (0)
; #define PG8_LDA(dst, b, h) do { _Pragma("unroll") for (int m = 0; m < 4; ++m) _Pragma("unroll") for (int k = 0; k < 2; ++k) dst[m][k] = *(const PG8_LAS bf16x8*)(lds + PG8_SA(b, h) + aoff + m * 2048 + k * 1024); } while (0)
; #define PG8_LDB(dst, b, h) do { _Pragma("unroll") for (int n = 0; n < 2; ++n) _Pragma("unroll") for (int k = 0; k < 2; ++k) dst[n][k] = *(const PG8_LAS bf16x8*)(lds + PG8_SB(b, h) + boff + n * 2048 + k * 1024); } while (0)
; #define PG8_MMA(ai, bj, At, Bt) do { __builtin_amdgcn_s_setprio(1); _Pragma("unroll") for (int m = 0; m < 4; ++m) _Pragma("unroll") for (int n = 0; n < 2; ++n) _Pragma("unroll") for (int k = 0; k < 2; ++k) \
;         acc[ai][bj][m][n] = __builtin_amdgcn_mfma_f32_16x16x32_bf16(Bt[n][k], At[m][k], acc[ai][bj][m][n], 0, 0, 0); __builtin_amdgcn_s_setprio(0); } while (0)
; #define PG8_WAIT_V(n) asm volatile("s_waitcnt vmcnt(" #n ")" ::: "memory")
; #define PG8_WAIT_L(n) asm volatile("s_waitcnt lgkmcnt(" #n ")" ::: "memory")
; #define PG8_BAR __builtin_amdgcn_s_barrier()
; #define PG8_SCHED __builtin_amdgcn_sched_barrier(0)
; template <class Epi, class Sched, bool ALIGN_EPI = false, bool SP2 = false>
; __device__ __forceinline__ void gemm_phase(PG8_LAS unsigned char* lds, const Gemm g, const Sched& S, const Epi& E) {
;     ...
;             PG8_LDB(B0, 0, 0); PG8_LDB(B1, 0, 1); PG8_SCHED; PG8_LDA(At, 0, 0); PG8_STAGE(PG8_SA(1, 1), a1 + hstep, voffA);
;             PG8_WAIT_V(8); PG8_WAIT_L(0); PG8_BAR; PG8_MMA(0, 0, At, B0); PG8_MMA(0, 1, At, B1); PG8_BAR; PG8_SCHED;
;             PG8_LDA(At, 0, 1); PG8_STAGE(PG8_SB(0, 0), b2, voffB); PG8_STAGE(PG8_SB(0, 1), b2 + hstep, voffB); PG8_STAGE(PG8_SA(0, 0), a2, voffA);
;             PG8_WAIT_V(8); PG8_WAIT_L(0); PG8_BAR; PG8_MMA(1, 0, At, B0); PG8_MMA(1, 1, At, B1); PG8_BAR; PG8_SCHED;
.LBB0_1230:
	ds_read_b128 v[146:149], v140
	ds_read_b128 v[150:153], v140 offset:1024
	ds_read_b128 v[154:157], v140 offset:2048
	ds_read_b128 v[158:161], v140 offset:3072
	ds_read_b128 v[168:171], v141
	ds_read_b128 v[172:175], v141 offset:1024
	ds_read_b128 v[176:179], v141 offset:2048
	ds_read_b128 v[180:183], v141 offset:3072
	s_add_u32 s50, s46, 0x100
	s_addc_u32 s51, s47, 0
	s_cmp_lg_u32 s30, 12
	s_cselect_b32 s52, s50, 0
	s_cselect_b32 s53, s51, 0
	s_add_u32 s54, s10, s52
	s_addc_u32 s55, s11, s53
	s_add_u32 s52, s8, s52
	s_addc_u32 s53, s9, s53
	s_mov_b32 m0, s33
	v_lshl_add_u64 v[162:163], v[134:135], 0, s[46:47]
	ds_read_b128 v[184:187], v142
	ds_read_b128 v[188:191], v142 offset:1024
	ds_read_b128 v[200:203], v142 offset:2048
	ds_read_b128 v[204:207], v142 offset:3072
	ds_read_b128 v[208:211], v142 offset:4096
	ds_read_b128 v[212:215], v142 offset:5120
	ds_read_b128 v[216:219], v142 offset:6144
	ds_read_b128 v[220:223], v142 offset:7168
	global_load_lds_dwordx4 v[162:163], off
	v_lshl_add_u64 v[162:163], v[136:137], 0, s[46:47]
	s_mov_b32 m0, s34
	s_nop 0
	global_load_lds_dwordx4 v[162:163], off
	s_waitcnt vmcnt(8)
	s_waitcnt lgkmcnt(0)
	s_setprio 1
	s_barrier
	v_mfma_f32_16x16x32_bf16 v[126:129], v[146:149], v[184:187], v[126:129]
	v_mfma_f32_16x16x32_bf16 v[122:125], v[154:157], v[184:187], v[122:125]
	v_mfma_f32_16x16x32_bf16 v[118:121], v[146:149], v[200:203], v[118:121]
	v_mfma_f32_16x16x32_bf16 v[114:117], v[154:157], v[200:203], v[114:117]
	v_mfma_f32_16x16x32_bf16 v[106:109], v[146:149], v[208:211], v[106:109]
	v_mfma_f32_16x16x32_bf16 v[98:101], v[154:157], v[208:211], v[98:101]
	v_mfma_f32_16x16x32_bf16 v[90:93], v[146:149], v[216:219], v[90:93]
	v_mfma_f32_16x16x32_bf16 v[82:85], v[154:157], v[216:219], v[82:85]
	v_mfma_f32_16x16x32_bf16 v[126:129], v[150:153], v[188:191], v[126:129]
	v_mfma_f32_16x16x32_bf16 v[122:125], v[158:161], v[188:191], v[122:125]
	v_mfma_f32_16x16x32_bf16 v[118:121], v[150:153], v[204:207], v[118:121]
	v_mfma_f32_16x16x32_bf16 v[114:117], v[158:161], v[204:207], v[114:117]
	v_mfma_f32_16x16x32_bf16 v[106:109], v[150:153], v[212:215], v[106:109]
	v_mfma_f32_16x16x32_bf16 v[98:101], v[158:161], v[212:215], v[98:101]
	v_mfma_f32_16x16x32_bf16 v[90:93], v[150:153], v[220:223], v[90:93]
	v_mfma_f32_16x16x32_bf16 v[82:85], v[158:161], v[220:223], v[82:85]
	s_setprio 0
	s_setprio 1
	v_mfma_f32_16x16x32_bf16 v[110:113], v[168:171], v[184:187], v[110:113]
	v_mfma_f32_16x16x32_bf16 v[102:105], v[176:179], v[184:187], v[102:105]
	v_mfma_f32_16x16x32_bf16 v[94:97], v[168:171], v[200:203], v[94:97]
	v_mfma_f32_16x16x32_bf16 v[86:89], v[176:179], v[200:203], v[86:89]
	v_mfma_f32_16x16x32_bf16 v[78:81], v[168:171], v[208:211], v[78:81]
	v_mfma_f32_16x16x32_bf16 v[74:77], v[176:179], v[208:211], v[74:77]
	v_mfma_f32_16x16x32_bf16 v[70:73], v[168:171], v[216:219], v[70:73]
	v_mfma_f32_16x16x32_bf16 v[66:69], v[176:179], v[216:219], v[66:69]
	v_mfma_f32_16x16x32_bf16 v[110:113], v[172:175], v[188:191], v[110:113]
	v_mfma_f32_16x16x32_bf16 v[102:105], v[180:183], v[188:191], v[102:105]
	v_mfma_f32_16x16x32_bf16 v[94:97], v[172:175], v[204:207], v[94:97]
	v_mfma_f32_16x16x32_bf16 v[86:89], v[180:183], v[204:207], v[86:89]
	v_mfma_f32_16x16x32_bf16 v[78:81], v[172:175], v[212:215], v[78:81]
	v_mfma_f32_16x16x32_bf16 v[74:77], v[180:183], v[212:215], v[74:77]
	v_mfma_f32_16x16x32_bf16 v[70:73], v[172:175], v[220:223], v[70:73]
	v_mfma_f32_16x16x32_bf16 v[66:69], v[180:183], v[220:223], v[66:69]
	s_barrier
	s_setprio 0
	s_mov_b32 m0, s35
	v_lshl_add_u64 v[162:163], s[52:53], 0, v[130:131]
	s_add_u32 s46, s52, 0x100000
	ds_read_b128 v[184:187], v142 offset:16384
	ds_read_b128 v[188:191], v142 offset:17408
	ds_read_b128 v[200:203], v142 offset:18432
	ds_read_b128 v[204:207], v142 offset:19456
	ds_read_b128 v[208:211], v142 offset:20480
	ds_read_b128 v[212:215], v142 offset:21504
	ds_read_b128 v[216:219], v142 offset:22528
	ds_read_b128 v[220:223], v142 offset:23552
	global_load_lds_dwordx4 v[162:163], off
	v_lshl_add_u64 v[192:193], s[52:53], 0, v[132:133]
	s_mov_b32 m0, s39
	s_addc_u32 s47, s53, 0
	global_load_lds_dwordx4 v[192:193], off
	v_lshl_add_u64 v[194:195], s[46:47], 0, v[130:131]
	s_mov_b32 m0, s40
	v_lshl_add_u64 v[224:225], s[54:55], 0, v[132:133]
	global_load_lds_dwordx4 v[194:195], off
	v_lshl_add_u64 v[194:195], s[46:47], 0, v[132:133]
	s_mov_b32 m0, s41
	s_nop 0
	global_load_lds_dwordx4 v[194:195], off
	v_lshl_add_u64 v[194:195], s[54:55], 0, v[130:131]
	s_mov_b32 m0, s7
	s_nop 0
	global_load_lds_dwordx4 v[194:195], off
	s_mov_b32 m0, s16
	s_nop 0
	global_load_lds_dwordx4 v[224:225], off
	s_waitcnt vmcnt(8)
	s_waitcnt lgkmcnt(0)
	s_setprio 1
	s_barrier
; #define PG8_STAGE(bufoff, gbase, voff) do { _Pragma("unroll") for (int _i = 0; _i < 2; ++_i) \
;         __builtin_amdgcn_global_load_lds((const unsigned*)((const char*)(gbase) + (voff)[_i]), (PG8_LAS unsigned*)(lds + (bufoff) + ldsw + _i * 8192), 16, 0, 0); } while (0)
; #define PG8_LDA(dst, b, h) do { _Pragma("unroll") for (int m = 0; m < 4; ++m) _Pragma("unroll") for (int k = 0; k < 2; ++k) dst[m][k] = *(const PG8_LAS bf16x8*)(lds + PG8_SA(b, h) + aoff + m * 2048 + k * 1024); } while (0)
; #define PG8_LDB(dst, b, h) do { _Pragma("unroll") for (int n = 0; n < 2; ++n) _Pragma("unroll") for (int k = 0; k < 2; ++k) dst[n][k] = *(const PG8_LAS bf16x8*)(lds + PG8_SB(b, h) + boff + n * 2048 + k * 1024); } while (0)
; #define PG8_MMA(ai, bj, At, Bt) do { __builtin_amdgcn_s_setprio(1); _Pragma("unroll") for (int m = 0; m < 4; ++m) _Pragma("unroll") for (int n = 0; n < 2; ++n) _Pragma("unroll") for (int k = 0; k < 2; ++k) \
;         acc[ai][bj][m][n] = __builtin_amdgcn_mfma_f32_16x16x32_bf16(Bt[n][k], At[m][k], acc[ai][bj][m][n], 0, 0, 0); __builtin_amdgcn_s_setprio(0); } while (0)
; #define PG8_WAIT_V(n) asm volatile("s_waitcnt vmcnt(" #n ")" ::: "memory")
; #define PG8_WAIT_L(n) asm volatile("s_waitcnt lgkmcnt(" #n ")" ::: "memory")
; #define PG8_BAR __builtin_amdgcn_s_barrier()
; #define PG8_SCHED __builtin_amdgcn_sched_barrier(0)
; template <class Epi, class Sched, bool ALIGN_EPI = false, bool SP2 = false>
; __device__ __forceinline__ void gemm_phase(PG8_LAS unsigned char* lds, const Gemm g, const Sched& S, const Epi& E) {
;     ...
;             PG8_WAIT_V(8); PG8_WAIT_L(0); PG8_BAR; PG8_MMA(1, 0, At, B0); PG8_MMA(1, 1, At, B1); PG8_BAR; PG8_SCHED;
;             PG8_LDB(B0, 1, 0); PG8_LDB(B1, 1, 1); PG8_SCHED; PG8_LDA(At, 1, 0); PG8_STAGE(PG8_SA(0, 1), a2 + hstep, voffA);
;             PG8_WAIT_V(8); PG8_WAIT_L(0); PG8_BAR; PG8_MMA(0, 0, At, B0); PG8_MMA(0, 1, At, B1); PG8_BAR; PG8_SCHED;
	v_mfma_f32_16x16x32_bf16 v[62:65], v[146:149], v[184:187], v[62:65]
	v_mfma_f32_16x16x32_bf16 v[58:61], v[154:157], v[184:187], v[58:61]
	v_mfma_f32_16x16x32_bf16 v[54:57], v[146:149], v[200:203], v[54:57]
	v_mfma_f32_16x16x32_bf16 v[50:53], v[154:157], v[200:203], v[50:53]
	v_mfma_f32_16x16x32_bf16 v[42:45], v[146:149], v[208:211], v[42:45]
	v_mfma_f32_16x16x32_bf16 v[34:37], v[154:157], v[208:211], v[34:37]
	v_mfma_f32_16x16x32_bf16 v[26:29], v[146:149], v[216:219], v[26:29]
	v_mfma_f32_16x16x32_bf16 v[18:21], v[154:157], v[216:219], v[18:21]
	v_mfma_f32_16x16x32_bf16 v[62:65], v[150:153], v[188:191], v[62:65]
	v_mfma_f32_16x16x32_bf16 v[58:61], v[158:161], v[188:191], v[58:61]
	v_mfma_f32_16x16x32_bf16 v[54:57], v[150:153], v[204:207], v[54:57]
	v_mfma_f32_16x16x32_bf16 v[50:53], v[158:161], v[204:207], v[50:53]
	v_mfma_f32_16x16x32_bf16 v[42:45], v[150:153], v[212:215], v[42:45]
	v_mfma_f32_16x16x32_bf16 v[34:37], v[158:161], v[212:215], v[34:37]
	v_mfma_f32_16x16x32_bf16 v[26:29], v[150:153], v[220:223], v[26:29]
	v_mfma_f32_16x16x32_bf16 v[18:21], v[158:161], v[220:223], v[18:21]
	s_setprio 0
	s_setprio 1
	v_mfma_f32_16x16x32_bf16 v[46:49], v[168:171], v[184:187], v[46:49]
	v_mfma_f32_16x16x32_bf16 v[38:41], v[176:179], v[184:187], v[38:41]
	v_mfma_f32_16x16x32_bf16 v[30:33], v[168:171], v[200:203], v[30:33]
	v_mfma_f32_16x16x32_bf16 v[22:25], v[176:179], v[200:203], v[22:25]
	v_mfma_f32_16x16x32_bf16 v[14:17], v[168:171], v[208:211], v[14:17]
	v_mfma_f32_16x16x32_bf16 v[10:13], v[176:179], v[208:211], v[10:13]
	v_mfma_f32_16x16x32_bf16 v[6:9], v[168:171], v[216:219], v[6:9]
	v_mfma_f32_16x16x32_bf16 v[2:5], v[176:179], v[216:219], v[2:5]
	v_mfma_f32_16x16x32_bf16 v[46:49], v[172:175], v[188:191], v[46:49]
	v_mfma_f32_16x16x32_bf16 v[38:41], v[180:183], v[188:191], v[38:41]
	v_mfma_f32_16x16x32_bf16 v[30:33], v[172:175], v[204:207], v[30:33]
	v_mfma_f32_16x16x32_bf16 v[22:25], v[180:183], v[204:207], v[22:25]
	v_mfma_f32_16x16x32_bf16 v[14:17], v[172:175], v[212:215], v[14:17]
	v_mfma_f32_16x16x32_bf16 v[10:13], v[180:183], v[212:215], v[10:13]
	v_mfma_f32_16x16x32_bf16 v[6:9], v[172:175], v[220:223], v[6:9]
	v_mfma_f32_16x16x32_bf16 v[2:5], v[180:183], v[220:223], v[2:5]
	s_barrier
	s_setprio 0
	ds_read_b128 v[146:149], v143
	ds_read_b128 v[150:153], v143 offset:1024
	ds_read_b128 v[154:157], v143 offset:2048
	ds_read_b128 v[158:161], v143 offset:3072
	ds_read_b128 v[168:171], v144
	ds_read_b128 v[172:175], v144 offset:1024
	ds_read_b128 v[176:179], v144 offset:2048
	ds_read_b128 v[180:183], v144 offset:3072
	s_add_u32 s46, s54, 0x100000
	s_addc_u32 s47, s55, 0
	s_mov_b32 m0, s17
	v_lshl_add_u64 v[226:227], s[46:47], 0, v[130:131]
	ds_read_b128 v[184:187], v142 offset:32768
	ds_read_b128 v[188:191], v142 offset:33792
	ds_read_b128 v[200:203], v142 offset:34816
	ds_read_b128 v[204:207], v142 offset:35840
	ds_read_b128 v[208:211], v142 offset:36864
	ds_read_b128 v[212:215], v142 offset:37888
	ds_read_b128 v[216:219], v142 offset:38912
	ds_read_b128 v[220:223], v142 offset:39936
	global_load_lds_dwordx4 v[226:227], off
	v_lshl_add_u64 v[226:227], s[46:47], 0, v[132:133]
	s_mov_b32 m0, s26
	s_nop 0
	global_load_lds_dwordx4 v[226:227], off
	s_waitcnt vmcnt(8)
	s_waitcnt lgkmcnt(0)
	s_setprio 1
	s_barrier
	v_mfma_f32_16x16x32_bf16 v[126:129], v[146:149], v[184:187], v[126:129]
	v_mfma_f32_16x16x32_bf16 v[122:125], v[154:157], v[184:187], v[122:125]
	v_mfma_f32_16x16x32_bf16 v[118:121], v[146:149], v[200:203], v[118:121]
	v_mfma_f32_16x16x32_bf16 v[114:117], v[154:157], v[200:203], v[114:117]
	v_mfma_f32_16x16x32_bf16 v[106:109], v[146:149], v[208:211], v[106:109]
	v_mfma_f32_16x16x32_bf16 v[98:101], v[154:157], v[208:211], v[98:101]
	v_mfma_f32_16x16x32_bf16 v[90:93], v[146:149], v[216:219], v[90:93]
	v_mfma_f32_16x16x32_bf16 v[82:85], v[154:157], v[216:219], v[82:85]
	v_mfma_f32_16x16x32_bf16 v[126:129], v[150:153], v[188:191], v[126:129]
	v_mfma_f32_16x16x32_bf16 v[122:125], v[158:161], v[188:191], v[122:125]
	v_mfma_f32_16x16x32_bf16 v[118:121], v[150:153], v[204:207], v[118:121]
	v_mfma_f32_16x16x32_bf16 v[114:117], v[158:161], v[204:207], v[114:117]
	v_mfma_f32_16x16x32_bf16 v[106:109], v[150:153], v[212:215], v[106:109]
	v_mfma_f32_16x16x32_bf16 v[98:101], v[158:161], v[212:215], v[98:101]
	v_mfma_f32_16x16x32_bf16 v[90:93], v[150:153], v[220:223], v[90:93]
	v_mfma_f32_16x16x32_bf16 v[82:85], v[158:161], v[220:223], v[82:85]
	s_setprio 0
	s_setprio 1
	v_mfma_f32_16x16x32_bf16 v[110:113], v[168:171], v[184:187], v[110:113]
	v_mfma_f32_16x16x32_bf16 v[102:105], v[176:179], v[184:187], v[102:105]
	v_mfma_f32_16x16x32_bf16 v[94:97], v[168:171], v[200:203], v[94:97]
	v_mfma_f32_16x16x32_bf16 v[86:89], v[176:179], v[200:203], v[86:89]
	v_mfma_f32_16x16x32_bf16 v[78:81], v[168:171], v[208:211], v[78:81]
	v_mfma_f32_16x16x32_bf16 v[74:77], v[176:179], v[208:211], v[74:77]
	v_mfma_f32_16x16x32_bf16 v[70:73], v[168:171], v[216:219], v[70:73]
	v_mfma_f32_16x16x32_bf16 v[66:69], v[176:179], v[216:219], v[66:69]
	v_mfma_f32_16x16x32_bf16 v[110:113], v[172:175], v[188:191], v[110:113]
	v_mfma_f32_16x16x32_bf16 v[102:105], v[180:183], v[188:191], v[102:105]
	v_mfma_f32_16x16x32_bf16 v[94:97], v[172:175], v[204:207], v[94:97]
	v_mfma_f32_16x16x32_bf16 v[86:89], v[180:183], v[204:207], v[86:89]
	v_mfma_f32_16x16x32_bf16 v[78:81], v[172:175], v[212:215], v[78:81]
	v_mfma_f32_16x16x32_bf16 v[74:77], v[180:183], v[212:215], v[74:77]
	v_mfma_f32_16x16x32_bf16 v[70:73], v[172:175], v[220:223], v[70:73]
	v_mfma_f32_16x16x32_bf16 v[66:69], v[180:183], v[220:223], v[66:69]
	s_barrier
; #define PG8_STAGE(bufoff, gbase, voff) do { _Pragma("unroll") for (int _i = 0; _i < 2; ++_i) \
;         __builtin_amdgcn_global_load_lds((const unsigned*)((const char*)(gbase) + (voff)[_i]), (PG8_LAS unsigned*)(lds + (bufoff) + ldsw + _i * 8192), 16, 0, 0); } while (0)
; #define PG8_LDA(dst, b, h) do { _Pragma("unroll") for (int m = 0; m < 4; ++m) _Pragma("unroll") for (int k = 0; k < 2; ++k) dst[m][k] = *(const PG8_LAS bf16x8*)(lds + PG8_SA(b, h) + aoff + m * 2048 + k * 1024); } while (0)
; #define PG8_MMA(ai, bj, At, Bt) do { __builtin_amdgcn_s_setprio(1); _Pragma("unroll") for (int m = 0; m < 4; ++m) _Pragma("unroll") for (int n = 0; n < 2; ++n) _Pragma("unroll") for (int k = 0; k < 2; ++k) \
;         acc[ai][bj][m][n] = __builtin_amdgcn_mfma_f32_16x16x32_bf16(Bt[n][k], At[m][k], acc[ai][bj][m][n], 0, 0, 0); __builtin_amdgcn_s_setprio(0); } while (0)
; #define PG8_WAIT_V(n) asm volatile("s_waitcnt vmcnt(" #n ")" ::: "memory")
; #define PG8_WAIT_L(n) asm volatile("s_waitcnt lgkmcnt(" #n ")" ::: "memory")
; #define PG8_BAR __builtin_amdgcn_s_barrier()
; #define PG8_SCHED __builtin_amdgcn_sched_barrier(0)
; template <class Epi, class Sched, bool ALIGN_EPI = false, bool SP2 = false>
; __device__ __forceinline__ void gemm_phase(PG8_LAS unsigned char* lds, const Gemm g, const Sched& S, const Epi& E) {
;     ...
;             PG8_LDA(At, 1, 1); PG8_STAGE(PG8_SB(1, 0), b3, voffB); PG8_STAGE(PG8_SB(1, 1), b3 + hstep, voffB); PG8_STAGE(PG8_SA(1, 0), a3, voffA);
;             PG8_WAIT_V(8); PG8_WAIT_L(0); PG8_BAR; PG8_MMA(1, 0, At, B0); PG8_MMA(1, 1, At, B1); PG8_BAR; PG8_SCHED;
;     ...
;         if constexpr (ALIGN_EPI) { if (wr == 0) PG8_BAR; }
	s_setprio 0
	s_mov_b32 m0, s44
	v_lshl_add_u64 v[162:163], v[162:163], 0, s[12:13]
	s_add_u32 s46, s52, 0x100080
	ds_read_b128 v[184:187], v142 offset:49152
	ds_read_b128 v[188:191], v142 offset:50176
	ds_read_b128 v[200:203], v142 offset:51200
	ds_read_b128 v[204:207], v142 offset:52224
	ds_read_b128 v[208:211], v142 offset:53248
	ds_read_b128 v[212:215], v142 offset:54272
	ds_read_b128 v[216:219], v142 offset:55296
	ds_read_b128 v[220:223], v142 offset:56320
	global_load_lds_dwordx4 v[162:163], off
	v_lshl_add_u64 v[162:163], v[192:193], 0, s[12:13]
	s_mov_b32 m0, s45
	s_addc_u32 s47, s53, 0
	global_load_lds_dwordx4 v[162:163], off
	v_lshl_add_u64 v[162:163], s[46:47], 0, v[130:131]
	s_mov_b32 m0, s56
	s_nop 0
	global_load_lds_dwordx4 v[162:163], off
	v_lshl_add_u64 v[162:163], s[46:47], 0, v[132:133]
	s_mov_b32 m0, s57
	s_nop 0
	global_load_lds_dwordx4 v[162:163], off
	v_lshl_add_u64 v[162:163], v[194:195], 0, s[12:13]
	s_mov_b32 m0, s28
	s_nop 0
	global_load_lds_dwordx4 v[162:163], off
	v_lshl_add_u64 v[162:163], v[224:225], 0, s[12:13]
	s_mov_b32 m0, s29
	s_nop 0
	global_load_lds_dwordx4 v[162:163], off
	s_waitcnt vmcnt(8)
	s_waitcnt lgkmcnt(0)
	s_setprio 1
	s_barrier
	v_mfma_f32_16x16x32_bf16 v[62:65], v[146:149], v[184:187], v[62:65]
	v_mfma_f32_16x16x32_bf16 v[58:61], v[154:157], v[184:187], v[58:61]
	v_mfma_f32_16x16x32_bf16 v[54:57], v[146:149], v[200:203], v[54:57]
	v_mfma_f32_16x16x32_bf16 v[50:53], v[154:157], v[200:203], v[50:53]
	v_mfma_f32_16x16x32_bf16 v[42:45], v[146:149], v[208:211], v[42:45]
	v_mfma_f32_16x16x32_bf16 v[34:37], v[154:157], v[208:211], v[34:37]
	v_mfma_f32_16x16x32_bf16 v[26:29], v[146:149], v[216:219], v[26:29]
	v_mfma_f32_16x16x32_bf16 v[18:21], v[154:157], v[216:219], v[18:21]
	v_mfma_f32_16x16x32_bf16 v[62:65], v[150:153], v[188:191], v[62:65]
	v_mfma_f32_16x16x32_bf16 v[58:61], v[158:161], v[188:191], v[58:61]
	v_mfma_f32_16x16x32_bf16 v[54:57], v[150:153], v[204:207], v[54:57]
	v_mfma_f32_16x16x32_bf16 v[50:53], v[158:161], v[204:207], v[50:53]
	v_mfma_f32_16x16x32_bf16 v[42:45], v[150:153], v[212:215], v[42:45]
	v_mfma_f32_16x16x32_bf16 v[34:37], v[158:161], v[212:215], v[34:37]
	v_mfma_f32_16x16x32_bf16 v[26:29], v[150:153], v[220:223], v[26:29]
	v_mfma_f32_16x16x32_bf16 v[18:21], v[158:161], v[220:223], v[18:21]
	s_setprio 0
	s_setprio 1
	v_mfma_f32_16x16x32_bf16 v[46:49], v[168:171], v[184:187], v[46:49]
	v_mfma_f32_16x16x32_bf16 v[38:41], v[176:179], v[184:187], v[38:41]
	v_mfma_f32_16x16x32_bf16 v[30:33], v[168:171], v[200:203], v[30:33]
	v_mfma_f32_16x16x32_bf16 v[22:25], v[176:179], v[200:203], v[22:25]
	v_mfma_f32_16x16x32_bf16 v[14:17], v[168:171], v[208:211], v[14:17]
	v_mfma_f32_16x16x32_bf16 v[10:13], v[176:179], v[208:211], v[10:13]
	v_mfma_f32_16x16x32_bf16 v[6:9], v[168:171], v[216:219], v[6:9]
	v_mfma_f32_16x16x32_bf16 v[2:5], v[176:179], v[216:219], v[2:5]
	v_mfma_f32_16x16x32_bf16 v[46:49], v[172:175], v[188:191], v[46:49]
	v_mfma_f32_16x16x32_bf16 v[38:41], v[180:183], v[188:191], v[38:41]
	v_mfma_f32_16x16x32_bf16 v[30:33], v[172:175], v[204:207], v[30:33]
	v_mfma_f32_16x16x32_bf16 v[22:25], v[180:183], v[204:207], v[22:25]
	v_mfma_f32_16x16x32_bf16 v[14:17], v[172:175], v[212:215], v[14:17]
	v_mfma_f32_16x16x32_bf16 v[10:13], v[180:183], v[212:215], v[10:13]
	v_mfma_f32_16x16x32_bf16 v[6:9], v[172:175], v[220:223], v[6:9]
	v_mfma_f32_16x16x32_bf16 v[2:5], v[180:183], v[220:223], v[2:5]
	s_barrier
	s_setprio 0
	s_add_i32 s30, s30, 2
	s_cmp_gt_u32 s30, 13
	s_mov_b64 s[46:47], s[50:51]
	s_cbranch_scc0 .LBB0_1230
	s_cmpk_lt_u32 s2, 0x100
	s_cbranch_scc0 .LBB0_1233
	s_barrier

; #define PG8_STAGE(bufoff, gbase, voff) do { _Pragma("unroll") for (int _i = 0; _i < 2; ++_i) \
;         __builtin_amdgcn_global_load_lds((const unsigned*)((const char*)(gbase) + (voff)[_i]), (PG8_LAS unsigned*)(lds + (bufoff) + ldsw + _i * 8192), 16, 0, 0); } while (0)
; #define PG8_LDA(dst, b, h) do { _Pragma("unroll") for (int m = 0; m < 4; ++m) _Pragma("unroll") for (int k = 0; k < 2; ++k) dst[m][k] = *(const PG8_LAS bf16x8*)(lds + PG8_SA(b, h) + aoff + m * 2048 + k * 1024); } while (0)
; #define PG8_LDB(dst, b, h) do { _Pragma("unroll") for (int n = 0; n < 2; ++n) _Pragma("unroll") for (int k = 0; k < 2; ++k) dst[n][k] = *(const PG8_LAS bf16x8*)(lds + PG8_SB(b, h) + boff + n * 2048 + k * 1024); } while (0)
; #define PG8_MMA(ai, bj, At, Bt) do { __builtin_amdgcn_s_setprio(1); _Pragma("unroll") for (int m = 0; m < 4; ++m) _Pragma("unroll") for (int n = 0; n < 2; ++n) _Pragma("unroll") for (int k = 0; k < 2; ++k) \
;         acc[ai][bj][m][n] = __builtin_amdgcn_mfma_f32_16x16x32_bf16(Bt[n][k], At[m][k], acc[ai][bj][m][n], 0, 0, 0); __builtin_amdgcn_s_setprio(0); } while (0)
; #define PG8_WAIT_V(n) asm volatile("s_waitcnt vmcnt(" #n ")" ::: "memory")
; #define PG8_WAIT_L(n) asm volatile("s_waitcnt lgkmcnt(" #n ")" ::: "memory")
; #define PG8_BAR __builtin_amdgcn_s_barrier()
; #define PG8_SCHED __builtin_amdgcn_sched_barrier(0)
; template <class Epi, class Sched, bool ALIGN_EPI = false, bool SP2 = false>
; __device__ __forceinline__ void gemm_phase(PG8_LAS unsigned char* lds, const Gemm g, const Sched& S, const Epi& E) {
;     ...
;             PG8_LDB(B0, 0, 0); PG8_LDB(B1, 0, 1); PG8_SCHED; PG8_LDA(At, 0, 0); PG8_STAGE(PG8_SA(1, 1), a1 + hstep, voffA);
;             PG8_WAIT_V(8); PG8_WAIT_L(0); PG8_BAR; PG8_MMA(0, 0, At, B0); PG8_MMA(0, 1, At, B1); PG8_BAR; PG8_SCHED;
;             PG8_LDA(At, 0, 1); PG8_STAGE(PG8_SB(0, 0), b2, voffB); PG8_STAGE(PG8_SB(0, 1), b2 + hstep, voffB); PG8_STAGE(PG8_SA(0, 0), a2, voffA);
;             PG8_WAIT_V(8); PG8_WAIT_L(0); PG8_BAR; PG8_MMA(1, 0, At, B0); PG8_MMA(1, 1, At, B1); PG8_BAR; PG8_SCHED;
.LBB0_1478:
	v_add_u32_e32 v144, s31, v201
	v_add_u32_e32 v160, s52, v201
	ds_read_b128 v[132:135], v144
	ds_read_b128 v[136:139], v144 offset:1024
	ds_read_b128 v[140:143], v144 offset:2048
	ds_read_b128 v[144:147], v144 offset:3072
	ds_read_b128 v[148:151], v160
	ds_read_b128 v[152:155], v160 offset:1024
	ds_read_b128 v[156:159], v160 offset:2048
	ds_read_b128 v[160:163], v160 offset:3072
	s_add_u32 s50, s82, 0xfff00080
	s_addc_u32 s56, s83, -1
	s_and_b64 s[34:35], s[84:85], exec
	s_cselect_b32 s87, s65, s56
	s_cselect_b32 s86, s69, s50
	s_cselect_b32 s85, s67, s88
	s_cselect_b32 s84, s77, s79
	v_lshl_add_u64 v[192:193], s[82:83], 0, v[220:221]
	s_add_i32 m0, s28, 0xc000
	ds_read_b128 v[164:167], v242
	ds_read_b128 v[168:171], v242 offset:1024
	ds_read_b128 v[172:175], v242 offset:2048
	ds_read_b128 v[176:179], v242 offset:3072
	ds_read_b128 v[180:183], v242 offset:4096
	ds_read_b128 v[184:187], v242 offset:5120
	ds_read_b128 v[188:191], v242 offset:6144
	ds_read_b128 v[226:229], v242 offset:7168
	global_load_lds_dwordx4 v[192:193], off
	v_lshl_add_u64 v[192:193], s[82:83], 0, v[222:223]
	s_add_i32 m0, s28, 0xe000
	s_nop 0
	global_load_lds_dwordx4 v[192:193], off
	s_waitcnt vmcnt(8)
	s_waitcnt lgkmcnt(0)
	s_setprio 1
	s_barrier
	v_mfma_f32_16x16x32_bf16 v[126:129], v[132:135], v[164:167], v[126:129]
	v_mfma_f32_16x16x32_bf16 v[46:49], v[140:143], v[164:167], v[46:49]
	v_mfma_f32_16x16x32_bf16 v[118:121], v[132:135], v[172:175], v[118:121]
	v_mfma_f32_16x16x32_bf16 v[122:125], v[140:143], v[172:175], v[122:125]
	v_mfma_f32_16x16x32_bf16 v[110:113], v[132:135], v[180:183], v[110:113]
	v_mfma_f32_16x16x32_bf16 v[114:117], v[140:143], v[180:183], v[114:117]
	v_mfma_f32_16x16x32_bf16 v[102:105], v[132:135], v[188:191], v[102:105]
	v_mfma_f32_16x16x32_bf16 v[106:109], v[140:143], v[188:191], v[106:109]
	v_mfma_f32_16x16x32_bf16 v[126:129], v[136:139], v[168:171], v[126:129]
	v_mfma_f32_16x16x32_bf16 v[46:49], v[144:147], v[168:171], v[46:49]
	v_mfma_f32_16x16x32_bf16 v[118:121], v[136:139], v[176:179], v[118:121]
	v_mfma_f32_16x16x32_bf16 v[122:125], v[144:147], v[176:179], v[122:125]
	v_mfma_f32_16x16x32_bf16 v[110:113], v[136:139], v[184:187], v[110:113]
	v_mfma_f32_16x16x32_bf16 v[114:117], v[144:147], v[184:187], v[114:117]
	v_mfma_f32_16x16x32_bf16 v[102:105], v[136:139], v[226:229], v[102:105]
	v_mfma_f32_16x16x32_bf16 v[106:109], v[144:147], v[226:229], v[106:109]
	s_setprio 0
	s_setprio 1
	v_mfma_f32_16x16x32_bf16 v[54:57], v[148:151], v[164:167], v[54:57]
	v_mfma_f32_16x16x32_bf16 v[38:41], v[156:159], v[164:167], v[38:41]
	v_mfma_f32_16x16x32_bf16 v[58:61], v[148:151], v[172:175], v[58:61]
	v_mfma_f32_16x16x32_bf16 v[30:33], v[156:159], v[172:175], v[30:33]
	v_mfma_f32_16x16x32_bf16 v[62:65], v[148:151], v[180:183], v[62:65]
	v_mfma_f32_16x16x32_bf16 v[22:25], v[156:159], v[180:183], v[22:25]
	v_mfma_f32_16x16x32_bf16 v[98:101], v[148:151], v[188:191], v[98:101]
	v_mfma_f32_16x16x32_bf16 v[50:53], v[156:159], v[188:191], v[50:53]
	v_mfma_f32_16x16x32_bf16 v[54:57], v[152:155], v[168:171], v[54:57]
	v_mfma_f32_16x16x32_bf16 v[38:41], v[160:163], v[168:171], v[38:41]
	v_mfma_f32_16x16x32_bf16 v[58:61], v[152:155], v[176:179], v[58:61]
	v_mfma_f32_16x16x32_bf16 v[30:33], v[160:163], v[176:179], v[30:33]
	v_mfma_f32_16x16x32_bf16 v[62:65], v[152:155], v[184:187], v[62:65]
	v_mfma_f32_16x16x32_bf16 v[22:25], v[160:163], v[184:187], v[22:25]
	v_mfma_f32_16x16x32_bf16 v[98:101], v[152:155], v[226:229], v[98:101]
	v_mfma_f32_16x16x32_bf16 v[50:53], v[160:163], v[226:229], v[50:53]
	s_barrier
	s_setprio 0
	s_add_i32 s34, s31, s45
	v_lshl_add_u64 v[192:193], s[84:85], 0, v[208:209]
	s_mov_b32 m0, s34
	ds_read_b128 v[164:167], v242 offset:16384
	ds_read_b128 v[168:171], v242 offset:17408
	ds_read_b128 v[172:175], v242 offset:18432
	ds_read_b128 v[176:179], v242 offset:19456
	ds_read_b128 v[180:183], v242 offset:20480
	ds_read_b128 v[184:187], v242 offset:21504
	ds_read_b128 v[188:191], v242 offset:22528
	ds_read_b128 v[226:229], v242 offset:23552
	global_load_lds_dwordx4 v[192:193], off
	s_add_i32 m0, s34, 0x2000
	s_add_u32 s34, s84, 0x100000
	v_lshl_add_u64 v[194:195], s[84:85], 0, v[212:213]
	s_addc_u32 s35, s85, 0
	s_add_i32 s50, s52, s45
	global_load_lds_dwordx4 v[194:195], off
	v_lshl_add_u64 v[230:231], s[34:35], 0, v[208:209]
	s_mov_b32 m0, s50
	v_lshl_add_u64 v[232:233], s[86:87], 0, v[210:211]
	global_load_lds_dwordx4 v[230:231], off
	v_lshl_add_u64 v[230:231], s[34:35], 0, v[212:213]
	s_add_i32 m0, s50, 0x2000
	s_nop 0
	global_load_lds_dwordx4 v[230:231], off
	v_lshl_add_u64 v[230:231], s[86:87], 0, v[206:207]
	s_mov_b32 m0, s28
	s_nop 0
	global_load_lds_dwordx4 v[230:231], off
	s_mov_b32 m0, s29
	s_nop 0
	global_load_lds_dwordx4 v[232:233], off
	s_waitcnt vmcnt(8)
	s_waitcnt lgkmcnt(0)
	s_setprio 1
	s_barrier
; #define PG8_STAGE(bufoff, gbase, voff) do { _Pragma("unroll") for (int _i = 0; _i < 2; ++_i) \
;         __builtin_amdgcn_global_load_lds((const unsigned*)((const char*)(gbase) + (voff)[_i]), (PG8_LAS unsigned*)(lds + (bufoff) + ldsw + _i * 8192), 16, 0, 0); } while (0)
; #define PG8_LDA(dst, b, h) do { _Pragma("unroll") for (int m = 0; m < 4; ++m) _Pragma("unroll") for (int k = 0; k < 2; ++k) dst[m][k] = *(const PG8_LAS bf16x8*)(lds + PG8_SA(b, h) + aoff + m * 2048 + k * 1024); } while (0)
; #define PG8_LDB(dst, b, h) do { _Pragma("unroll") for (int n = 0; n < 2; ++n) _Pragma("unroll") for (int k = 0; k < 2; ++k) dst[n][k] = *(const PG8_LAS bf16x8*)(lds + PG8_SB(b, h) + boff + n * 2048 + k * 1024); } while (0)
; #define PG8_MMA(ai, bj, At, Bt) do { __builtin_amdgcn_s_setprio(1); _Pragma("unroll") for (int m = 0; m < 4; ++m) _Pragma("unroll") for (int n = 0; n < 2; ++n) _Pragma("unroll") for (int k = 0; k < 2; ++k) \
;         acc[ai][bj][m][n] = __builtin_amdgcn_mfma_f32_16x16x32_bf16(Bt[n][k], At[m][k], acc[ai][bj][m][n], 0, 0, 0); __builtin_amdgcn_s_setprio(0); } while (0)
; #define PG8_WAIT_V(n) asm volatile("s_waitcnt vmcnt(" #n ")" ::: "memory")
; #define PG8_WAIT_L(n) asm volatile("s_waitcnt lgkmcnt(" #n ")" ::: "memory")
; #define PG8_BAR __builtin_amdgcn_s_barrier()
; #define PG8_SCHED __builtin_amdgcn_sched_barrier(0)
; template <class Epi, class Sched, bool ALIGN_EPI = false, bool SP2 = false>
; __device__ __forceinline__ void gemm_phase(PG8_LAS unsigned char* lds, const Gemm g, const Sched& S, const Epi& E) {
;     ...
;             PG8_WAIT_V(8); PG8_WAIT_L(0); PG8_BAR; PG8_MMA(1, 0, At, B0); PG8_MMA(1, 1, At, B1); PG8_BAR; PG8_SCHED;
;             PG8_LDB(B0, 1, 0); PG8_LDB(B1, 1, 1); PG8_SCHED; PG8_LDA(At, 1, 0); PG8_STAGE(PG8_SA(0, 1), a2 + hstep, voffA);
;             PG8_WAIT_V(8); PG8_WAIT_L(0); PG8_BAR; PG8_MMA(0, 0, At, B0); PG8_MMA(0, 1, At, B1); PG8_BAR; PG8_SCHED;
	v_mfma_f32_16x16x32_bf16 v[78:81], v[132:135], v[164:167], v[78:81]
	v_mfma_f32_16x16x32_bf16 v[14:17], v[140:143], v[164:167], v[14:17]
	v_mfma_f32_16x16x32_bf16 v[66:69], v[132:135], v[172:175], v[66:69]
	v_mfma_f32_16x16x32_bf16 v[94:97], v[140:143], v[172:175], v[94:97]
	v_mfma_f32_16x16x32_bf16 v[70:73], v[132:135], v[180:183], v[70:73]
	v_mfma_f32_16x16x32_bf16 v[90:93], v[140:143], v[180:183], v[90:93]
	v_mfma_f32_16x16x32_bf16 v[74:77], v[132:135], v[188:191], v[74:77]
	v_mfma_f32_16x16x32_bf16 v[10:13], v[140:143], v[188:191], v[10:13]
	v_mfma_f32_16x16x32_bf16 v[78:81], v[136:139], v[168:171], v[78:81]
	v_mfma_f32_16x16x32_bf16 v[14:17], v[144:147], v[168:171], v[14:17]
	v_mfma_f32_16x16x32_bf16 v[66:69], v[136:139], v[176:179], v[66:69]
	v_mfma_f32_16x16x32_bf16 v[94:97], v[144:147], v[176:179], v[94:97]
	v_mfma_f32_16x16x32_bf16 v[70:73], v[136:139], v[184:187], v[70:73]
	v_mfma_f32_16x16x32_bf16 v[90:93], v[144:147], v[184:187], v[90:93]
	v_mfma_f32_16x16x32_bf16 v[74:77], v[136:139], v[226:229], v[74:77]
	v_mfma_f32_16x16x32_bf16 v[10:13], v[144:147], v[226:229], v[10:13]
	s_setprio 0
	s_setprio 1
	v_mfma_f32_16x16x32_bf16 v[42:45], v[148:151], v[164:167], v[42:45]
	v_mfma_f32_16x16x32_bf16 v[2:5], v[156:159], v[164:167], v[2:5]
	v_mfma_f32_16x16x32_bf16 v[34:37], v[148:151], v[172:175], v[34:37]
	v_mfma_f32_16x16x32_bf16 v[6:9], v[156:159], v[172:175], v[6:9]
	v_mfma_f32_16x16x32_bf16 v[86:89], v[148:151], v[180:183], v[86:89]
	v_mfma_f32_16x16x32_bf16 v[26:29], v[156:159], v[180:183], v[26:29]
	v_mfma_f32_16x16x32_bf16 v[82:85], v[148:151], v[188:191], v[82:85]
	v_mfma_f32_16x16x32_bf16 v[18:21], v[156:159], v[188:191], v[18:21]
	v_mfma_f32_16x16x32_bf16 v[42:45], v[152:155], v[168:171], v[42:45]
	v_mfma_f32_16x16x32_bf16 v[2:5], v[160:163], v[168:171], v[2:5]
	v_mfma_f32_16x16x32_bf16 v[34:37], v[152:155], v[176:179], v[34:37]
	v_mfma_f32_16x16x32_bf16 v[6:9], v[160:163], v[176:179], v[6:9]
	v_mfma_f32_16x16x32_bf16 v[86:89], v[152:155], v[184:187], v[86:89]
	v_mfma_f32_16x16x32_bf16 v[26:29], v[160:163], v[184:187], v[26:29]
	v_mfma_f32_16x16x32_bf16 v[82:85], v[152:155], v[226:229], v[82:85]
	v_mfma_f32_16x16x32_bf16 v[18:21], v[160:163], v[226:229], v[18:21]
	s_barrier
	s_setprio 0
	s_add_i32 s50, 0, 0x18000
	s_add_i32 s56, 0, 0x1c000
	v_add_u32_e32 v144, s50, v201
	v_add_u32_e32 v160, s56, v201
	ds_read_b128 v[132:135], v144
	ds_read_b128 v[136:139], v144 offset:1024
	ds_read_b128 v[140:143], v144 offset:2048
	ds_read_b128 v[144:147], v144 offset:3072
	ds_read_b128 v[148:151], v160
	ds_read_b128 v[152:155], v160 offset:1024
	ds_read_b128 v[156:159], v160 offset:2048
	ds_read_b128 v[160:163], v160 offset:3072
	s_add_u32 s34, s86, 0x100000
	s_addc_u32 s35, s87, 0
	s_mov_b32 m0, s16
	v_lshl_add_u64 v[246:247], s[34:35], 0, v[206:207]
	ds_read_b128 v[164:167], v242 offset:32768
	ds_read_b128 v[168:171], v242 offset:33792
	ds_read_b128 v[172:175], v242 offset:34816
	ds_read_b128 v[176:179], v242 offset:35840
	ds_read_b128 v[180:183], v242 offset:36864
	ds_read_b128 v[184:187], v242 offset:37888
	ds_read_b128 v[188:191], v242 offset:38912
	ds_read_b128 v[226:229], v242 offset:39936
	global_load_lds_dwordx4 v[246:247], off
	v_lshl_add_u64 v[246:247], s[34:35], 0, v[210:211]
	s_mov_b32 m0, s17
	s_nop 0
	global_load_lds_dwordx4 v[246:247], off
	s_waitcnt vmcnt(8)
	s_waitcnt lgkmcnt(0)
	s_setprio 1
	s_barrier
	v_mfma_f32_16x16x32_bf16 v[126:129], v[132:135], v[164:167], v[126:129]
	v_mfma_f32_16x16x32_bf16 v[46:49], v[140:143], v[164:167], v[46:49]
	v_mfma_f32_16x16x32_bf16 v[118:121], v[132:135], v[172:175], v[118:121]
	v_mfma_f32_16x16x32_bf16 v[122:125], v[140:143], v[172:175], v[122:125]
	v_mfma_f32_16x16x32_bf16 v[110:113], v[132:135], v[180:183], v[110:113]
	v_mfma_f32_16x16x32_bf16 v[114:117], v[140:143], v[180:183], v[114:117]
	v_mfma_f32_16x16x32_bf16 v[102:105], v[132:135], v[188:191], v[102:105]
	v_mfma_f32_16x16x32_bf16 v[106:109], v[140:143], v[188:191], v[106:109]
	v_mfma_f32_16x16x32_bf16 v[126:129], v[136:139], v[168:171], v[126:129]
	v_mfma_f32_16x16x32_bf16 v[46:49], v[144:147], v[168:171], v[46:49]
	v_mfma_f32_16x16x32_bf16 v[118:121], v[136:139], v[176:179], v[118:121]
	v_mfma_f32_16x16x32_bf16 v[122:125], v[144:147], v[176:179], v[122:125]
	v_mfma_f32_16x16x32_bf16 v[110:113], v[136:139], v[184:187], v[110:113]
	v_mfma_f32_16x16x32_bf16 v[114:117], v[144:147], v[184:187], v[114:117]
	v_mfma_f32_16x16x32_bf16 v[102:105], v[136:139], v[226:229], v[102:105]
	v_mfma_f32_16x16x32_bf16 v[106:109], v[144:147], v[226:229], v[106:109]
	s_setprio 0
	s_setprio 1
	v_mfma_f32_16x16x32_bf16 v[54:57], v[148:151], v[164:167], v[54:57]
	v_mfma_f32_16x16x32_bf16 v[38:41], v[156:159], v[164:167], v[38:41]
	v_mfma_f32_16x16x32_bf16 v[58:61], v[148:151], v[172:175], v[58:61]
	v_mfma_f32_16x16x32_bf16 v[30:33], v[156:159], v[172:175], v[30:33]
	v_mfma_f32_16x16x32_bf16 v[62:65], v[148:151], v[180:183], v[62:65]
	v_mfma_f32_16x16x32_bf16 v[22:25], v[156:159], v[180:183], v[22:25]
	v_mfma_f32_16x16x32_bf16 v[98:101], v[148:151], v[188:191], v[98:101]
	v_mfma_f32_16x16x32_bf16 v[50:53], v[156:159], v[188:191], v[50:53]
	v_mfma_f32_16x16x32_bf16 v[54:57], v[152:155], v[168:171], v[54:57]
	v_mfma_f32_16x16x32_bf16 v[38:41], v[160:163], v[168:171], v[38:41]
	v_mfma_f32_16x16x32_bf16 v[58:61], v[152:155], v[176:179], v[58:61]
	v_mfma_f32_16x16x32_bf16 v[30:33], v[160:163], v[176:179], v[30:33]
	v_mfma_f32_16x16x32_bf16 v[62:65], v[152:155], v[184:187], v[62:65]
	v_mfma_f32_16x16x32_bf16 v[22:25], v[160:163], v[184:187], v[22:25]
	v_mfma_f32_16x16x32_bf16 v[98:101], v[152:155], v[226:229], v[98:101]
	v_mfma_f32_16x16x32_bf16 v[50:53], v[160:163], v[226:229], v[50:53]
	s_barrier
; #define PG8_STAGE(bufoff, gbase, voff) do { _Pragma("unroll") for (int _i = 0; _i < 2; ++_i) \
;         __builtin_amdgcn_global_load_lds((const unsigned*)((const char*)(gbase) + (voff)[_i]), (PG8_LAS unsigned*)(lds + (bufoff) + ldsw + _i * 8192), 16, 0, 0); } while (0)
; #define PG8_LDA(dst, b, h) do { _Pragma("unroll") for (int m = 0; m < 4; ++m) _Pragma("unroll") for (int k = 0; k < 2; ++k) dst[m][k] = *(const PG8_LAS bf16x8*)(lds + PG8_SA(b, h) + aoff + m * 2048 + k * 1024); } while (0)
; #define PG8_MMA(ai, bj, At, Bt) do { __builtin_amdgcn_s_setprio(1); _Pragma("unroll") for (int m = 0; m < 4; ++m) _Pragma("unroll") for (int n = 0; n < 2; ++n) _Pragma("unroll") for (int k = 0; k < 2; ++k) \
;         acc[ai][bj][m][n] = __builtin_amdgcn_mfma_f32_16x16x32_bf16(Bt[n][k], At[m][k], acc[ai][bj][m][n], 0, 0, 0); __builtin_amdgcn_s_setprio(0); } while (0)
; #define PG8_WAIT_V(n) asm volatile("s_waitcnt vmcnt(" #n ")" ::: "memory")
; #define PG8_WAIT_L(n) asm volatile("s_waitcnt lgkmcnt(" #n ")" ::: "memory")
; #define PG8_BAR __builtin_amdgcn_s_barrier()
; #define PG8_SCHED __builtin_amdgcn_sched_barrier(0)
; template <class Epi, class Sched, bool ALIGN_EPI = false, bool SP2 = false>
; __device__ __forceinline__ void gemm_phase(PG8_LAS unsigned char* lds, const Gemm g, const Sched& S, const Epi& E) {
;     ...
;             PG8_LDA(At, 1, 1); PG8_STAGE(PG8_SB(1, 0), b3, voffB); PG8_STAGE(PG8_SB(1, 1), b3 + hstep, voffB); PG8_STAGE(PG8_SA(1, 0), a3, voffA);
;             PG8_WAIT_V(8); PG8_WAIT_L(0); PG8_BAR; PG8_MMA(1, 0, At, B0); PG8_MMA(1, 1, At, B1); PG8_BAR; PG8_SCHED;
	s_setprio 0
	s_add_i32 s34, s50, s45
	v_lshl_add_u64 v[192:193], v[192:193], 0, s[54:55]
	s_mov_b32 m0, s34
	ds_read_b128 v[164:167], v242 offset:49152
	ds_read_b128 v[168:171], v242 offset:50176
	ds_read_b128 v[172:175], v242 offset:51200
	ds_read_b128 v[176:179], v242 offset:52224
	ds_read_b128 v[180:183], v242 offset:53248
	ds_read_b128 v[184:187], v242 offset:54272
	ds_read_b128 v[188:191], v242 offset:55296
	ds_read_b128 v[226:229], v242 offset:56320
	global_load_lds_dwordx4 v[192:193], off
	s_add_i32 m0, s34, 0x2000
	s_add_u32 s34, s84, 0x100080
	v_lshl_add_u64 v[192:193], v[194:195], 0, s[54:55]
	s_addc_u32 s35, s85, 0
	s_add_i32 s50, s56, s45
	global_load_lds_dwordx4 v[192:193], off
	v_lshl_add_u64 v[192:193], s[34:35], 0, v[208:209]
	s_mov_b32 m0, s50
	s_nop 0
	global_load_lds_dwordx4 v[192:193], off
	v_lshl_add_u64 v[192:193], s[34:35], 0, v[212:213]
	s_add_i32 m0, s50, 0x2000
	s_nop 0
	global_load_lds_dwordx4 v[192:193], off
	v_lshl_add_u64 v[192:193], v[230:231], 0, s[54:55]
	s_mov_b32 m0, s39
	s_nop 0
	global_load_lds_dwordx4 v[192:193], off
	v_lshl_add_u64 v[192:193], v[232:233], 0, s[54:55]
	s_mov_b32 m0, s46
	s_nop 0
	global_load_lds_dwordx4 v[192:193], off
	s_waitcnt vmcnt(8)
	s_waitcnt lgkmcnt(0)
	s_setprio 1
	s_barrier
	v_mfma_f32_16x16x32_bf16 v[78:81], v[132:135], v[164:167], v[78:81]
	v_mfma_f32_16x16x32_bf16 v[14:17], v[140:143], v[164:167], v[14:17]
	v_mfma_f32_16x16x32_bf16 v[66:69], v[132:135], v[172:175], v[66:69]
	v_mfma_f32_16x16x32_bf16 v[94:97], v[140:143], v[172:175], v[94:97]
	v_mfma_f32_16x16x32_bf16 v[70:73], v[132:135], v[180:183], v[70:73]
	v_mfma_f32_16x16x32_bf16 v[90:93], v[140:143], v[180:183], v[90:93]
	v_mfma_f32_16x16x32_bf16 v[74:77], v[132:135], v[188:191], v[74:77]
	v_mfma_f32_16x16x32_bf16 v[10:13], v[140:143], v[188:191], v[10:13]
	v_mfma_f32_16x16x32_bf16 v[78:81], v[136:139], v[168:171], v[78:81]
	v_mfma_f32_16x16x32_bf16 v[14:17], v[144:147], v[168:171], v[14:17]
	v_mfma_f32_16x16x32_bf16 v[66:69], v[136:139], v[176:179], v[66:69]
	v_mfma_f32_16x16x32_bf16 v[94:97], v[144:147], v[176:179], v[94:97]
	v_mfma_f32_16x16x32_bf16 v[70:73], v[136:139], v[184:187], v[70:73]
	v_mfma_f32_16x16x32_bf16 v[90:93], v[144:147], v[184:187], v[90:93]
	v_mfma_f32_16x16x32_bf16 v[74:77], v[136:139], v[226:229], v[74:77]
	v_mfma_f32_16x16x32_bf16 v[10:13], v[144:147], v[226:229], v[10:13]
	s_setprio 0
	s_setprio 1
	v_mfma_f32_16x16x32_bf16 v[42:45], v[148:151], v[164:167], v[42:45]
	v_mfma_f32_16x16x32_bf16 v[2:5], v[156:159], v[164:167], v[2:5]
	v_mfma_f32_16x16x32_bf16 v[34:37], v[148:151], v[172:175], v[34:37]
	v_mfma_f32_16x16x32_bf16 v[6:9], v[156:159], v[172:175], v[6:9]
	v_mfma_f32_16x16x32_bf16 v[86:89], v[148:151], v[180:183], v[86:89]
	v_mfma_f32_16x16x32_bf16 v[26:29], v[156:159], v[180:183], v[26:29]
	v_mfma_f32_16x16x32_bf16 v[82:85], v[148:151], v[188:191], v[82:85]
	v_mfma_f32_16x16x32_bf16 v[18:21], v[156:159], v[188:191], v[18:21]
	v_mfma_f32_16x16x32_bf16 v[42:45], v[152:155], v[168:171], v[42:45]
	v_mfma_f32_16x16x32_bf16 v[2:5], v[160:163], v[168:171], v[2:5]
	v_mfma_f32_16x16x32_bf16 v[34:37], v[152:155], v[176:179], v[34:37]
	v_mfma_f32_16x16x32_bf16 v[6:9], v[160:163], v[176:179], v[6:9]
	v_mfma_f32_16x16x32_bf16 v[86:89], v[152:155], v[184:187], v[86:89]
	v_mfma_f32_16x16x32_bf16 v[26:29], v[160:163], v[184:187], v[26:29]
	v_mfma_f32_16x16x32_bf16 v[82:85], v[152:155], v[226:229], v[82:85]
	v_mfma_f32_16x16x32_bf16 v[18:21], v[160:163], v[226:229], v[18:21]
	s_barrier
	s_setprio 0
	s_add_i32 s89, s89, 2
	s_add_u32 s82, s82, 0x100
	s_addc_u32 s83, s83, 0
	s_add_u32 s79, s79, 0x100
	s_addc_u32 s88, s88, 0
	s_cmp_gt_u32 s89, 61
	s_cbranch_scc1 .LBB0_1490

; #define PG8_STAGE(bufoff, gbase, voff) do { _Pragma("unroll") for (int _i = 0; _i < 2; ++_i) \
;         __builtin_amdgcn_global_load_lds((const unsigned*)((const char*)(gbase) + (voff)[_i]), (PG8_LAS unsigned*)(lds + (bufoff) + ldsw + _i * 8192), 16, 0, 0); } while (0)
; #define PG8_LDA(dst, b, h) do { _Pragma("unroll") for (int m = 0; m < 4; ++m) _Pragma("unroll") for (int k = 0; k < 2; ++k) dst[m][k] = *(const PG8_LAS bf16x8*)(lds + PG8_SA(b, h) + aoff + m * 2048 + k * 1024); } while (0)
; #define PG8_LDB(dst, b, h) do { _Pragma("unroll") for (int n = 0; n < 2; ++n) _Pragma("unroll") for (int k = 0; k < 2; ++k) dst[n][k] = *(const PG8_LAS bf16x8*)(lds + PG8_SB(b, h) + boff + n * 2048 + k * 1024); } while (0)
; #define PG8_MMA(ai, bj, At, Bt) do { __builtin_amdgcn_s_setprio(1); _Pragma("unroll") for (int m = 0; m < 4; ++m) _Pragma("unroll") for (int n = 0; n < 2; ++n) _Pragma("unroll") for (int k = 0; k < 2; ++k) \
;         acc[ai][bj][m][n] = __builtin_amdgcn_mfma_f32_16x16x32_bf16(Bt[n][k], At[m][k], acc[ai][bj][m][n], 0, 0, 0); __builtin_amdgcn_s_setprio(0); } while (0)
; #define PG8_WAIT_V(n) asm volatile("s_waitcnt vmcnt(" #n ")" ::: "memory")
; #define PG8_WAIT_L(n) asm volatile("s_waitcnt lgkmcnt(" #n ")" ::: "memory")
; #define PG8_BAR __builtin_amdgcn_s_barrier()
; #define PG8_SCHED __builtin_amdgcn_sched_barrier(0)
; template <class Epi, class Sched, bool ALIGN_EPI = false, bool SP2 = false>
; __device__ __forceinline__ void gemm_phase(PG8_LAS unsigned char* lds, const Gemm g, const Sched& S, const Epi& E) {
;     ...
;             PG8_LDB(B0, 0, 0); PG8_LDB(B1, 0, 1); PG8_SCHED; PG8_LDA(At, 0, 0); PG8_STAGE(PG8_SA(1, 1), a1 + hstep, voffA);
;             PG8_WAIT_V(8); PG8_WAIT_L(0); PG8_BAR; PG8_MMA(0, 0, At, B0); PG8_MMA(0, 1, At, B1); PG8_BAR; PG8_SCHED;
;             PG8_LDA(At, 0, 1); PG8_STAGE(PG8_SB(0, 0), b2, voffB); PG8_STAGE(PG8_SB(0, 1), b2 + hstep, voffB); PG8_STAGE(PG8_SA(0, 0), a2, voffA);
;             PG8_WAIT_V(8); PG8_WAIT_L(0); PG8_BAR; PG8_MMA(1, 0, At, B0); PG8_MMA(1, 1, At, B1); PG8_BAR; PG8_SCHED;
.LBB0_1731:
	ds_read_b128 v[170:173], v166
	ds_read_b128 v[174:177], v166 offset:1024
	ds_read_b128 v[178:181], v166 offset:2048
	ds_read_b128 v[182:185], v166 offset:3072
	ds_read_b128 v[186:189], v167
	ds_read_b128 v[190:193], v167 offset:1024
	ds_read_b128 v[196:199], v167 offset:2048
	ds_read_b128 v[202:205], v167 offset:3072
	s_add_u32 s48, s40, 0x100
	s_addc_u32 s49, s41, 0
	s_cmpk_eq_i32 s56, 0xa8
	s_cselect_b32 s53, s7, s49
	s_cselect_b32 s52, s6, s48
	s_cselect_b32 s51, s39, s55
	s_cselect_b32 s50, s38, s54
	v_lshl_add_u64 v[146:147], s[40:41], 0, v[138:139]
	s_add_i32 m0, s16, 0xc000
	ds_read_b128 v[206:209], v168
	ds_read_b128 v[210:213], v168 offset:1024
	ds_read_b128 v[214:217], v168 offset:2048
	ds_read_b128 v[218:221], v168 offset:3072
	ds_read_b128 v[222:225], v168 offset:4096
	ds_read_b128 v[226:229], v168 offset:5120
	ds_read_b128 v[230:233], v168 offset:6144
	ds_read_b128 v[234:237], v168 offset:7168
	global_load_lds_dwordx4 v[146:147], off
	v_lshl_add_u64 v[146:147], s[40:41], 0, v[140:141]
	s_add_i32 m0, s16, 0xe000
	s_nop 0
	global_load_lds_dwordx4 v[146:147], off
	s_waitcnt vmcnt(8)
	s_waitcnt lgkmcnt(0)
	s_setprio 1
	s_barrier
	v_mfma_f32_16x16x32_bf16 v[126:129], v[170:173], v[206:209], v[126:129]
	v_mfma_f32_16x16x32_bf16 v[122:125], v[178:181], v[206:209], v[122:125]
	v_mfma_f32_16x16x32_bf16 v[110:113], v[170:173], v[214:217], v[110:113]
	v_mfma_f32_16x16x32_bf16 v[106:109], v[178:181], v[214:217], v[106:109]
	v_mfma_f32_16x16x32_bf16 v[94:97], v[170:173], v[222:225], v[94:97]
	v_mfma_f32_16x16x32_bf16 v[90:93], v[178:181], v[222:225], v[90:93]
	v_mfma_f32_16x16x32_bf16 v[78:81], v[170:173], v[230:233], v[78:81]
	v_mfma_f32_16x16x32_bf16 v[74:77], v[178:181], v[230:233], v[74:77]
	v_mfma_f32_16x16x32_bf16 v[126:129], v[174:177], v[210:213], v[126:129]
	v_mfma_f32_16x16x32_bf16 v[122:125], v[182:185], v[210:213], v[122:125]
	v_mfma_f32_16x16x32_bf16 v[110:113], v[174:177], v[218:221], v[110:113]
	v_mfma_f32_16x16x32_bf16 v[106:109], v[182:185], v[218:221], v[106:109]
	v_mfma_f32_16x16x32_bf16 v[94:97], v[174:177], v[226:229], v[94:97]
	v_mfma_f32_16x16x32_bf16 v[90:93], v[182:185], v[226:229], v[90:93]
	v_mfma_f32_16x16x32_bf16 v[78:81], v[174:177], v[234:237], v[78:81]
	v_mfma_f32_16x16x32_bf16 v[74:77], v[182:185], v[234:237], v[74:77]
	s_setprio 0
	s_setprio 1
	v_mfma_f32_16x16x32_bf16 v[118:121], v[186:189], v[206:209], v[118:121]
	v_mfma_f32_16x16x32_bf16 v[114:117], v[196:199], v[206:209], v[114:117]
	v_mfma_f32_16x16x32_bf16 v[102:105], v[186:189], v[214:217], v[102:105]
	v_mfma_f32_16x16x32_bf16 v[98:101], v[196:199], v[214:217], v[98:101]
	v_mfma_f32_16x16x32_bf16 v[86:89], v[186:189], v[222:225], v[86:89]
	v_mfma_f32_16x16x32_bf16 v[82:85], v[196:199], v[222:225], v[82:85]
	v_mfma_f32_16x16x32_bf16 v[70:73], v[186:189], v[230:233], v[70:73]
	v_mfma_f32_16x16x32_bf16 v[66:69], v[196:199], v[230:233], v[66:69]
	v_mfma_f32_16x16x32_bf16 v[118:121], v[190:193], v[210:213], v[118:121]
	v_mfma_f32_16x16x32_bf16 v[114:117], v[202:205], v[210:213], v[114:117]
	v_mfma_f32_16x16x32_bf16 v[102:105], v[190:193], v[218:221], v[102:105]
	v_mfma_f32_16x16x32_bf16 v[98:101], v[202:205], v[218:221], v[98:101]
	v_mfma_f32_16x16x32_bf16 v[86:89], v[190:193], v[226:229], v[86:89]
	v_mfma_f32_16x16x32_bf16 v[82:85], v[202:205], v[226:229], v[82:85]
	v_mfma_f32_16x16x32_bf16 v[70:73], v[190:193], v[234:237], v[70:73]
	v_mfma_f32_16x16x32_bf16 v[66:69], v[202:205], v[234:237], v[66:69]
	s_barrier
	s_setprio 0
	s_add_i32 s40, s31, s3
	v_lshl_add_u64 v[146:147], s[50:51], 0, v[132:133]
	s_mov_b32 m0, s40
	ds_read_b128 v[206:209], v168 offset:16384
	ds_read_b128 v[210:213], v168 offset:17408
	ds_read_b128 v[214:217], v168 offset:18432
	ds_read_b128 v[218:221], v168 offset:19456
	ds_read_b128 v[222:225], v168 offset:20480
	ds_read_b128 v[226:229], v168 offset:21504
	ds_read_b128 v[230:233], v168 offset:22528
	ds_read_b128 v[234:237], v168 offset:23552
	global_load_lds_dwordx4 v[146:147], off
	s_add_i32 m0, s40, 0x2000
	s_add_u32 s40, s50, 0x2b0000
	v_lshl_add_u64 v[194:195], s[50:51], 0, v[136:137]
	s_addc_u32 s41, s51, 0
	s_add_i32 s57, s35, s3
	global_load_lds_dwordx4 v[194:195], off
	v_lshl_add_u64 v[238:239], s[40:41], 0, v[132:133]
	s_mov_b32 m0, s57
	v_lshl_add_u64 v[240:241], s[52:53], 0, v[134:135]
	global_load_lds_dwordx4 v[238:239], off
	v_lshl_add_u64 v[238:239], s[40:41], 0, v[136:137]
	s_add_i32 m0, s57, 0x2000
	s_nop 0
	global_load_lds_dwordx4 v[238:239], off
	v_lshl_add_u64 v[238:239], s[52:53], 0, v[130:131]
	s_mov_b32 m0, s16
	s_nop 0
	global_load_lds_dwordx4 v[238:239], off
	s_mov_b32 m0, s17
	s_nop 0
	global_load_lds_dwordx4 v[240:241], off
	s_waitcnt vmcnt(8)
	s_waitcnt lgkmcnt(0)
	s_setprio 1
	s_barrier
; #define PG8_STAGE(bufoff, gbase, voff) do { _Pragma("unroll") for (int _i = 0; _i < 2; ++_i) \
;         __builtin_amdgcn_global_load_lds((const unsigned*)((const char*)(gbase) + (voff)[_i]), (PG8_LAS unsigned*)(lds + (bufoff) + ldsw + _i * 8192), 16, 0, 0); } while (0)
; #define PG8_LDA(dst, b, h) do { _Pragma("unroll") for (int m = 0; m < 4; ++m) _Pragma("unroll") for (int k = 0; k < 2; ++k) dst[m][k] = *(const PG8_LAS bf16x8*)(lds + PG8_SA(b, h) + aoff + m * 2048 + k * 1024); } while (0)
; #define PG8_LDB(dst, b, h) do { _Pragma("unroll") for (int n = 0; n < 2; ++n) _Pragma("unroll") for (int k = 0; k < 2; ++k) dst[n][k] = *(const PG8_LAS bf16x8*)(lds + PG8_SB(b, h) + boff + n * 2048 + k * 1024); } while (0)
; #define PG8_MMA(ai, bj, At, Bt) do { __builtin_amdgcn_s_setprio(1); _Pragma("unroll") for (int m = 0; m < 4; ++m) _Pragma("unroll") for (int n = 0; n < 2; ++n) _Pragma("unroll") for (int k = 0; k < 2; ++k) \
;         acc[ai][bj][m][n] = __builtin_amdgcn_mfma_f32_16x16x32_bf16(Bt[n][k], At[m][k], acc[ai][bj][m][n], 0, 0, 0); __builtin_amdgcn_s_setprio(0); } while (0)
; #define PG8_WAIT_V(n) asm volatile("s_waitcnt vmcnt(" #n ")" ::: "memory")
; #define PG8_WAIT_L(n) asm volatile("s_waitcnt lgkmcnt(" #n ")" ::: "memory")
; #define PG8_BAR __builtin_amdgcn_s_barrier()
; #define PG8_SCHED __builtin_amdgcn_sched_barrier(0)
; template <class Epi, class Sched, bool ALIGN_EPI = false, bool SP2 = false>
; __device__ __forceinline__ void gemm_phase(PG8_LAS unsigned char* lds, const Gemm g, const Sched& S, const Epi& E) {
;     ...
;             PG8_WAIT_V(8); PG8_WAIT_L(0); PG8_BAR; PG8_MMA(1, 0, At, B0); PG8_MMA(1, 1, At, B1); PG8_BAR; PG8_SCHED;
;             PG8_LDB(B0, 1, 0); PG8_LDB(B1, 1, 1); PG8_SCHED; PG8_LDA(At, 1, 0); PG8_STAGE(PG8_SA(0, 1), a2 + hstep, voffA);
;             PG8_WAIT_V(8); PG8_WAIT_L(0); PG8_BAR; PG8_MMA(0, 0, At, B0); PG8_MMA(0, 1, At, B1); PG8_BAR; PG8_SCHED;
	v_mfma_f32_16x16x32_bf16 v[62:65], v[170:173], v[206:209], v[62:65]
	v_mfma_f32_16x16x32_bf16 v[58:61], v[178:181], v[206:209], v[58:61]
	v_mfma_f32_16x16x32_bf16 v[46:49], v[170:173], v[214:217], v[46:49]
	v_mfma_f32_16x16x32_bf16 v[42:45], v[178:181], v[214:217], v[42:45]
	v_mfma_f32_16x16x32_bf16 v[30:33], v[170:173], v[222:225], v[30:33]
	v_mfma_f32_16x16x32_bf16 v[26:29], v[178:181], v[222:225], v[26:29]
	v_mfma_f32_16x16x32_bf16 v[14:17], v[170:173], v[230:233], v[14:17]
	v_mfma_f32_16x16x32_bf16 v[10:13], v[178:181], v[230:233], v[10:13]
	v_mfma_f32_16x16x32_bf16 v[62:65], v[174:177], v[210:213], v[62:65]
	v_mfma_f32_16x16x32_bf16 v[58:61], v[182:185], v[210:213], v[58:61]
	v_mfma_f32_16x16x32_bf16 v[46:49], v[174:177], v[218:221], v[46:49]
	v_mfma_f32_16x16x32_bf16 v[42:45], v[182:185], v[218:221], v[42:45]
	v_mfma_f32_16x16x32_bf16 v[30:33], v[174:177], v[226:229], v[30:33]
	v_mfma_f32_16x16x32_bf16 v[26:29], v[182:185], v[226:229], v[26:29]
	v_mfma_f32_16x16x32_bf16 v[14:17], v[174:177], v[234:237], v[14:17]
	v_mfma_f32_16x16x32_bf16 v[10:13], v[182:185], v[234:237], v[10:13]
	s_setprio 0
	s_setprio 1
	v_mfma_f32_16x16x32_bf16 v[54:57], v[186:189], v[206:209], v[54:57]
	v_mfma_f32_16x16x32_bf16 v[50:53], v[196:199], v[206:209], v[50:53]
	v_mfma_f32_16x16x32_bf16 v[38:41], v[186:189], v[214:217], v[38:41]
	v_mfma_f32_16x16x32_bf16 v[34:37], v[196:199], v[214:217], v[34:37]
	v_mfma_f32_16x16x32_bf16 v[22:25], v[186:189], v[222:225], v[22:25]
	v_mfma_f32_16x16x32_bf16 v[18:21], v[196:199], v[222:225], v[18:21]
	v_mfma_f32_16x16x32_bf16 v[6:9], v[186:189], v[230:233], v[6:9]
	v_mfma_f32_16x16x32_bf16 v[2:5], v[196:199], v[230:233], v[2:5]
	v_mfma_f32_16x16x32_bf16 v[54:57], v[190:193], v[210:213], v[54:57]
	v_mfma_f32_16x16x32_bf16 v[50:53], v[202:205], v[210:213], v[50:53]
	v_mfma_f32_16x16x32_bf16 v[38:41], v[190:193], v[218:221], v[38:41]
	v_mfma_f32_16x16x32_bf16 v[34:37], v[202:205], v[218:221], v[34:37]
	v_mfma_f32_16x16x32_bf16 v[22:25], v[190:193], v[226:229], v[22:25]
	v_mfma_f32_16x16x32_bf16 v[18:21], v[202:205], v[226:229], v[18:21]
	v_mfma_f32_16x16x32_bf16 v[6:9], v[190:193], v[234:237], v[6:9]
	v_mfma_f32_16x16x32_bf16 v[2:5], v[202:205], v[234:237], v[2:5]
	s_barrier
	s_setprio 0
	s_add_i32 s57, 0, 0x18000
	v_add_u32_e32 v169, s57, v148
	s_add_i32 s58, 0, 0x1c000
	ds_read_b128 v[170:173], v169
	ds_read_b128 v[174:177], v169 offset:1024
	ds_read_b128 v[178:181], v169 offset:2048
	ds_read_b128 v[182:185], v169 offset:3072
	v_add_u32_e32 v169, s58, v148
	ds_read_b128 v[186:189], v169
	ds_read_b128 v[190:193], v169 offset:1024
	ds_read_b128 v[196:199], v169 offset:2048
	ds_read_b128 v[202:205], v169 offset:3072
	s_add_u32 s40, s52, 0x2b0000
	s_addc_u32 s41, s53, 0
	s_mov_b32 m0, s25
	v_lshl_add_u64 v[242:243], s[40:41], 0, v[130:131]
	ds_read_b128 v[206:209], v168 offset:32768
	ds_read_b128 v[210:213], v168 offset:33792
	ds_read_b128 v[214:217], v168 offset:34816
	ds_read_b128 v[218:221], v168 offset:35840
	ds_read_b128 v[222:225], v168 offset:36864
	ds_read_b128 v[226:229], v168 offset:37888
	ds_read_b128 v[230:233], v168 offset:38912
	ds_read_b128 v[234:237], v168 offset:39936
	global_load_lds_dwordx4 v[242:243], off
	v_lshl_add_u64 v[242:243], s[40:41], 0, v[134:135]
	s_mov_b32 m0, s26
	s_nop 0
	global_load_lds_dwordx4 v[242:243], off
	s_waitcnt vmcnt(8)
	s_waitcnt lgkmcnt(0)
	s_setprio 1
	s_barrier
	v_mfma_f32_16x16x32_bf16 v[126:129], v[170:173], v[206:209], v[126:129]
	v_mfma_f32_16x16x32_bf16 v[122:125], v[178:181], v[206:209], v[122:125]
	v_mfma_f32_16x16x32_bf16 v[110:113], v[170:173], v[214:217], v[110:113]
	v_mfma_f32_16x16x32_bf16 v[106:109], v[178:181], v[214:217], v[106:109]
	v_mfma_f32_16x16x32_bf16 v[94:97], v[170:173], v[222:225], v[94:97]
	v_mfma_f32_16x16x32_bf16 v[90:93], v[178:181], v[222:225], v[90:93]
	v_mfma_f32_16x16x32_bf16 v[78:81], v[170:173], v[230:233], v[78:81]
	v_mfma_f32_16x16x32_bf16 v[74:77], v[178:181], v[230:233], v[74:77]
	v_mfma_f32_16x16x32_bf16 v[126:129], v[174:177], v[210:213], v[126:129]
	v_mfma_f32_16x16x32_bf16 v[122:125], v[182:185], v[210:213], v[122:125]
	v_mfma_f32_16x16x32_bf16 v[110:113], v[174:177], v[218:221], v[110:113]
	v_mfma_f32_16x16x32_bf16 v[106:109], v[182:185], v[218:221], v[106:109]
	v_mfma_f32_16x16x32_bf16 v[94:97], v[174:177], v[226:229], v[94:97]
	v_mfma_f32_16x16x32_bf16 v[90:93], v[182:185], v[226:229], v[90:93]
	v_mfma_f32_16x16x32_bf16 v[78:81], v[174:177], v[234:237], v[78:81]
	v_mfma_f32_16x16x32_bf16 v[74:77], v[182:185], v[234:237], v[74:77]
	s_setprio 0
	s_setprio 1
	v_mfma_f32_16x16x32_bf16 v[118:121], v[186:189], v[206:209], v[118:121]
	v_mfma_f32_16x16x32_bf16 v[114:117], v[196:199], v[206:209], v[114:117]
	v_mfma_f32_16x16x32_bf16 v[102:105], v[186:189], v[214:217], v[102:105]
	v_mfma_f32_16x16x32_bf16 v[98:101], v[196:199], v[214:217], v[98:101]
	v_mfma_f32_16x16x32_bf16 v[86:89], v[186:189], v[222:225], v[86:89]
	v_mfma_f32_16x16x32_bf16 v[82:85], v[196:199], v[222:225], v[82:85]
	v_mfma_f32_16x16x32_bf16 v[70:73], v[186:189], v[230:233], v[70:73]
	v_mfma_f32_16x16x32_bf16 v[66:69], v[196:199], v[230:233], v[66:69]
	v_mfma_f32_16x16x32_bf16 v[118:121], v[190:193], v[210:213], v[118:121]
	v_mfma_f32_16x16x32_bf16 v[114:117], v[202:205], v[210:213], v[114:117]
	v_mfma_f32_16x16x32_bf16 v[102:105], v[190:193], v[218:221], v[102:105]
	v_mfma_f32_16x16x32_bf16 v[98:101], v[202:205], v[218:221], v[98:101]
	v_mfma_f32_16x16x32_bf16 v[86:89], v[190:193], v[226:229], v[86:89]
	v_mfma_f32_16x16x32_bf16 v[82:85], v[202:205], v[226:229], v[82:85]
	v_mfma_f32_16x16x32_bf16 v[70:73], v[190:193], v[234:237], v[70:73]
	v_mfma_f32_16x16x32_bf16 v[66:69], v[202:205], v[234:237], v[66:69]
	s_barrier
; #define PG8_STAGE(bufoff, gbase, voff) do { _Pragma("unroll") for (int _i = 0; _i < 2; ++_i) \
;         __builtin_amdgcn_global_load_lds((const unsigned*)((const char*)(gbase) + (voff)[_i]), (PG8_LAS unsigned*)(lds + (bufoff) + ldsw + _i * 8192), 16, 0, 0); } while (0)
; #define PG8_LDA(dst, b, h) do { _Pragma("unroll") for (int m = 0; m < 4; ++m) _Pragma("unroll") for (int k = 0; k < 2; ++k) dst[m][k] = *(const PG8_LAS bf16x8*)(lds + PG8_SA(b, h) + aoff + m * 2048 + k * 1024); } while (0)
; #define PG8_MMA(ai, bj, At, Bt) do { __builtin_amdgcn_s_setprio(1); _Pragma("unroll") for (int m = 0; m < 4; ++m) _Pragma("unroll") for (int n = 0; n < 2; ++n) _Pragma("unroll") for (int k = 0; k < 2; ++k) \
;         acc[ai][bj][m][n] = __builtin_amdgcn_mfma_f32_16x16x32_bf16(Bt[n][k], At[m][k], acc[ai][bj][m][n], 0, 0, 0); __builtin_amdgcn_s_setprio(0); } while (0)
; #define PG8_WAIT_V(n) asm volatile("s_waitcnt vmcnt(" #n ")" ::: "memory")
; #define PG8_WAIT_L(n) asm volatile("s_waitcnt lgkmcnt(" #n ")" ::: "memory")
; #define PG8_BAR __builtin_amdgcn_s_barrier()
; #define PG8_SCHED __builtin_amdgcn_sched_barrier(0)
; template <class Epi, class Sched, bool ALIGN_EPI = false, bool SP2 = false>
; __device__ __forceinline__ void gemm_phase(PG8_LAS unsigned char* lds, const Gemm g, const Sched& S, const Epi& E) {
;     ...
;             PG8_LDA(At, 1, 1); PG8_STAGE(PG8_SB(1, 0), b3, voffB); PG8_STAGE(PG8_SB(1, 1), b3 + hstep, voffB); PG8_STAGE(PG8_SA(1, 0), a3, voffA);
;             PG8_WAIT_V(8); PG8_WAIT_L(0); PG8_BAR; PG8_MMA(1, 0, At, B0); PG8_MMA(1, 1, At, B1); PG8_BAR; PG8_SCHED;
;     ...
;         if constexpr (ALIGN_EPI) { if (wr == 0) PG8_BAR; }
	s_setprio 0
	s_add_i32 s40, s57, s3
	v_lshl_add_u64 v[146:147], v[146:147], 0, s[10:11]
	s_mov_b32 m0, s40
	ds_read_b128 v[206:209], v168 offset:49152
	ds_read_b128 v[210:213], v168 offset:50176
	ds_read_b128 v[214:217], v168 offset:51200
	ds_read_b128 v[218:221], v168 offset:52224
	ds_read_b128 v[222:225], v168 offset:53248
	ds_read_b128 v[226:229], v168 offset:54272
	ds_read_b128 v[230:233], v168 offset:55296
	ds_read_b128 v[234:237], v168 offset:56320
	global_load_lds_dwordx4 v[146:147], off
	s_add_i32 m0, s40, 0x2000
	s_add_u32 s40, s50, 0x2b0080
	v_lshl_add_u64 v[146:147], v[194:195], 0, s[10:11]
	s_addc_u32 s41, s51, 0
	s_add_i32 s50, s58, s3
	global_load_lds_dwordx4 v[146:147], off
	v_lshl_add_u64 v[146:147], s[40:41], 0, v[132:133]
	s_mov_b32 m0, s50
	s_nop 0
	global_load_lds_dwordx4 v[146:147], off
	v_lshl_add_u64 v[146:147], s[40:41], 0, v[136:137]
	s_add_i32 m0, s50, 0x2000
	s_nop 0
	global_load_lds_dwordx4 v[146:147], off
	v_lshl_add_u64 v[146:147], v[238:239], 0, s[10:11]
	s_mov_b32 m0, s28
	s_nop 0
	global_load_lds_dwordx4 v[146:147], off
	v_lshl_add_u64 v[146:147], v[240:241], 0, s[10:11]
	s_mov_b32 m0, s29
	s_nop 0
	global_load_lds_dwordx4 v[146:147], off
	s_waitcnt vmcnt(8)
	s_waitcnt lgkmcnt(0)
	s_setprio 1
	s_barrier
	v_mfma_f32_16x16x32_bf16 v[62:65], v[170:173], v[206:209], v[62:65]
	v_mfma_f32_16x16x32_bf16 v[58:61], v[178:181], v[206:209], v[58:61]
	v_mfma_f32_16x16x32_bf16 v[46:49], v[170:173], v[214:217], v[46:49]
	v_mfma_f32_16x16x32_bf16 v[42:45], v[178:181], v[214:217], v[42:45]
	v_mfma_f32_16x16x32_bf16 v[30:33], v[170:173], v[222:225], v[30:33]
	v_mfma_f32_16x16x32_bf16 v[26:29], v[178:181], v[222:225], v[26:29]
	v_mfma_f32_16x16x32_bf16 v[14:17], v[170:173], v[230:233], v[14:17]
	v_mfma_f32_16x16x32_bf16 v[10:13], v[178:181], v[230:233], v[10:13]
	v_mfma_f32_16x16x32_bf16 v[62:65], v[174:177], v[210:213], v[62:65]
	v_mfma_f32_16x16x32_bf16 v[58:61], v[182:185], v[210:213], v[58:61]
	v_mfma_f32_16x16x32_bf16 v[46:49], v[174:177], v[218:221], v[46:49]
	v_mfma_f32_16x16x32_bf16 v[42:45], v[182:185], v[218:221], v[42:45]
	v_mfma_f32_16x16x32_bf16 v[30:33], v[174:177], v[226:229], v[30:33]
	v_mfma_f32_16x16x32_bf16 v[26:29], v[182:185], v[226:229], v[26:29]
	v_mfma_f32_16x16x32_bf16 v[14:17], v[174:177], v[234:237], v[14:17]
	v_mfma_f32_16x16x32_bf16 v[10:13], v[182:185], v[234:237], v[10:13]
	s_setprio 0
	s_setprio 1
	v_mfma_f32_16x16x32_bf16 v[54:57], v[186:189], v[206:209], v[54:57]
	v_mfma_f32_16x16x32_bf16 v[50:53], v[196:199], v[206:209], v[50:53]
	v_mfma_f32_16x16x32_bf16 v[38:41], v[186:189], v[214:217], v[38:41]
	v_mfma_f32_16x16x32_bf16 v[34:37], v[196:199], v[214:217], v[34:37]
	v_mfma_f32_16x16x32_bf16 v[22:25], v[186:189], v[222:225], v[22:25]
	v_mfma_f32_16x16x32_bf16 v[18:21], v[196:199], v[222:225], v[18:21]
	v_mfma_f32_16x16x32_bf16 v[6:9], v[186:189], v[230:233], v[6:9]
	v_mfma_f32_16x16x32_bf16 v[2:5], v[196:199], v[230:233], v[2:5]
	v_mfma_f32_16x16x32_bf16 v[54:57], v[190:193], v[210:213], v[54:57]
	v_mfma_f32_16x16x32_bf16 v[50:53], v[202:205], v[210:213], v[50:53]
	v_mfma_f32_16x16x32_bf16 v[38:41], v[190:193], v[218:221], v[38:41]
	v_mfma_f32_16x16x32_bf16 v[34:37], v[202:205], v[218:221], v[34:37]
	v_mfma_f32_16x16x32_bf16 v[22:25], v[190:193], v[226:229], v[22:25]
	v_mfma_f32_16x16x32_bf16 v[18:21], v[202:205], v[226:229], v[18:21]
	v_mfma_f32_16x16x32_bf16 v[6:9], v[190:193], v[234:237], v[6:9]
	v_mfma_f32_16x16x32_bf16 v[2:5], v[202:205], v[234:237], v[2:5]
	s_barrier
	s_setprio 0
	s_add_i32 s56, s56, 2
	s_add_u32 s54, s54, 0x100
	s_addc_u32 s55, s55, 0
	s_cmpk_gt_u32 s56, 0xa9
	s_mov_b64 s[40:41], s[48:49]
	s_cbranch_scc0 .LBB0_1731
	s_and_b64 vcc, exec, s[12:13]
	s_cbranch_vccz .LBB0_1734
	s_barrier

; #define PG8_STAGE(bufoff, gbase, voff) do { _Pragma("unroll") for (int _i = 0; _i < 2; ++_i) \
;         __builtin_amdgcn_global_load_lds((const unsigned*)((const char*)(gbase) + (voff)[_i]), (PG8_LAS unsigned*)(lds + (bufoff) + ldsw + _i * 8192), 16, 0, 0); } while (0)
; #define PG8_LDA(dst, b, h) do { _Pragma("unroll") for (int m = 0; m < 4; ++m) _Pragma("unroll") for (int k = 0; k < 2; ++k) dst[m][k] = *(const PG8_LAS bf16x8*)(lds + PG8_SA(b, h) + aoff + m * 2048 + k * 1024); } while (0)
; #define PG8_LDB(dst, b, h) do { _Pragma("unroll") for (int n = 0; n < 2; ++n) _Pragma("unroll") for (int k = 0; k < 2; ++k) dst[n][k] = *(const PG8_LAS bf16x8*)(lds + PG8_SB(b, h) + boff + n * 2048 + k * 1024); } while (0)
; #define PG8_MMA(ai, bj, At, Bt) do { __builtin_amdgcn_s_setprio(1); _Pragma("unroll") for (int m = 0; m < 4; ++m) _Pragma("unroll") for (int n = 0; n < 2; ++n) _Pragma("unroll") for (int k = 0; k < 2; ++k) \
;         acc[ai][bj][m][n] = __builtin_amdgcn_mfma_f32_16x16x32_bf16(Bt[n][k], At[m][k], acc[ai][bj][m][n], 0, 0, 0); __builtin_amdgcn_s_setprio(0); } while (0)
; #define PG8_WAIT_V(n) asm volatile("s_waitcnt vmcnt(" #n ")" ::: "memory")
; #define PG8_WAIT_L(n) asm volatile("s_waitcnt lgkmcnt(" #n ")" ::: "memory")
; #define PG8_BAR __builtin_amdgcn_s_barrier()
; #define PG8_SCHED __builtin_amdgcn_sched_barrier(0)
; template <class Epi, class Sched, bool ALIGN_EPI = false, bool SP2 = false>
; __device__ __forceinline__ void gemm_phase(PG8_LAS unsigned char* lds, const Gemm g, const Sched& S, const Epi& E) {
;     ...
;             PG8_LDB(B0, 0, 0); PG8_LDB(B1, 0, 1); PG8_SCHED; PG8_LDA(At, 0, 0); PG8_STAGE(PG8_SA(1, 1), a1 + hstep, voffA);
;             PG8_WAIT_V(8); PG8_WAIT_L(0); PG8_BAR; PG8_MMA(0, 0, At, B0); PG8_MMA(0, 1, At, B1); PG8_BAR; PG8_SCHED;
;             PG8_LDA(At, 0, 1); PG8_STAGE(PG8_SB(0, 0), b2, voffB); PG8_STAGE(PG8_SB(0, 1), b2 + hstep, voffB); PG8_STAGE(PG8_SA(0, 0), a2, voffA);
;             PG8_WAIT_V(8); PG8_WAIT_L(0); PG8_BAR; PG8_MMA(1, 0, At, B0); PG8_MMA(1, 1, At, B1); PG8_BAR; PG8_SCHED;
.LBB0_1746:
	ds_read_b128 v[140:143], v134
	ds_read_b128 v[144:147], v134 offset:1024
	ds_read_b128 v[148:151], v134 offset:2048
	ds_read_b128 v[152:155], v134 offset:3072
	ds_read_b128 v[156:159], v135
	ds_read_b128 v[160:163], v135 offset:1024
	ds_read_b128 v[164:167], v135 offset:2048
	ds_read_b128 v[168:171], v135 offset:3072
	s_add_i32 s36, s38, 2
	s_mov_b32 s37, s11
	s_or_b32 s10, s38, 1
	s_lshl_b64 s[40:41], s[36:37], 7
	s_cmp_lg_u32 s38, s42
	s_cselect_b32 s38, s40, 0
	s_cselect_b32 s37, s41, 0
	s_add_u32 s40, s6, s38
	s_addc_u32 s41, s7, s37
	s_add_u32 s38, s2, s38
	s_addc_u32 s39, s3, s37
	s_lshl_b64 s[52:53], s[10:11], 7
	s_add_u32 s52, s8, s52
	s_addc_u32 s53, s9, s53
	s_mov_b32 m0, s43
	v_lshl_add_u64 v[192:193], s[52:53], 0, v[128:129]
	ds_read_b128 v[172:175], v136
	ds_read_b128 v[176:179], v136 offset:1024
	ds_read_b128 v[180:183], v136 offset:2048
	ds_read_b128 v[184:187], v136 offset:3072
	ds_read_b128 v[188:191], v136 offset:4096
	ds_read_b128 v[196:199], v136 offset:5120
	ds_read_b128 v[202:205], v136 offset:6144
	ds_read_b128 v[206:209], v136 offset:7168
	global_load_lds_dwordx4 v[192:193], off
	v_lshl_add_u64 v[192:193], s[52:53], 0, v[130:131]
	s_mov_b32 m0, s44
	s_nop 0
	global_load_lds_dwordx4 v[192:193], off
	s_waitcnt vmcnt(8)
	s_waitcnt lgkmcnt(0)
	s_setprio 1
	s_barrier
	v_mfma_f32_16x16x32_bf16 v[124:127], v[140:143], v[172:175], v[124:127]
	v_mfma_f32_16x16x32_bf16 v[120:123], v[148:151], v[172:175], v[120:123]
	v_mfma_f32_16x16x32_bf16 v[116:119], v[140:143], v[180:183], v[116:119]
	v_mfma_f32_16x16x32_bf16 v[112:115], v[148:151], v[180:183], v[112:115]
	v_mfma_f32_16x16x32_bf16 v[104:107], v[140:143], v[188:191], v[104:107]
	v_mfma_f32_16x16x32_bf16 v[96:99], v[148:151], v[188:191], v[96:99]
	v_mfma_f32_16x16x32_bf16 v[88:91], v[140:143], v[202:205], v[88:91]
	v_mfma_f32_16x16x32_bf16 v[80:83], v[148:151], v[202:205], v[80:83]
	v_mfma_f32_16x16x32_bf16 v[124:127], v[144:147], v[176:179], v[124:127]
	v_mfma_f32_16x16x32_bf16 v[120:123], v[152:155], v[176:179], v[120:123]
	v_mfma_f32_16x16x32_bf16 v[116:119], v[144:147], v[184:187], v[116:119]
	v_mfma_f32_16x16x32_bf16 v[112:115], v[152:155], v[184:187], v[112:115]
	v_mfma_f32_16x16x32_bf16 v[104:107], v[144:147], v[196:199], v[104:107]
	v_mfma_f32_16x16x32_bf16 v[96:99], v[152:155], v[196:199], v[96:99]
	v_mfma_f32_16x16x32_bf16 v[88:91], v[144:147], v[206:209], v[88:91]
	v_mfma_f32_16x16x32_bf16 v[80:83], v[152:155], v[206:209], v[80:83]
	s_setprio 0
	s_setprio 1
	v_mfma_f32_16x16x32_bf16 v[108:111], v[156:159], v[172:175], v[108:111]
	v_mfma_f32_16x16x32_bf16 v[100:103], v[164:167], v[172:175], v[100:103]
	v_mfma_f32_16x16x32_bf16 v[92:95], v[156:159], v[180:183], v[92:95]
	v_mfma_f32_16x16x32_bf16 v[84:87], v[164:167], v[180:183], v[84:87]
	v_mfma_f32_16x16x32_bf16 v[76:79], v[156:159], v[188:191], v[76:79]
	v_mfma_f32_16x16x32_bf16 v[72:75], v[164:167], v[188:191], v[72:75]
	v_mfma_f32_16x16x32_bf16 v[68:71], v[156:159], v[202:205], v[68:71]
	v_mfma_f32_16x16x32_bf16 v[64:67], v[164:167], v[202:205], v[64:67]
	v_mfma_f32_16x16x32_bf16 v[108:111], v[160:163], v[176:179], v[108:111]
	v_mfma_f32_16x16x32_bf16 v[100:103], v[168:171], v[176:179], v[100:103]
	v_mfma_f32_16x16x32_bf16 v[92:95], v[160:163], v[184:187], v[92:95]
	v_mfma_f32_16x16x32_bf16 v[84:87], v[168:171], v[184:187], v[84:87]
	v_mfma_f32_16x16x32_bf16 v[76:79], v[160:163], v[196:199], v[76:79]
	v_mfma_f32_16x16x32_bf16 v[72:75], v[168:171], v[196:199], v[72:75]
	v_mfma_f32_16x16x32_bf16 v[68:71], v[160:163], v[206:209], v[68:71]
	v_mfma_f32_16x16x32_bf16 v[64:67], v[168:171], v[206:209], v[64:67]
	s_barrier
	s_setprio 0
	s_mov_b32 m0, s31
	v_lshl_add_u64 v[192:193], s[38:39], 0, v[128:129]
	s_add_u32 s52, s38, 0x2b0000
	ds_read_b128 v[172:175], v136 offset:16384
	ds_read_b128 v[176:179], v136 offset:17408
	ds_read_b128 v[180:183], v136 offset:18432
	ds_read_b128 v[184:187], v136 offset:19456
	ds_read_b128 v[188:191], v136 offset:20480
	ds_read_b128 v[196:199], v136 offset:21504
	ds_read_b128 v[202:205], v136 offset:22528
	ds_read_b128 v[206:209], v136 offset:23552
	global_load_lds_dwordx4 v[192:193], off
	v_lshl_add_u64 v[194:195], s[38:39], 0, v[130:131]
	s_mov_b32 m0, s45
	s_addc_u32 s53, s39, 0
	global_load_lds_dwordx4 v[194:195], off
	v_lshl_add_u64 v[210:211], s[52:53], 0, v[128:129]
	s_mov_b32 m0, s46
	v_lshl_add_u64 v[212:213], s[40:41], 0, v[130:131]
	global_load_lds_dwordx4 v[210:211], off
	v_lshl_add_u64 v[210:211], s[52:53], 0, v[130:131]
	s_mov_b32 m0, s47
	s_nop 0
	global_load_lds_dwordx4 v[210:211], off
	v_lshl_add_u64 v[210:211], s[40:41], 0, v[128:129]
	s_mov_b32 m0, s26
	s_nop 0
	global_load_lds_dwordx4 v[210:211], off
	s_mov_b32 m0, s27
	s_nop 0
	global_load_lds_dwordx4 v[212:213], off
	s_waitcnt vmcnt(8)
	s_waitcnt lgkmcnt(0)
	s_setprio 1
	s_barrier
; #define PG8_STAGE(bufoff, gbase, voff) do { _Pragma("unroll") for (int _i = 0; _i < 2; ++_i) \
;         __builtin_amdgcn_global_load_lds((const unsigned*)((const char*)(gbase) + (voff)[_i]), (PG8_LAS unsigned*)(lds + (bufoff) + ldsw + _i * 8192), 16, 0, 0); } while (0)
; #define PG8_LDA(dst, b, h) do { _Pragma("unroll") for (int m = 0; m < 4; ++m) _Pragma("unroll") for (int k = 0; k < 2; ++k) dst[m][k] = *(const PG8_LAS bf16x8*)(lds + PG8_SA(b, h) + aoff + m * 2048 + k * 1024); } while (0)
; #define PG8_LDB(dst, b, h) do { _Pragma("unroll") for (int n = 0; n < 2; ++n) _Pragma("unroll") for (int k = 0; k < 2; ++k) dst[n][k] = *(const PG8_LAS bf16x8*)(lds + PG8_SB(b, h) + boff + n * 2048 + k * 1024); } while (0)
; #define PG8_MMA(ai, bj, At, Bt) do { __builtin_amdgcn_s_setprio(1); _Pragma("unroll") for (int m = 0; m < 4; ++m) _Pragma("unroll") for (int n = 0; n < 2; ++n) _Pragma("unroll") for (int k = 0; k < 2; ++k) \
;         acc[ai][bj][m][n] = __builtin_amdgcn_mfma_f32_16x16x32_bf16(Bt[n][k], At[m][k], acc[ai][bj][m][n], 0, 0, 0); __builtin_amdgcn_s_setprio(0); } while (0)
; #define PG8_WAIT_V(n) asm volatile("s_waitcnt vmcnt(" #n ")" ::: "memory")
; #define PG8_WAIT_L(n) asm volatile("s_waitcnt lgkmcnt(" #n ")" ::: "memory")
; #define PG8_BAR __builtin_amdgcn_s_barrier()
; #define PG8_SCHED __builtin_amdgcn_sched_barrier(0)
; template <class Epi, class Sched, bool ALIGN_EPI = false, bool SP2 = false>
; __device__ __forceinline__ void gemm_phase(PG8_LAS unsigned char* lds, const Gemm g, const Sched& S, const Epi& E) {
;     ...
;             PG8_WAIT_V(8); PG8_WAIT_L(0); PG8_BAR; PG8_MMA(1, 0, At, B0); PG8_MMA(1, 1, At, B1); PG8_BAR; PG8_SCHED;
;             PG8_LDB(B0, 1, 0); PG8_LDB(B1, 1, 1); PG8_SCHED; PG8_LDA(At, 1, 0); PG8_STAGE(PG8_SA(0, 1), a2 + hstep, voffA);
;             PG8_WAIT_V(8); PG8_WAIT_L(0); PG8_BAR; PG8_MMA(0, 0, At, B0); PG8_MMA(0, 1, At, B1); PG8_BAR; PG8_SCHED;
	v_mfma_f32_16x16x32_bf16 v[60:63], v[140:143], v[172:175], v[60:63]
	v_mfma_f32_16x16x32_bf16 v[56:59], v[148:151], v[172:175], v[56:59]
	v_mfma_f32_16x16x32_bf16 v[52:55], v[140:143], v[180:183], v[52:55]
	v_mfma_f32_16x16x32_bf16 v[48:51], v[148:151], v[180:183], v[48:51]
	v_mfma_f32_16x16x32_bf16 v[40:43], v[140:143], v[188:191], v[40:43]
	v_mfma_f32_16x16x32_bf16 v[32:35], v[148:151], v[188:191], v[32:35]
	v_mfma_f32_16x16x32_bf16 v[24:27], v[140:143], v[202:205], v[24:27]
	v_mfma_f32_16x16x32_bf16 v[16:19], v[148:151], v[202:205], v[16:19]
	v_mfma_f32_16x16x32_bf16 v[60:63], v[144:147], v[176:179], v[60:63]
	v_mfma_f32_16x16x32_bf16 v[56:59], v[152:155], v[176:179], v[56:59]
	v_mfma_f32_16x16x32_bf16 v[52:55], v[144:147], v[184:187], v[52:55]
	v_mfma_f32_16x16x32_bf16 v[48:51], v[152:155], v[184:187], v[48:51]
	v_mfma_f32_16x16x32_bf16 v[40:43], v[144:147], v[196:199], v[40:43]
	v_mfma_f32_16x16x32_bf16 v[32:35], v[152:155], v[196:199], v[32:35]
	v_mfma_f32_16x16x32_bf16 v[24:27], v[144:147], v[206:209], v[24:27]
	v_mfma_f32_16x16x32_bf16 v[16:19], v[152:155], v[206:209], v[16:19]
	s_setprio 0
	s_setprio 1
	v_mfma_f32_16x16x32_bf16 v[44:47], v[156:159], v[172:175], v[44:47]
	v_mfma_f32_16x16x32_bf16 v[36:39], v[164:167], v[172:175], v[36:39]
	v_mfma_f32_16x16x32_bf16 v[28:31], v[156:159], v[180:183], v[28:31]
	v_mfma_f32_16x16x32_bf16 v[20:23], v[164:167], v[180:183], v[20:23]
	v_mfma_f32_16x16x32_bf16 v[12:15], v[156:159], v[188:191], v[12:15]
	v_mfma_f32_16x16x32_bf16 v[8:11], v[164:167], v[188:191], v[8:11]
	v_mfma_f32_16x16x32_bf16 v[4:7], v[156:159], v[202:205], v[4:7]
	v_mfma_f32_16x16x32_bf16 v[0:3], v[164:167], v[202:205], v[0:3]
	v_mfma_f32_16x16x32_bf16 v[44:47], v[160:163], v[176:179], v[44:47]
	v_mfma_f32_16x16x32_bf16 v[36:39], v[168:171], v[176:179], v[36:39]
	v_mfma_f32_16x16x32_bf16 v[28:31], v[160:163], v[184:187], v[28:31]
	v_mfma_f32_16x16x32_bf16 v[20:23], v[168:171], v[184:187], v[20:23]
	v_mfma_f32_16x16x32_bf16 v[12:15], v[160:163], v[196:199], v[12:15]
	v_mfma_f32_16x16x32_bf16 v[8:11], v[168:171], v[196:199], v[8:11]
	v_mfma_f32_16x16x32_bf16 v[4:7], v[160:163], v[206:209], v[4:7]
	v_mfma_f32_16x16x32_bf16 v[0:3], v[168:171], v[206:209], v[0:3]
	s_barrier
	s_setprio 0
	ds_read_b128 v[140:143], v137
	ds_read_b128 v[144:147], v137 offset:1024
	ds_read_b128 v[148:151], v137 offset:2048
	ds_read_b128 v[152:155], v137 offset:3072
	ds_read_b128 v[156:159], v138
	ds_read_b128 v[160:163], v138 offset:1024
	ds_read_b128 v[164:167], v138 offset:2048
	ds_read_b128 v[168:171], v138 offset:3072
	s_add_u32 s40, s40, 0x2b0000
	s_addc_u32 s41, s41, 0
	s_mov_b32 m0, s28
	v_lshl_add_u64 v[214:215], s[40:41], 0, v[128:129]
	ds_read_b128 v[172:175], v136 offset:32768
	ds_read_b128 v[176:179], v136 offset:33792
	ds_read_b128 v[180:183], v136 offset:34816
	ds_read_b128 v[184:187], v136 offset:35840
	ds_read_b128 v[188:191], v136 offset:36864
	ds_read_b128 v[196:199], v136 offset:37888
	ds_read_b128 v[202:205], v136 offset:38912
	ds_read_b128 v[206:209], v136 offset:39936
	global_load_lds_dwordx4 v[214:215], off
	v_lshl_add_u64 v[214:215], s[40:41], 0, v[130:131]
	s_mov_b32 m0, s30
	s_nop 0
	global_load_lds_dwordx4 v[214:215], off
	s_waitcnt vmcnt(8)
	s_waitcnt lgkmcnt(0)
	s_setprio 1
	s_barrier
	v_mfma_f32_16x16x32_bf16 v[124:127], v[140:143], v[172:175], v[124:127]
	v_mfma_f32_16x16x32_bf16 v[120:123], v[148:151], v[172:175], v[120:123]
	v_mfma_f32_16x16x32_bf16 v[116:119], v[140:143], v[180:183], v[116:119]
	v_mfma_f32_16x16x32_bf16 v[112:115], v[148:151], v[180:183], v[112:115]
	v_mfma_f32_16x16x32_bf16 v[104:107], v[140:143], v[188:191], v[104:107]
	v_mfma_f32_16x16x32_bf16 v[96:99], v[148:151], v[188:191], v[96:99]
	v_mfma_f32_16x16x32_bf16 v[88:91], v[140:143], v[202:205], v[88:91]
	v_mfma_f32_16x16x32_bf16 v[80:83], v[148:151], v[202:205], v[80:83]
	v_mfma_f32_16x16x32_bf16 v[124:127], v[144:147], v[176:179], v[124:127]
	v_mfma_f32_16x16x32_bf16 v[120:123], v[152:155], v[176:179], v[120:123]
	v_mfma_f32_16x16x32_bf16 v[116:119], v[144:147], v[184:187], v[116:119]
	v_mfma_f32_16x16x32_bf16 v[112:115], v[152:155], v[184:187], v[112:115]
	v_mfma_f32_16x16x32_bf16 v[104:107], v[144:147], v[196:199], v[104:107]
	v_mfma_f32_16x16x32_bf16 v[96:99], v[152:155], v[196:199], v[96:99]
	v_mfma_f32_16x16x32_bf16 v[88:91], v[144:147], v[206:209], v[88:91]
	v_mfma_f32_16x16x32_bf16 v[80:83], v[152:155], v[206:209], v[80:83]
	s_setprio 0
	s_setprio 1
	v_mfma_f32_16x16x32_bf16 v[108:111], v[156:159], v[172:175], v[108:111]
	v_mfma_f32_16x16x32_bf16 v[100:103], v[164:167], v[172:175], v[100:103]
	v_mfma_f32_16x16x32_bf16 v[92:95], v[156:159], v[180:183], v[92:95]
	v_mfma_f32_16x16x32_bf16 v[84:87], v[164:167], v[180:183], v[84:87]
	v_mfma_f32_16x16x32_bf16 v[76:79], v[156:159], v[188:191], v[76:79]
	v_mfma_f32_16x16x32_bf16 v[72:75], v[164:167], v[188:191], v[72:75]
	v_mfma_f32_16x16x32_bf16 v[68:71], v[156:159], v[202:205], v[68:71]
	v_mfma_f32_16x16x32_bf16 v[64:67], v[164:167], v[202:205], v[64:67]
	v_mfma_f32_16x16x32_bf16 v[108:111], v[160:163], v[176:179], v[108:111]
	v_mfma_f32_16x16x32_bf16 v[100:103], v[168:171], v[176:179], v[100:103]
	v_mfma_f32_16x16x32_bf16 v[92:95], v[160:163], v[184:187], v[92:95]
	v_mfma_f32_16x16x32_bf16 v[84:87], v[168:171], v[184:187], v[84:87]
	v_mfma_f32_16x16x32_bf16 v[76:79], v[160:163], v[196:199], v[76:79]
	v_mfma_f32_16x16x32_bf16 v[72:75], v[168:171], v[196:199], v[72:75]
	v_mfma_f32_16x16x32_bf16 v[68:71], v[160:163], v[206:209], v[68:71]
	v_mfma_f32_16x16x32_bf16 v[64:67], v[168:171], v[206:209], v[64:67]
	s_barrier
; #define PG8_STAGE(bufoff, gbase, voff) do { _Pragma("unroll") for (int _i = 0; _i < 2; ++_i) \
;         __builtin_amdgcn_global_load_lds((const unsigned*)((const char*)(gbase) + (voff)[_i]), (PG8_LAS unsigned*)(lds + (bufoff) + ldsw + _i * 8192), 16, 0, 0); } while (0)
; #define PG8_LDA(dst, b, h) do { _Pragma("unroll") for (int m = 0; m < 4; ++m) _Pragma("unroll") for (int k = 0; k < 2; ++k) dst[m][k] = *(const PG8_LAS bf16x8*)(lds + PG8_SA(b, h) + aoff + m * 2048 + k * 1024); } while (0)
; #define PG8_MMA(ai, bj, At, Bt) do { __builtin_amdgcn_s_setprio(1); _Pragma("unroll") for (int m = 0; m < 4; ++m) _Pragma("unroll") for (int n = 0; n < 2; ++n) _Pragma("unroll") for (int k = 0; k < 2; ++k) \
;         acc[ai][bj][m][n] = __builtin_amdgcn_mfma_f32_16x16x32_bf16(Bt[n][k], At[m][k], acc[ai][bj][m][n], 0, 0, 0); __builtin_amdgcn_s_setprio(0); } while (0)
; #define PG8_WAIT_V(n) asm volatile("s_waitcnt vmcnt(" #n ")" ::: "memory")
; #define PG8_WAIT_L(n) asm volatile("s_waitcnt lgkmcnt(" #n ")" ::: "memory")
; #define PG8_BAR __builtin_amdgcn_s_barrier()
; #define PG8_SCHED __builtin_amdgcn_sched_barrier(0)
; template <class Epi, class Sched, bool ALIGN_EPI = false, bool SP2 = false>
; __device__ __forceinline__ void gemm_phase(PG8_LAS unsigned char* lds, const Gemm g, const Sched& S, const Epi& E) {
;     ...
;             PG8_LDA(At, 1, 1); PG8_STAGE(PG8_SB(1, 0), b3, voffB); PG8_STAGE(PG8_SB(1, 1), b3 + hstep, voffB); PG8_STAGE(PG8_SA(1, 0), a3, voffA);
;             PG8_WAIT_V(8); PG8_WAIT_L(0); PG8_BAR; PG8_MMA(1, 0, At, B0); PG8_MMA(1, 1, At, B1); PG8_BAR; PG8_SCHED;
;     ...
;         if constexpr (ALIGN_EPI) { if (wr == 0) PG8_BAR; }
	s_setprio 0
	s_mov_b32 m0, s48
	v_lshl_add_u64 v[192:193], v[192:193], 0, s[12:13]
	s_add_u32 s38, s38, 0x2b0080
	ds_read_b128 v[172:175], v136 offset:49152
	ds_read_b128 v[176:179], v136 offset:50176
	ds_read_b128 v[180:183], v136 offset:51200
	ds_read_b128 v[184:187], v136 offset:52224
	ds_read_b128 v[188:191], v136 offset:53248
	ds_read_b128 v[196:199], v136 offset:54272
	ds_read_b128 v[202:205], v136 offset:55296
	ds_read_b128 v[206:209], v136 offset:56320
	global_load_lds_dwordx4 v[192:193], off
	v_lshl_add_u64 v[192:193], v[194:195], 0, s[12:13]
	s_mov_b32 m0, s49
	s_addc_u32 s39, s39, 0
	global_load_lds_dwordx4 v[192:193], off
	v_lshl_add_u64 v[192:193], s[38:39], 0, v[128:129]
	s_mov_b32 m0, s50
	s_nop 0
	global_load_lds_dwordx4 v[192:193], off
	v_lshl_add_u64 v[192:193], s[38:39], 0, v[130:131]
	s_mov_b32 m0, s51
	s_nop 0
	global_load_lds_dwordx4 v[192:193], off
	v_lshl_add_u64 v[192:193], v[210:211], 0, s[12:13]
	s_mov_b32 m0, s34
	s_nop 0
	global_load_lds_dwordx4 v[192:193], off
	v_lshl_add_u64 v[192:193], v[212:213], 0, s[12:13]
	s_mov_b32 m0, s35
	s_nop 0
	global_load_lds_dwordx4 v[192:193], off
	s_waitcnt vmcnt(8)
	s_waitcnt lgkmcnt(0)
	s_setprio 1
	s_barrier
	v_mfma_f32_16x16x32_bf16 v[60:63], v[140:143], v[172:175], v[60:63]
	v_mfma_f32_16x16x32_bf16 v[56:59], v[148:151], v[172:175], v[56:59]
	v_mfma_f32_16x16x32_bf16 v[52:55], v[140:143], v[180:183], v[52:55]
	v_mfma_f32_16x16x32_bf16 v[48:51], v[148:151], v[180:183], v[48:51]
	v_mfma_f32_16x16x32_bf16 v[40:43], v[140:143], v[188:191], v[40:43]
	v_mfma_f32_16x16x32_bf16 v[32:35], v[148:151], v[188:191], v[32:35]
	v_mfma_f32_16x16x32_bf16 v[24:27], v[140:143], v[202:205], v[24:27]
	v_mfma_f32_16x16x32_bf16 v[16:19], v[148:151], v[202:205], v[16:19]
	v_mfma_f32_16x16x32_bf16 v[60:63], v[144:147], v[176:179], v[60:63]
	v_mfma_f32_16x16x32_bf16 v[56:59], v[152:155], v[176:179], v[56:59]
	v_mfma_f32_16x16x32_bf16 v[52:55], v[144:147], v[184:187], v[52:55]
	v_mfma_f32_16x16x32_bf16 v[48:51], v[152:155], v[184:187], v[48:51]
	v_mfma_f32_16x16x32_bf16 v[40:43], v[144:147], v[196:199], v[40:43]
	v_mfma_f32_16x16x32_bf16 v[32:35], v[152:155], v[196:199], v[32:35]
	v_mfma_f32_16x16x32_bf16 v[24:27], v[144:147], v[206:209], v[24:27]
	v_mfma_f32_16x16x32_bf16 v[16:19], v[152:155], v[206:209], v[16:19]
	s_setprio 0
	s_setprio 1
	v_mfma_f32_16x16x32_bf16 v[44:47], v[156:159], v[172:175], v[44:47]
	v_mfma_f32_16x16x32_bf16 v[36:39], v[164:167], v[172:175], v[36:39]
	v_mfma_f32_16x16x32_bf16 v[28:31], v[156:159], v[180:183], v[28:31]
	v_mfma_f32_16x16x32_bf16 v[20:23], v[164:167], v[180:183], v[20:23]
	v_mfma_f32_16x16x32_bf16 v[12:15], v[156:159], v[188:191], v[12:15]
	v_mfma_f32_16x16x32_bf16 v[8:11], v[164:167], v[188:191], v[8:11]
	v_mfma_f32_16x16x32_bf16 v[4:7], v[156:159], v[202:205], v[4:7]
	v_mfma_f32_16x16x32_bf16 v[0:3], v[164:167], v[202:205], v[0:3]
	v_mfma_f32_16x16x32_bf16 v[44:47], v[160:163], v[176:179], v[44:47]
	v_mfma_f32_16x16x32_bf16 v[36:39], v[168:171], v[176:179], v[36:39]
	v_mfma_f32_16x16x32_bf16 v[28:31], v[160:163], v[184:187], v[28:31]
	v_mfma_f32_16x16x32_bf16 v[20:23], v[168:171], v[184:187], v[20:23]
	v_mfma_f32_16x16x32_bf16 v[12:15], v[160:163], v[196:199], v[12:15]
	v_mfma_f32_16x16x32_bf16 v[8:11], v[168:171], v[196:199], v[8:11]
	v_mfma_f32_16x16x32_bf16 v[4:7], v[160:163], v[206:209], v[4:7]
	v_mfma_f32_16x16x32_bf16 v[0:3], v[168:171], v[206:209], v[0:3]
	s_barrier
	s_setprio 0
	s_cmp_ge_u32 s36, s5
	s_mov_b32 s38, s36
	s_cbranch_scc0 .LBB0_1746
	s_cmpk_lt_u32 s16, 0x100
	s_cbranch_scc0 .LBB0_1749
	s_barrier
